# v024 + LR GEMM epilogue: bias vectors loaded once per unit instead of per 8-element group (removes 28 serialized load/store waits per unit); all removed ops keep s_nop placeholders
# speedup vs baseline: 1.0086x; 1.0019x over previous
; __device__ __forceinline__ void phase_norm_in(const Frame& F, const float* xp, const float* xs, const float* gain, bf16* xn, bf16* xb) {
;     for (int m = F.gw; m < T; m += F.NGW) {
;         const float* src_row = m < 8192 ? xp + (size_t)m * D : xs + (size_t)(m - 8192) * D;
;         const f32x4* xr = (const f32x4*)src_row + F.lane; const f32x4* gr = (const f32x4*)gain + F.lane;
;         f32x4 v[8]; float s = 0.f;
; #pragma unroll
;         for (int j = 0; j < 8; ++j) { v[j] = xr[64 * j]; s += (v[j].x * v[j].x + v[j].y * v[j].y) + (v[j].z * v[j].z + v[j].w * v[j].w); }
;         const float rstd = 1.0f / sqrtf(wave_sum(s) * (1.0f / D) + 1e-6f);
.LBB0_90:
	global_load_dwordx4 v[28:31], v184, s[18:19]
	global_load_dwordx4 v[24:27], v184, s[18:19] offset:1024
	global_load_dwordx4 v[20:23], v184, s[18:19] offset:2048
	global_load_dwordx4 v[16:19], v184, s[18:19] offset:3072
	v_lshl_add_u64 v[0:1], s[18:19], 0, v[184:185]
	v_add_co_u32_e32 v4, vcc, s33, v0
	s_lshl_b64 s[4:5], s[4:5], 12
	s_nop 0
	v_addc_co_u32_e32 v5, vcc, 0, v1, vcc
	global_load_dwordx4 v[8:11], v[4:5], off
	global_load_dwordx4 v[12:15], v[4:5], off offset:1024
	global_load_dwordx4 v[0:3], v[4:5], off offset:3072
	s_nop 0
	global_load_dwordx4 v[4:7], v[4:5], off offset:2048
	v_mbcnt_lo_u32_b32 v50, -1, 0
	v_mbcnt_hi_u32_b32 v50, -1, v50
	v_mbcnt_lo_u32_b32 v68, -1, 0
	v_mbcnt_hi_u32_b32 v68, -1, v68
	v_mbcnt_lo_u32_b32 v69, -1, 0
	v_mbcnt_hi_u32_b32 v69, -1, v69
	v_mbcnt_lo_u32_b32 v70, -1, 0
	v_mbcnt_hi_u32_b32 v70, -1, v70
	v_mbcnt_lo_u32_b32 v71, -1, 0
	v_mbcnt_hi_u32_b32 v71, -1, v71
	v_mbcnt_lo_u32_b32 v72, -1, 0
	v_mbcnt_hi_u32_b32 v72, -1, v72
	s_nop 0
	v_lshlrev_b32_e32 v50, 2, v50
	v_xor_b32_e32 v73, 4, v50
	s_add_u32 s10, s10, s12
	s_addc_u32 s11, s11, s13
	s_add_u32 s14, s14, s16
	s_addc_u32 s15, s15, s17
	s_cmp_lt_i32 s10, 0xa000
	s_waitcnt vmcnt(7)
	v_mov_b32_e32 v52, v29
	s_waitcnt vmcnt(6)
	v_mov_b32_e32 v53, v25
	v_mov_b32_e32 v56, v31
	v_mov_b32_e32 v57, v27
	v_mov_b32_e32 v50, v28
	v_mov_b32_e32 v51, v24
	v_mov_b32_e32 v54, v30
	v_mov_b32_e32 v55, v26
	s_waitcnt vmcnt(5)
	v_pk_mul_f32 v[58:59], v[22:23], v[22:23]
	v_pk_mul_f32 v[60:61], v[20:21], v[20:21]
	v_pk_mul_f32 v[52:53], v[52:53], v[52:53]
	v_pk_mul_f32 v[56:57], v[56:57], v[56:57]
	v_pk_mov_b32 v[66:67], v[60:61], v[58:59] op_sel:[1,0]
	v_mov_b32_e32 v61, v59
	v_pk_fma_f32 v[50:51], v[50:51], v[50:51], v[52:53]
	v_pk_fma_f32 v[52:53], v[54:55], v[54:55], v[56:57]
	s_waitcnt vmcnt(4)
	v_mul_f32_e32 v62, v17, v17
	v_mul_f32_e32 v64, v19, v19
	v_pk_add_f32 v[54:55], v[66:67], v[60:61]
	v_pk_add_f32 v[50:51], v[50:51], v[52:53]
	v_pk_fma_f32 v[58:59], v[16:17], v[16:17], v[62:63] op_sel_hi:[1,1,0]
	v_pk_fma_f32 v[62:63], v[18:19], v[18:19], v[64:65] op_sel_hi:[1,1,0]
	s_waitcnt vmcnt(3)
	v_mul_f32_e32 v67, v8, v8
	v_mul_f32_e32 v74, v9, v9
	v_pk_add_f32 v[52:53], v[54:55], v[54:55] op_sel:[0,1] op_sel_hi:[1,0]
	v_pk_add_f32 v[50:51], v[50:51], v[50:51] op_sel:[0,1] op_sel_hi:[1,0]
	v_mul_f32_e32 v59, v10, v10
	v_mul_f32_e32 v63, v11, v11
	s_waitcnt vmcnt(2)
	v_pk_mul_f32 v[56:57], v[14:15], v[14:15]
	v_pk_mul_f32 v[60:61], v[12:13], v[12:13]
	v_mov_b32_e32 v53, v74
	v_mov_b32_e32 v51, v67
	v_pk_mov_b32 v[54:55], v[60:61], v[56:57] op_sel:[1,0]
	v_mov_b32_e32 v61, v57
	v_pk_add_f32 v[58:59], v[58:59], v[62:63]
	v_pk_add_f32 v[50:51], v[50:51], v[52:53]
	s_waitcnt vmcnt(0)
	v_mul_f32_e32 v64, v5, v5
	v_mul_f32_e32 v66, v7, v7
	v_pk_add_f32 v[54:55], v[54:55], v[60:61]
	v_pk_add_f32 v[50:51], v[50:51], v[58:59]
	v_mul_f32_e32 v75, v0, v0
	v_mul_f32_e32 v76, v1, v1
	v_mul_f32_e32 v77, v2, v2
	v_mul_f32_e32 v78, v3, v3
	v_pk_fma_f32 v[56:57], v[4:5], v[4:5], v[64:65] op_sel_hi:[1,1,0]
	v_pk_fma_f32 v[64:65], v[6:7], v[6:7], v[66:67] op_sel_hi:[1,1,0]
	v_pk_add_f32 v[54:55], v[54:55], v[54:55] op_sel:[0,1] op_sel_hi:[1,0]
	v_pk_add_f32 v[50:51], v[50:51], v[50:51] op_sel:[0,1] op_sel_hi:[1,0]
	v_mov_b32_e32 v57, v77
	v_mov_b32_e32 v65, v78
	v_mov_b32_e32 v55, v76
	v_mov_b32_e32 v51, v75
	v_pk_add_f32 v[56:57], v[56:57], v[64:65]
	v_pk_add_f32 v[50:51], v[50:51], v[54:55]
	v_lshlrev_b32_e32 v52, 2, v68
	v_pk_add_f32 v[50:51], v[50:51], v[56:57]
	v_xor_b32_e32 v52, 8, v52
	v_add_f32_e32 v50, v50, v51
	ds_bpermute_b32 v51, v73, v50
	v_cvt_pk_bf16_f32 v54, v28, v29
	s_waitcnt lgkmcnt(0)
	v_add_f32_e32 v50, v50, v51
	ds_bpermute_b32 v51, v52, v50
	v_lshlrev_b32_e32 v52, 2, v69
	v_xor_b32_e32 v52, 16, v52
	s_waitcnt lgkmcnt(0)
	v_add_f32_e32 v50, v50, v51
	ds_bpermute_b32 v51, v52, v50
	v_lshlrev_b32_e32 v52, 2, v70
	v_xor_b32_e32 v52, 32, v52
	s_waitcnt lgkmcnt(0)
	v_add_f32_e32 v50, v50, v51
	ds_bpermute_b32 v51, v52, v50
	v_lshlrev_b32_e32 v52, 2, v71
	v_xor_b32_e32 v52, 64, v52
	s_waitcnt lgkmcnt(0)
	v_add_f32_e32 v50, v50, v51
	ds_bpermute_b32 v51, v52, v50
	v_lshlrev_b32_e32 v52, 2, v72
	v_xor_b32_e32 v52, 0x80, v52
	s_waitcnt lgkmcnt(0)
	v_add_f32_e32 v50, v50, v51
	ds_bpermute_b32 v51, v52, v50
	v_lshl_add_u64 v[52:53], v[36:37], 0, s[4:5]
	s_waitcnt lgkmcnt(0)
; __device__ __forceinline__ unsigned pk2(float lo, float hi) { return cvt_pk_bf16(lo, hi); }
; __device__ __forceinline__ void phase_norm_in(const Frame& F, const float* xp, const float* xs, const float* gain, bf16* xn, bf16* xb) {
;     ...
;         const float rstd = 1.0f / sqrtf(wave_sum(s) * (1.0f / D) + 1e-6f);
;         v2u* o8 = (v2u*)(xn + (size_t)m * D) + F.lane; v2u* b8 = (v2u*)(xb + (size_t)m * D) + F.lane;
; #pragma unroll
;         for (int j = 0; j < 8; ++j) { const f32x4 g = gr[64 * j]; v2u w; w.x = pk2(v[j].x * rstd * g.x, v[j].y * rstd * g.y); w.y = pk2(v[j].z * rstd * g.z, v[j].w * rstd * g.w); o8[64 * j] = w;
;             v2u b; b.x = pk2(v[j].x, v[j].y); b.y = pk2(v[j].z, v[j].w); b8[64 * j] = b; }
	v_add_f32_e32 v50, v50, v51
	v_fmamk_f32 v50, v50, 0x3a000000, v208
	v_mul_f32_e32 v51, 0x4f800000, v50
	v_cmp_gt_f32_e32 vcc, s86, v50
	s_nop 1
	v_cndmask_b32_e32 v55, v50, v51, vcc
	v_sqrt_f32_e32 v56, v55
	v_lshl_add_u64 v[50:51], v[34:35], 0, s[4:5]
	v_add_u32_e32 v57, -1, v56
	v_add_u32_e32 v58, 1, v56
	v_fma_f32 v59, -v57, v56, v55
	v_fma_f32 v60, -v58, v56, v55
	v_cmp_ge_f32_e64 s[4:5], 0, v59
	s_nop 1
	v_cndmask_b32_e64 v56, v56, v57, s[4:5]
	v_cmp_lt_f32_e64 s[4:5], 0, v60
	s_nop 1
	v_cndmask_b32_e64 v56, v56, v58, s[4:5]
	v_mul_f32_e32 v57, 0x37800000, v56
	v_cndmask_b32_e32 v56, v56, v57, vcc
	v_cmp_class_f32_e32 vcc, v55, v204
	s_nop 1
	v_cndmask_b32_e32 v56, v56, v55, vcc
	v_div_scale_f32 v57, s[4:5], v56, v56, 1.0
	v_rcp_f32_e32 v58, v57
	v_div_scale_f32 v59, vcc, 1.0, v56, 1.0
	v_cvt_pk_bf16_f32 v55, v30, v31
	v_fma_f32 v60, -v57, v58, 1.0
	v_fmac_f32_e32 v58, v60, v58
	v_mul_f32_e32 v60, v59, v58
	v_fma_f32 v61, -v57, v60, v59
	v_fmac_f32_e32 v60, v61, v58
	v_fma_f32 v57, -v57, v60, v59
	v_div_fmas_f32 v57, v57, v58, v60
	v_div_fixup_f32 v56, v57, v56, 1.0
	v_pk_mul_f32 v[28:29], v[28:29], v[56:57] op_sel_hi:[1,0]
	v_pk_mul_f32 v[30:31], v[30:31], v[56:57] op_sel_hi:[1,0]
	s_waitcnt vmcnt(0)
	s_nop 1
	v_mov_b32_e32 v46, v96
	v_mov_b32_e32 v47, v97
	v_mov_b32_e32 v48, v98
	v_mov_b32_e32 v49, v99
	v_pk_mul_f32 v[28:29], v[46:47], v[28:29]
	v_pk_mul_f32 v[30:31], v[48:49], v[30:31]
	v_cvt_pk_bf16_f32 v28, v28, v29
	v_cvt_pk_bf16_f32 v29, v30, v31
	global_store_dwordx2 v[50:51], v[28:29], off
	global_store_dwordx2 v[52:53], v[54:55], off
	s_nop 0
	s_nop 1
	v_mov_b32_e32 v28, v100
	v_mov_b32_e32 v29, v101
	v_mov_b32_e32 v30, v102
	v_mov_b32_e32 v31, v103
	v_cvt_pk_bf16_f32 v46, v24, v25
	v_cvt_pk_bf16_f32 v47, v26, v27
	v_pk_mul_f32 v[24:25], v[24:25], v[56:57] op_sel_hi:[1,0]
	v_pk_mul_f32 v[26:27], v[26:27], v[56:57] op_sel_hi:[1,0]
	s_nop 0
	v_pk_mul_f32 v[24:25], v[28:29], v[24:25]
	v_pk_mul_f32 v[26:27], v[30:31], v[26:27]
	v_cvt_pk_bf16_f32 v24, v24, v25
	v_cvt_pk_bf16_f32 v25, v26, v27
	global_store_dwordx2 v[50:51], v[24:25], off offset:512
	global_store_dwordx2 v[52:53], v[46:47], off offset:512
	s_nop 0
	s_nop 1
	v_mov_b32_e32 v24, v104
	v_mov_b32_e32 v25, v105
	v_mov_b32_e32 v26, v106
	v_mov_b32_e32 v27, v107
	v_cvt_pk_bf16_f32 v28, v20, v21
	v_cvt_pk_bf16_f32 v29, v22, v23
	v_pk_mul_f32 v[20:21], v[20:21], v[56:57] op_sel_hi:[1,0]
	v_pk_mul_f32 v[22:23], v[22:23], v[56:57] op_sel_hi:[1,0]
	s_nop 0
	v_pk_mul_f32 v[20:21], v[20:21], v[24:25]
	v_pk_mul_f32 v[22:23], v[22:23], v[26:27]
	v_cvt_pk_bf16_f32 v20, v20, v21
	v_cvt_pk_bf16_f32 v21, v22, v23
	global_store_dwordx2 v[50:51], v[20:21], off offset:1024
	global_store_dwordx2 v[52:53], v[28:29], off offset:1024
	s_nop 0
	s_nop 1
	v_mov_b32_e32 v20, v108
	v_mov_b32_e32 v21, v109
	v_mov_b32_e32 v22, v110
	v_mov_b32_e32 v23, v111
	v_cvt_pk_bf16_f32 v24, v16, v17
	v_cvt_pk_bf16_f32 v25, v18, v19
	v_pk_mul_f32 v[16:17], v[16:17], v[56:57] op_sel_hi:[1,0]
	v_pk_mul_f32 v[18:19], v[18:19], v[56:57] op_sel_hi:[1,0]
	s_nop 0
	v_pk_mul_f32 v[16:17], v[16:17], v[20:21]
	v_pk_mul_f32 v[18:19], v[18:19], v[22:23]
	v_cvt_pk_bf16_f32 v16, v16, v17
	v_cvt_pk_bf16_f32 v17, v18, v19
	global_store_dwordx2 v[50:51], v[16:17], off offset:1536
	global_store_dwordx2 v[52:53], v[24:25], off offset:1536
	s_nop 0
	s_nop 1
	v_mov_b32_e32 v16, v112
	v_mov_b32_e32 v17, v113
	v_mov_b32_e32 v18, v114
	v_mov_b32_e32 v19, v115
	v_cvt_pk_bf16_f32 v20, v8, v9
	v_cvt_pk_bf16_f32 v21, v10, v11
	v_pk_mul_f32 v[8:9], v[8:9], v[56:57] op_sel_hi:[1,0]
	v_pk_mul_f32 v[10:11], v[10:11], v[56:57] op_sel_hi:[1,0]
	s_nop 0
	v_pk_mul_f32 v[8:9], v[8:9], v[16:17]
	v_pk_mul_f32 v[10:11], v[10:11], v[18:19]
	v_cvt_pk_bf16_f32 v8, v8, v9
	v_cvt_pk_bf16_f32 v9, v10, v11
	global_store_dwordx2 v[50:51], v[8:9], off offset:2048
	global_store_dwordx2 v[52:53], v[20:21], off offset:2048
	s_nop 0
	s_nop 1
	v_mov_b32_e32 v8, v116
	v_mov_b32_e32 v9, v117
	v_mov_b32_e32 v10, v118
	v_mov_b32_e32 v11, v119
	v_cvt_pk_bf16_f32 v16, v12, v13
	v_cvt_pk_bf16_f32 v17, v14, v15
	v_pk_mul_f32 v[12:13], v[12:13], v[56:57] op_sel_hi:[1,0]
	v_pk_mul_f32 v[14:15], v[14:15], v[56:57] op_sel_hi:[1,0]
	s_nop 0
	v_pk_mul_f32 v[8:9], v[12:13], v[8:9]
	v_pk_mul_f32 v[10:11], v[14:15], v[10:11]
	v_cvt_pk_bf16_f32 v8, v8, v9
	v_cvt_pk_bf16_f32 v9, v10, v11
	global_store_dwordx2 v[50:51], v[8:9], off offset:2560
	global_store_dwordx2 v[52:53], v[16:17], off offset:2560
	s_nop 0
	s_nop 1
	v_mov_b32_e32 v8, v120
	v_mov_b32_e32 v9, v121
	v_mov_b32_e32 v10, v122
	v_mov_b32_e32 v11, v123
	v_cvt_pk_bf16_f32 v12, v4, v5
	v_cvt_pk_bf16_f32 v13, v6, v7
	v_pk_mul_f32 v[4:5], v[4:5], v[56:57] op_sel_hi:[1,0]
	v_pk_mul_f32 v[6:7], v[6:7], v[56:57] op_sel_hi:[1,0]
	s_nop 0
	v_pk_mul_f32 v[4:5], v[4:5], v[8:9]
	v_pk_mul_f32 v[6:7], v[6:7], v[10:11]
	v_cvt_pk_bf16_f32 v4, v4, v5
	v_cvt_pk_bf16_f32 v5, v6, v7
	global_store_dwordx2 v[50:51], v[4:5], off offset:3072
	global_store_dwordx2 v[52:53], v[12:13], off offset:3072
	s_nop 0
	s_nop 1
	v_mov_b32_e32 v4, v124
	v_mov_b32_e32 v5, v125
	v_mov_b32_e32 v6, v126
	v_mov_b32_e32 v7, v127
	v_cvt_pk_bf16_f32 v8, v0, v1
	v_cvt_pk_bf16_f32 v9, v2, v3
	v_pk_mul_f32 v[0:1], v[0:1], v[56:57] op_sel_hi:[1,0]
	v_pk_mul_f32 v[2:3], v[2:3], v[56:57] op_sel_hi:[1,0]
	s_nop 0
	v_pk_mul_f32 v[0:1], v[0:1], v[4:5]
	v_pk_mul_f32 v[2:3], v[2:3], v[6:7]
	v_cvt_pk_bf16_f32 v0, v0, v1
	v_cvt_pk_bf16_f32 v1, v2, v3
	global_store_dwordx2 v[50:51], v[0:1], off offset:3584
	global_store_dwordx2 v[52:53], v[8:9], off offset:3584
	s_cbranch_scc0 .LBB0_93

; __device__ __forceinline__ void phase_norm(const Frame& F, const bf16* x, const float* gain, bf16* xn) {
;     for (int m = 2 * F.gw; m < T; m += 2 * F.NGW) {
;         v4u v[2][4]; float s[2] = {0.f, 0.f};
; #pragma unroll
;         for (int r = 0; r < 2; ++r) { const v4u* xr = (const v4u*)(x + (size_t)(m + r) * D) + F.lane;
; #pragma unroll
;             for (int j = 0; j < 4; ++j) v[r][j] = xr[64 * j]; }
; #pragma unroll
;         for (int r = 0; r < 2; ++r)
; #pragma unroll
;             for (int j = 0; j < 4; ++j)
; #pragma unroll
;                 for (int q = 0; q < 4; ++q) { const float a = bf_lo(v[r][j][q]), b = bf_hi(v[r][j][q]); s[r] += a * a + b * b; }
.LBB0_148:
	s_nop 0
	v_lshl_add_u64 v[2:3], s[12:13], 0, v[184:185]
	v_add_co_u32_e64 v44, s[4:5], s56, v2
	v_lshl_add_u64 v[0:1], s[16:17], 0, v[184:185]
	s_nop 0
	v_addc_co_u32_e64 v45, s[4:5], 0, v3, s[4:5]
	v_add_co_u32_e64 v42, s[4:5], s54, v2
	v_add_co_u32_e32 v4, vcc, 0xa000000, v0
	s_nop 0
	v_addc_co_u32_e64 v43, s[4:5], 0, v3, s[4:5]
	s_mov_b64 s[4:5], vcc
	s_nop 0
	v_addc_co_u32_e64 v5, s[4:5], 0, v1, s[4:5]
	v_add_co_u32_e32 v0, vcc, s87, v0
	global_load_dwordx4 v[16:19], v[4:5], off offset:3072
	global_load_dwordx4 v[48:51], v[4:5], off
	global_load_dwordx4 v[32:35], v[4:5], off offset:1024
	global_load_dwordx4 v[24:27], v[4:5], off offset:2048
	v_addc_co_u32_e32 v1, vcc, 0, v1, vcc
	global_load_dwordx4 v[12:15], v[0:1], off
	global_load_dwordx4 v[8:11], v[0:1], off offset:1024
	global_load_dwordx4 v[4:7], v[0:1], off offset:2048
	s_nop 0
	global_load_dwordx4 v[0:3], v[0:1], off offset:3072
	v_mbcnt_lo_u32_b32 v46, -1, 0
	v_mbcnt_hi_u32_b32 v46, -1, v46
	v_mbcnt_lo_u32_b32 v47, -1, 0
	v_mbcnt_hi_u32_b32 v47, -1, v47
	v_mbcnt_lo_u32_b32 v52, -1, 0
	v_mbcnt_hi_u32_b32 v52, -1, v52
	v_mbcnt_lo_u32_b32 v53, -1, 0
	v_mbcnt_hi_u32_b32 v53, -1, v53
	v_mbcnt_lo_u32_b32 v54, -1, 0
	v_mbcnt_hi_u32_b32 v54, -1, v54
	v_mbcnt_lo_u32_b32 v55, -1, 0
	v_mbcnt_hi_u32_b32 v55, -1, v55
	s_nop 0
	v_lshlrev_b32_e32 v46, 2, v46
	v_lshlrev_b32_e32 v47, 2, v47
	v_xor_b32_e32 v107, 4, v46
	v_xor_b32_e32 v108, 8, v47
	v_lshlrev_b32_e32 v52, 2, v52
	v_lshlrev_b32_e32 v53, 2, v53
	v_lshlrev_b32_e32 v54, 2, v54
	v_lshlrev_b32_e32 v55, 2, v55
	v_xor_b32_e32 v109, 16, v52
	v_xor_b32_e32 v110, 32, v53
	v_xor_b32_e32 v111, 64, v54
	v_xor_b32_e32 v112, 0x80, v55
	s_nop 0
	s_nop 0
	s_add_i32 s10, s10, s8
	s_add_u32 s12, s12, s14
	s_addc_u32 s13, s13, s15
	s_add_u32 s16, s16, s14
	s_addc_u32 s17, s17, s15
	s_cmp_lt_i32 s10, 0xa000
	s_waitcnt vmcnt(0)
	s_nop 1
	v_mov_b32_e32 v20, v132
	v_mov_b32_e32 v21, v133
	v_mov_b32_e32 v22, v134
	v_mov_b32_e32 v23, v135
	s_nop 1
	v_mov_b32_e32 v28, v136
	v_mov_b32_e32 v29, v137
	v_mov_b32_e32 v30, v138
	v_mov_b32_e32 v31, v139
	v_and_b32_e32 v47, 0xffff0000, v19
	v_and_b32_e32 v46, 0xffff0000, v18
	v_lshlrev_b32_e32 v72, 16, v49
	v_and_b32_e32 v73, 0xffff0000, v49
	v_lshlrev_b32_e32 v74, 16, v48
	v_and_b32_e32 v75, 0xffff0000, v48
	v_lshlrev_b32_e32 v67, 16, v19
	v_lshlrev_b32_e32 v66, 16, v18
	v_lshlrev_b32_e32 v68, 16, v51
	v_and_b32_e32 v69, 0xffff0000, v51
	v_lshlrev_b32_e32 v70, 16, v50
	v_and_b32_e32 v71, 0xffff0000, v50
	v_pk_mul_f32 v[76:77], v[46:47], v[46:47]
	v_pk_mul_f32 v[82:83], v[72:73], v[72:73]
	v_pk_mul_f32 v[84:85], v[74:75], v[74:75]
	v_lshlrev_b32_e32 v58, 16, v35
	v_and_b32_e32 v59, 0xffff0000, v35
	v_lshlrev_b32_e32 v60, 16, v34
	v_and_b32_e32 v61, 0xffff0000, v34
	v_lshlrev_b32_e32 v62, 16, v33
	v_and_b32_e32 v63, 0xffff0000, v33
	v_lshlrev_b32_e32 v64, 16, v32
	v_and_b32_e32 v65, 0xffff0000, v32
	v_lshlrev_b32_e32 v50, 16, v27
	v_and_b32_e32 v51, 0xffff0000, v27
	v_lshlrev_b32_e32 v52, 16, v26
	v_and_b32_e32 v53, 0xffff0000, v26
	v_lshlrev_b32_e32 v54, 16, v25
	v_and_b32_e32 v55, 0xffff0000, v25
	v_lshlrev_b32_e32 v56, 16, v24
	v_and_b32_e32 v57, 0xffff0000, v24
	v_lshlrev_b32_e32 v32, 16, v17
	v_and_b32_e32 v33, 0xffff0000, v17
	v_lshlrev_b32_e32 v34, 16, v16
	v_and_b32_e32 v35, 0xffff0000, v16
	v_pk_mul_f32 v[78:79], v[68:69], v[68:69]
	v_pk_mul_f32 v[80:81], v[70:71], v[70:71]
	v_lshlrev_b32_e32 v16, 16, v15
	v_and_b32_e32 v17, 0xffff0000, v15
	v_lshlrev_b32_e32 v18, 16, v14
	v_and_b32_e32 v19, 0xffff0000, v14
	v_lshlrev_b32_e32 v24, 16, v13
	v_and_b32_e32 v25, 0xffff0000, v13
	v_lshlrev_b32_e32 v26, 16, v12
	v_and_b32_e32 v27, 0xffff0000, v12
	v_lshlrev_b32_e32 v12, 16, v11
	v_and_b32_e32 v13, 0xffff0000, v11
	v_lshlrev_b32_e32 v14, 16, v10
	v_and_b32_e32 v15, 0xffff0000, v10
	v_lshlrev_b32_e32 v10, 16, v9
	v_and_b32_e32 v11, 0xffff0000, v9
	v_lshlrev_b32_e32 v48, 16, v8
	v_and_b32_e32 v49, 0xffff0000, v8
	v_pk_fma_f32 v[8:9], v[66:67], v[66:67], v[76:77]
	v_add_f32_e32 v76, v82, v83
	v_add_f32_e32 v77, v84, v85
	v_mov_b32_e32 v106, v66
	v_add_f32_e32 v66, v78, v79
	v_add_f32_e32 v78, v80, v81
	v_add_f32_e32 v76, v77, v76
	v_pk_mul_f32 v[92:93], v[64:65], v[64:65]
	v_add_f32_e32 v76, v78, v76
	v_pk_mul_f32 v[90:91], v[62:63], v[62:63]
	v_add_f32_e32 v79, v92, v93
	v_add_f32_e32 v66, v66, v76
	v_pk_mul_f32 v[88:89], v[60:61], v[60:61]
	v_add_f32_e32 v80, v90, v91
	v_add_f32_e32 v66, v79, v66
	v_pk_mul_f32 v[86:87], v[58:59], v[58:59]
	v_add_f32_e32 v81, v88, v89
	v_add_f32_e32 v66, v80, v66
	v_pk_mul_f32 v[98:99], v[56:57], v[56:57]
	v_add_f32_e32 v82, v86, v87
	v_add_f32_e32 v66, v81, v66
	v_pk_mul_f32 v[100:101], v[54:55], v[54:55]
	v_add_f32_e32 v83, v98, v99
	v_add_f32_e32 v66, v82, v66
	v_pk_mul_f32 v[96:97], v[52:53], v[52:53]
	v_add_f32_e32 v84, v100, v101
	v_add_f32_e32 v66, v83, v66
	v_pk_mul_f32 v[94:95], v[50:51], v[50:51]
	v_add_f32_e32 v85, v96, v97
	v_add_f32_e32 v66, v84, v66
	v_pk_mul_f32 v[102:103], v[34:35], v[34:35]
	v_add_f32_e32 v86, v94, v95
	v_add_f32_e32 v66, v85, v66
	v_pk_mul_f32 v[104:105], v[32:33], v[32:33]
	v_add_f32_e32 v87, v102, v103
	v_add_f32_e32 v66, v86, v66
	v_add_f32_e32 v88, v104, v105
	v_add_f32_e32 v66, v87, v66
	v_add_f32_e32 v66, v88, v66
	v_add_f32_e32 v8, v8, v66
	v_add_f32_e32 v8, v9, v8
	ds_bpermute_b32 v9, v107, v8
	v_mov_b32_e32 v107, v46
	v_mov_b32_e32 v46, v67
	v_pk_mul_f32 v[82:83], v[48:49], v[48:49]
	v_pk_mul_f32 v[80:81], v[10:11], v[10:11]
	s_waitcnt lgkmcnt(0)
	v_add_f32_e32 v8, v8, v9
	ds_bpermute_b32 v9, v108, v8
	s_waitcnt lgkmcnt(0)
	v_add_f32_e32 v8, v8, v9
	ds_bpermute_b32 v9, v109, v8
	s_waitcnt lgkmcnt(0)
; __device__ __forceinline__ unsigned pk2(float lo, float hi) { return cvt_pk_bf16(lo, hi); }
; __device__ __forceinline__ void phase_norm(const Frame& F, const bf16* x, const float* gain, bf16* xn) {
;     ...
;                 for (int q = 0; q < 4; ++q) { const float a = bf_lo(v[r][j][q]), b = bf_hi(v[r][j][q]); s[r] += a * a + b * b; }
;         const f32x4* gr = (const f32x4*)gain + 2 * F.lane;
; #pragma unroll
;         for (int r = 0; r < 2; ++r) {
;             const float rstd = 1.0f / sqrtf(wave_sum(s[r]) * (1.0f / D) + 1e-6f);
;             v4u* o = (v4u*)(xn + (size_t)(m + r) * D) + F.lane;
; #pragma unroll
;             for (int j = 0; j < 4; ++j) { const f32x4 g0 = gr[128 * j], g1 = gr[128 * j + 1]; const v4u w = v[r][j]; v4u ow;
;                 ow.x = pk2(bf_lo(w.x) * rstd * g0.x, bf_hi(w.x) * rstd * g0.y); ow.y = pk2(bf_lo(w.y) * rstd * g0.z, bf_hi(w.y) * rstd * g0.w);
;                 ow.z = pk2(bf_lo(w.z) * rstd * g1.x, bf_hi(w.z) * rstd * g1.y); ow.w = pk2(bf_lo(w.w) * rstd * g1.z, bf_hi(w.w) * rstd * g1.w);
;                 o[64 * j] = ow; }
	v_add_f32_e32 v8, v8, v9
	ds_bpermute_b32 v9, v110, v8
	s_waitcnt lgkmcnt(0)
	v_add_f32_e32 v8, v8, v9
	ds_bpermute_b32 v9, v111, v8
	s_waitcnt lgkmcnt(0)
	v_add_f32_e32 v8, v8, v9
	ds_bpermute_b32 v9, v112, v8
	s_waitcnt lgkmcnt(0)
	v_add_f32_e32 v8, v8, v9
	v_fmamk_f32 v8, v8, 0x3a000000, v208
	v_mul_f32_e32 v9, 0x4f800000, v8
	v_cmp_gt_f32_e32 vcc, s86, v8
	s_nop 1
	v_cndmask_b32_e32 v8, v8, v9, vcc
	v_sqrt_f32_e32 v9, v8
	s_nop 0
	v_add_u32_e32 v66, -1, v9
	v_add_u32_e32 v76, 1, v9
	v_fma_f32 v77, -v66, v9, v8
	v_fma_f32 v78, -v76, v9, v8
	v_cmp_ge_f32_e64 s[4:5], 0, v77
	s_nop 1
	v_cndmask_b32_e64 v9, v9, v66, s[4:5]
	v_cmp_lt_f32_e64 s[4:5], 0, v78
	s_nop 1
	v_cndmask_b32_e64 v9, v9, v76, s[4:5]
	v_mul_f32_e32 v66, 0x37800000, v9
	v_cndmask_b32_e32 v9, v9, v66, vcc
	v_cmp_class_f32_e32 vcc, v8, v204
	s_nop 1
	v_cndmask_b32_e32 v8, v9, v8, vcc
	v_div_scale_f32 v9, s[4:5], v8, v8, 1.0
	v_rcp_f32_e32 v76, v9
	v_div_scale_f32 v66, vcc, 1.0, v8, 1.0
	v_fma_f32 v77, -v9, v76, 1.0
	v_fmac_f32_e32 v76, v77, v76
	v_mul_f32_e32 v77, v66, v76
	v_fma_f32 v78, -v9, v77, v66
	v_fmac_f32_e32 v77, v78, v76
	v_fma_f32 v9, -v9, v77, v66
	v_div_fmas_f32 v9, v9, v76, v77
	v_div_fixup_f32 v66, v9, v8, 1.0
	v_pk_mul_f32 v[8:9], v[66:67], v[74:75] op_sel_hi:[0,1]
	v_pk_mul_f32 v[72:73], v[66:67], v[72:73] op_sel_hi:[0,1]
	v_pk_mul_f32 v[70:71], v[66:67], v[70:71] op_sel_hi:[0,1]
	v_pk_mul_f32 v[68:69], v[66:67], v[68:69] op_sel_hi:[0,1]
	v_pk_mul_f32 v[8:9], v[28:29], v[8:9]
	v_pk_mul_f32 v[28:29], v[30:31], v[72:73]
	v_pk_mul_f32 v[30:31], v[20:21], v[70:71]
	v_pk_mul_f32 v[68:69], v[22:23], v[68:69]
	v_cvt_pk_bf16_f32 v20, v8, v9
	v_cvt_pk_bf16_f32 v21, v28, v29
	v_cvt_pk_bf16_f32 v22, v30, v31
	v_cvt_pk_bf16_f32 v23, v68, v69
	global_store_dwordx4 v[42:43], v[20:23], off offset:-4096
	s_nop 0
	s_nop 1
	v_mov_b32_e32 v68, v140
	v_mov_b32_e32 v69, v141
	v_mov_b32_e32 v70, v142
	v_mov_b32_e32 v71, v143
	s_nop 0
	s_nop 1
	v_mov_b32_e32 v72, v144
	v_mov_b32_e32 v73, v145
	v_mov_b32_e32 v74, v146
	v_mov_b32_e32 v75, v147
	v_lshlrev_b32_e32 v20, 16, v7
	v_and_b32_e32 v21, 0xffff0000, v7
	v_lshlrev_b32_e32 v22, 16, v6
	v_and_b32_e32 v23, 0xffff0000, v6
	v_pk_mul_f32 v[6:7], v[66:67], v[64:65] op_sel_hi:[0,1]
	v_pk_mul_f32 v[62:63], v[66:67], v[62:63] op_sel_hi:[0,1]
	v_pk_mul_f32 v[60:61], v[66:67], v[60:61] op_sel_hi:[0,1]
	v_pk_mul_f32 v[58:59], v[66:67], v[58:59] op_sel_hi:[0,1]
	v_pk_mul_f32 v[78:79], v[14:15], v[14:15]
	v_lshlrev_b32_e32 v30, 16, v4
	v_and_b32_e32 v31, 0xffff0000, v4
	v_pk_mul_f32 v[76:77], v[12:13], v[12:13]
	v_lshlrev_b32_e32 v28, 16, v5
	v_and_b32_e32 v29, 0xffff0000, v5
	v_pk_mul_f32 v[90:91], v[30:31], v[30:31]
	v_pk_mul_f32 v[88:89], v[28:29], v[28:29]
	v_pk_mul_f32 v[86:87], v[22:23], v[22:23]
	v_pk_mul_f32 v[84:85], v[20:21], v[20:21]
	v_lshlrev_b32_e32 v4, 16, v1
	v_and_b32_e32 v5, 0xffff0000, v1
	v_lshlrev_b32_e32 v9, 16, v3
	v_lshlrev_b32_e32 v8, 16, v2
	v_and_b32_e32 v3, 0xffff0000, v3
	v_and_b32_e32 v2, 0xffff0000, v2
	v_pk_mul_f32 v[92:93], v[4:5], v[4:5]
	s_nop 0
	v_pk_mul_f32 v[6:7], v[68:69], v[6:7]
	v_pk_mul_f32 v[62:63], v[70:71], v[62:63]
	s_nop 0
	v_pk_mul_f32 v[60:61], v[72:73], v[60:61]
	v_pk_mul_f32 v[64:65], v[74:75], v[58:59]
	v_cvt_pk_bf16_f32 v58, v6, v7
	v_cvt_pk_bf16_f32 v59, v62, v63
	v_cvt_pk_bf16_f32 v60, v60, v61
	v_cvt_pk_bf16_f32 v61, v64, v65
	global_store_dwordx4 v[44:45], v[58:61], off offset:1024
	s_nop 0
	s_nop 1
	v_mov_b32_e32 v58, v148
	v_mov_b32_e32 v59, v149
	v_mov_b32_e32 v60, v150
	v_mov_b32_e32 v61, v151
	s_nop 0
	s_nop 0
	s_nop 1
	v_mov_b32_e32 v62, v152
	v_mov_b32_e32 v63, v153
	v_mov_b32_e32 v64, v154
	v_mov_b32_e32 v65, v155
	v_pk_mul_f32 v[68:69], v[16:17], v[16:17]
	v_pk_mul_f32 v[72:73], v[24:25], v[24:25]
	v_add_f32_e32 v67, v68, v69
	v_pk_mul_f32 v[56:57], v[66:67], v[56:57] op_sel_hi:[0,1]
	v_pk_mul_f32 v[54:55], v[66:67], v[54:55] op_sel_hi:[0,1]
	v_pk_mul_f32 v[52:53], v[66:67], v[52:53] op_sel_hi:[0,1]
	v_pk_mul_f32 v[50:51], v[66:67], v[50:51] op_sel_hi:[0,1]
	v_pk_mul_f32 v[74:75], v[26:27], v[26:27]
	v_pk_mul_f32 v[70:71], v[18:19], v[18:19]
	v_add_f32_e32 v68, v72, v73
	v_lshlrev_b32_e32 v6, 16, v0
	v_and_b32_e32 v7, 0xffff0000, v0
	v_add_f32_e32 v69, v86, v87
	v_pk_mul_f32 v[94:95], v[6:7], v[6:7]
	v_pk_mul_f32 v[0:1], v[2:3], v[2:3]
	v_add_f32_e32 v72, v92, v93
	v_pk_fma_f32 v[0:1], v[8:9], v[8:9], v[0:1]
	v_pk_mul_f32 v[32:33], v[66:67], v[32:33] op_sel_hi:[0,1]
	v_pk_mul_f32 v[46:47], v[66:67], v[46:47] op_sel_hi:[0,1]
	s_nop 0
	v_pk_mul_f32 v[56:57], v[58:59], v[56:57]
	v_pk_mul_f32 v[54:55], v[60:61], v[54:55]
	s_nop 0
	v_pk_mul_f32 v[52:53], v[62:63], v[52:53]
	v_pk_mul_f32 v[58:59], v[64:65], v[50:51]
	v_cvt_pk_bf16_f32 v50, v56, v57
	v_cvt_pk_bf16_f32 v51, v54, v55
	v_cvt_pk_bf16_f32 v52, v52, v53
	v_cvt_pk_bf16_f32 v53, v58, v59
	global_store_dwordx4 v[44:45], v[50:53], off offset:2048
	s_nop 0
	s_nop 1
	v_mov_b32_e32 v50, v156
	v_mov_b32_e32 v51, v157
	v_mov_b32_e32 v52, v158
	v_mov_b32_e32 v53, v159
	s_nop 0
	s_nop 0
	s_nop 1
	v_mov_b32_e32 v54, v160
	v_mov_b32_e32 v55, v161
	v_mov_b32_e32 v56, v162
	v_mov_b32_e32 v57, v163
	v_add_f32_e32 v58, v74, v75
	v_add_f32_e32 v59, v70, v71
	v_add_f32_e32 v58, v58, v68
	v_add_f32_e32 v58, v59, v58
	v_add_f32_e32 v60, v82, v83
	v_add_f32_e32 v58, v67, v58
	v_add_f32_e32 v61, v80, v81
	v_add_f32_e32 v58, v60, v58
	v_add_f32_e32 v62, v78, v79
	v_add_f32_e32 v58, v61, v58
	v_add_f32_e32 v63, v76, v77
	v_add_f32_e32 v58, v62, v58
	v_add_f32_e32 v64, v90, v91
	v_add_f32_e32 v58, v63, v58
	v_add_f32_e32 v65, v88, v89
	v_add_f32_e32 v58, v64, v58
	v_add_f32_e32 v58, v65, v58
	v_add_f32_e32 v70, v84, v85
	v_add_f32_e32 v58, v69, v58
; __device__ __forceinline__ unsigned pk2(float lo, float hi) { return cvt_pk_bf16(lo, hi); }
; __device__ __forceinline__ void phase_norm(const Frame& F, const bf16* x, const float* gain, bf16* xn) {
;     ...
;         for (int r = 0; r < 2; ++r) {
;             const float rstd = 1.0f / sqrtf(wave_sum(s[r]) * (1.0f / D) + 1e-6f);
;             v4u* o = (v4u*)(xn + (size_t)(m + r) * D) + F.lane;
; #pragma unroll
;             for (int j = 0; j < 4; ++j) { const f32x4 g0 = gr[128 * j], g1 = gr[128 * j + 1]; const v4u w = v[r][j]; v4u ow;
;                 ow.x = pk2(bf_lo(w.x) * rstd * g0.x, bf_hi(w.x) * rstd * g0.y); ow.y = pk2(bf_lo(w.y) * rstd * g0.z, bf_hi(w.y) * rstd * g0.w);
;                 ow.z = pk2(bf_lo(w.z) * rstd * g1.x, bf_hi(w.z) * rstd * g1.y); ow.w = pk2(bf_lo(w.w) * rstd * g1.z, bf_hi(w.w) * rstd * g1.w);
;                 o[64 * j] = ow; }
	v_add_f32_e32 v71, v94, v95
	v_add_f32_e32 v58, v70, v58
	v_add_f32_e32 v58, v71, v58
	v_add_f32_e32 v58, v72, v58
	v_add_f32_e32 v0, v0, v58
	v_add_f32_e32 v58, v1, v0
	v_pk_mul_f32 v[0:1], v[66:67], v[34:35] op_sel_hi:[0,1]
	v_pk_mul_f32 v[34:35], v[66:67], v[106:107] op_sel_hi:[0,1]
	s_nop 0
	v_pk_mul_f32 v[0:1], v[50:51], v[0:1]
	v_pk_mul_f32 v[50:51], v[52:53], v[32:33]
	s_nop 0
	v_pk_mul_f32 v[34:35], v[54:55], v[34:35]
	v_pk_mul_f32 v[46:47], v[56:57], v[46:47]
	v_cvt_pk_bf16_f32 v32, v0, v1
	v_cvt_pk_bf16_f32 v33, v50, v51
	v_cvt_pk_bf16_f32 v34, v34, v35
	v_cvt_pk_bf16_f32 v35, v46, v47
	global_store_dwordx4 v[44:45], v[32:35], off offset:3072
	v_mbcnt_lo_u32_b32 v0, -1, 0
	v_mbcnt_hi_u32_b32 v0, -1, v0
	v_mbcnt_lo_u32_b32 v1, -1, 0
	v_mbcnt_hi_u32_b32 v1, -1, v1
	v_mbcnt_lo_u32_b32 v50, -1, 0
	v_mbcnt_hi_u32_b32 v50, -1, v50
	v_mbcnt_lo_u32_b32 v51, -1, 0
	v_mbcnt_hi_u32_b32 v51, -1, v51
	v_mbcnt_lo_u32_b32 v52, -1, 0
	v_mbcnt_hi_u32_b32 v52, -1, v52
	v_mbcnt_lo_u32_b32 v53, -1, 0
	v_mbcnt_hi_u32_b32 v53, -1, v53
	s_nop 0
	s_nop 1
	v_mov_b32_e32 v32, v132
	v_mov_b32_e32 v33, v133
	v_mov_b32_e32 v34, v134
	v_mov_b32_e32 v35, v135
	s_nop 0
	s_nop 1
	v_mov_b32_e32 v44, v136
	v_mov_b32_e32 v45, v137
	v_mov_b32_e32 v46, v138
	v_mov_b32_e32 v47, v139
	v_lshlrev_b32_e32 v0, 2, v0
	v_xor_b32_e32 v0, 4, v0
	ds_bpermute_b32 v0, v0, v58
	v_lshlrev_b32_e32 v1, 2, v1
	v_xor_b32_e32 v1, 8, v1
	v_lshlrev_b32_e32 v50, 2, v50
	v_xor_b32_e32 v50, 16, v50
	s_waitcnt lgkmcnt(0)
	v_add_f32_e32 v0, v58, v0
	ds_bpermute_b32 v1, v1, v0
	v_lshlrev_b32_e32 v51, 2, v51
	v_xor_b32_e32 v51, 32, v51
	v_lshlrev_b32_e32 v52, 2, v52
	v_xor_b32_e32 v52, 64, v52
	s_waitcnt lgkmcnt(0)
	v_add_f32_e32 v0, v0, v1
	ds_bpermute_b32 v1, v50, v0
	v_lshlrev_b32_e32 v53, 2, v53
	v_xor_b32_e32 v53, 0x80, v53
	s_waitcnt lgkmcnt(0)
	v_add_f32_e32 v0, v0, v1
	ds_bpermute_b32 v1, v51, v0
	s_waitcnt lgkmcnt(0)
	v_add_f32_e32 v0, v0, v1
	ds_bpermute_b32 v1, v52, v0
	s_waitcnt lgkmcnt(0)
	v_add_f32_e32 v0, v0, v1
	ds_bpermute_b32 v1, v53, v0
	s_waitcnt lgkmcnt(0)
	v_add_f32_e32 v0, v0, v1
	v_fmamk_f32 v0, v0, 0x3a000000, v208
	v_mul_f32_e32 v1, 0x4f800000, v0
	v_cmp_gt_f32_e32 vcc, s86, v0
	s_nop 1
	v_cndmask_b32_e32 v0, v0, v1, vcc
	v_sqrt_f32_e32 v1, v0
	s_nop 0
	v_add_u32_e32 v50, -1, v1
	v_add_u32_e32 v51, 1, v1
	v_fma_f32 v52, -v50, v1, v0
	v_fma_f32 v53, -v51, v1, v0
	v_cmp_ge_f32_e64 s[4:5], 0, v52
	s_nop 1
	v_cndmask_b32_e64 v1, v1, v50, s[4:5]
	v_cmp_lt_f32_e64 s[4:5], 0, v53
	s_nop 1
	v_cndmask_b32_e64 v1, v1, v51, s[4:5]
	v_mul_f32_e32 v50, 0x37800000, v1
	v_cndmask_b32_e32 v1, v1, v50, vcc
	v_cmp_class_f32_e32 vcc, v0, v204
	s_nop 1
	v_cndmask_b32_e32 v0, v1, v0, vcc
	v_div_scale_f32 v1, s[4:5], v0, v0, 1.0
	v_rcp_f32_e32 v51, v1
	v_div_scale_f32 v50, vcc, 1.0, v0, 1.0
	v_fma_f32 v52, -v1, v51, 1.0
	v_fmac_f32_e32 v51, v52, v51
	v_mul_f32_e32 v52, v50, v51
	v_fma_f32 v53, -v1, v52, v50
	v_fmac_f32_e32 v52, v53, v51
	v_fma_f32 v1, -v1, v52, v50
	v_div_fmas_f32 v1, v1, v51, v52
	v_div_fixup_f32 v0, v1, v0, 1.0
	v_pk_mul_f32 v[26:27], v[0:1], v[26:27] op_sel_hi:[0,1]
	v_pk_mul_f32 v[24:25], v[0:1], v[24:25] op_sel_hi:[0,1]
	v_pk_mul_f32 v[18:19], v[0:1], v[18:19] op_sel_hi:[0,1]
	v_pk_mul_f32 v[16:17], v[0:1], v[16:17] op_sel_hi:[0,1]
	s_nop 0
	v_pk_mul_f32 v[26:27], v[44:45], v[26:27]
	v_pk_mul_f32 v[24:25], v[46:47], v[24:25]
	v_pk_mul_f32 v[18:19], v[32:33], v[18:19]
	v_pk_mul_f32 v[32:33], v[34:35], v[16:17]
	v_cvt_pk_bf16_f32 v16, v26, v27
	v_cvt_pk_bf16_f32 v17, v24, v25
	v_cvt_pk_bf16_f32 v18, v18, v19
	v_cvt_pk_bf16_f32 v19, v32, v33
	global_store_dwordx4 v[42:43], v[16:19], off
	s_nop 0
	s_nop 1
	v_mov_b32_e32 v16, v140
	v_mov_b32_e32 v17, v141
	v_mov_b32_e32 v18, v142
	v_mov_b32_e32 v19, v143
	s_nop 0
	s_nop 0
	s_nop 1
	v_mov_b32_e32 v24, v144
	v_mov_b32_e32 v25, v145
	v_mov_b32_e32 v26, v146
	v_mov_b32_e32 v27, v147
	v_pk_mul_f32 v[32:33], v[0:1], v[48:49] op_sel_hi:[0,1]
	v_pk_mul_f32 v[10:11], v[0:1], v[10:11] op_sel_hi:[0,1]
	v_pk_mul_f32 v[14:15], v[0:1], v[14:15] op_sel_hi:[0,1]
	v_pk_mul_f32 v[12:13], v[0:1], v[12:13] op_sel_hi:[0,1]
	v_pk_mul_f32 v[22:23], v[0:1], v[22:23] op_sel_hi:[0,1]
	v_pk_mul_f32 v[20:21], v[0:1], v[20:21] op_sel_hi:[0,1]
	v_pk_mul_f32 v[6:7], v[0:1], v[6:7] op_sel_hi:[0,1]
	v_pk_mul_f32 v[4:5], v[0:1], v[4:5] op_sel_hi:[0,1]
	s_nop 0
	v_pk_mul_f32 v[16:17], v[16:17], v[32:33]
	v_pk_mul_f32 v[18:19], v[18:19], v[10:11]
	s_nop 0
	v_pk_mul_f32 v[14:15], v[24:25], v[14:15]
	v_pk_mul_f32 v[24:25], v[26:27], v[12:13]
	v_cvt_pk_bf16_f32 v10, v16, v17
	v_cvt_pk_bf16_f32 v11, v18, v19
	v_cvt_pk_bf16_f32 v12, v14, v15
	v_cvt_pk_bf16_f32 v13, v24, v25
	global_store_dwordx4 v[42:43], v[10:13], off offset:1024
	s_nop 0
	s_nop 1
	v_mov_b32_e32 v10, v148
	v_mov_b32_e32 v11, v149
	v_mov_b32_e32 v12, v150
	v_mov_b32_e32 v13, v151
	s_nop 0
	s_nop 0
	s_nop 1
	v_mov_b32_e32 v14, v152
	v_mov_b32_e32 v15, v153
	v_mov_b32_e32 v16, v154
	v_mov_b32_e32 v17, v155
	v_pk_mul_f32 v[18:19], v[0:1], v[30:31] op_sel_hi:[0,1]
	v_pk_mul_f32 v[24:25], v[0:1], v[28:29] op_sel_hi:[0,1]
	s_nop 0
	v_pk_mul_f32 v[10:11], v[18:19], v[10:11]
	v_pk_mul_f32 v[12:13], v[24:25], v[12:13]
	s_nop 0
	v_pk_mul_f32 v[14:15], v[22:23], v[14:15]
	v_pk_mul_f32 v[16:17], v[20:21], v[16:17]
	v_cvt_pk_bf16_f32 v10, v10, v11
	v_cvt_pk_bf16_f32 v11, v12, v13
	v_cvt_pk_bf16_f32 v12, v14, v15
	v_cvt_pk_bf16_f32 v13, v16, v17
	global_store_dwordx4 v[42:43], v[10:13], off offset:2048
	s_nop 0
	s_nop 1
	v_mov_b32_e32 v10, v156
	v_mov_b32_e32 v11, v157
	v_mov_b32_e32 v12, v158
	v_mov_b32_e32 v13, v159
	s_nop 0
	s_nop 0
	s_nop 1
	v_mov_b32_e32 v14, v160
	v_mov_b32_e32 v15, v161
	v_mov_b32_e32 v16, v162
	v_mov_b32_e32 v17, v163
	v_mov_b32_e32 v18, v8
	v_mov_b32_e32 v19, v2
	v_mov_b32_e32 v2, v9
	v_pk_mul_f32 v[8:9], v[0:1], v[18:19] op_sel_hi:[0,1]
	v_pk_mul_f32 v[0:1], v[0:1], v[2:3] op_sel_hi:[0,1]
	s_nop 0
	v_pk_mul_f32 v[2:3], v[6:7], v[10:11]
	v_pk_mul_f32 v[4:5], v[4:5], v[12:13]
	s_nop 0
	v_pk_mul_f32 v[6:7], v[8:9], v[14:15]
	v_pk_mul_f32 v[8:9], v[0:1], v[16:17]
	v_cvt_pk_bf16_f32 v0, v2, v3
	v_cvt_pk_bf16_f32 v1, v4, v5
	v_cvt_pk_bf16_f32 v2, v6, v7
	v_cvt_pk_bf16_f32 v3, v8, v9
	global_store_dwordx4 v[42:43], v[0:3], off offset:3072
	s_cbranch_scc1 .LBB0_148

; __device__ __forceinline__ void phase_norm(const Frame& F, const bf16* x, const float* gain, bf16* xn) {
;     for (int m = 2 * F.gw; m < T; m += 2 * F.NGW) {
;         v4u v[2][4]; float s[2] = {0.f, 0.f};
; #pragma unroll
;         for (int r = 0; r < 2; ++r) { const v4u* xr = (const v4u*)(x + (size_t)(m + r) * D) + F.lane;
; #pragma unroll
;             for (int j = 0; j < 4; ++j) v[r][j] = xr[64 * j]; }
; #pragma unroll
;         for (int r = 0; r < 2; ++r)
; #pragma unroll
;             for (int j = 0; j < 4; ++j)
; #pragma unroll
;                 for (int q = 0; q < 4; ++q) { const float a = bf_lo(v[r][j][q]), b = bf_hi(v[r][j][q]); s[r] += a * a + b * b; }
.LBB0_335:
	v_lshl_add_u64 v[0:1], s[16:17], 0, v[184:185]
	v_add_co_u32_e32 v2, vcc, 0xa000000, v0
	v_lshl_add_u64 v[44:45], s[12:13], 0, v[184:185]
	s_nop 0
	v_addc_co_u32_e32 v3, vcc, 0, v1, vcc
	global_load_dwordx4 v[46:49], v[2:3], off
	global_load_dwordx4 v[24:27], v[2:3], off offset:1024
	global_load_dwordx4 v[20:23], v[2:3], off offset:2048
	global_load_dwordx4 v[16:19], v[2:3], off offset:3072
	v_add_co_u32_e32 v0, vcc, s87, v0
	s_add_i32 s10, s10, s8
	s_nop 0
	v_addc_co_u32_e32 v1, vcc, 0, v1, vcc
	global_load_dwordx4 v[12:15], v[0:1], off
	global_load_dwordx4 v[8:11], v[0:1], off offset:1024
	global_load_dwordx4 v[4:7], v[0:1], off offset:2048
	s_nop 0
	global_load_dwordx4 v[0:3], v[0:1], off offset:3072
	v_mbcnt_lo_u32_b32 v42, -1, 0
	v_mbcnt_hi_u32_b32 v42, -1, v42
	s_add_u32 s12, s12, s14
	v_lshlrev_b32_e32 v42, 2, v42
	v_xor_b32_e32 v98, 4, v42
	v_mbcnt_lo_u32_b32 v42, -1, 0
	v_mbcnt_hi_u32_b32 v42, -1, v42
	s_addc_u32 s13, s13, s15
	v_lshlrev_b32_e32 v42, 2, v42
	v_xor_b32_e32 v99, 8, v42
	v_mbcnt_lo_u32_b32 v42, -1, 0
	v_mbcnt_hi_u32_b32 v42, -1, v42
	s_add_u32 s16, s16, s14
	v_lshlrev_b32_e32 v42, 2, v42
	v_xor_b32_e32 v100, 16, v42
	v_mbcnt_lo_u32_b32 v42, -1, 0
	v_mbcnt_hi_u32_b32 v42, -1, v42
	s_addc_u32 s17, s17, s15
	v_lshlrev_b32_e32 v42, 2, v42
	v_xor_b32_e32 v101, 32, v42
	v_mbcnt_lo_u32_b32 v42, -1, 0
	v_mbcnt_hi_u32_b32 v42, -1, v42
	s_cmp_lt_i32 s10, 0xa000
	v_lshlrev_b32_e32 v42, 2, v42
	v_xor_b32_e32 v102, 64, v42
	v_mbcnt_lo_u32_b32 v42, -1, 0
	v_mbcnt_hi_u32_b32 v42, -1, v42
	s_nop 0
	s_nop 0
	v_lshlrev_b32_e32 v42, 2, v42
	v_xor_b32_e32 v103, 0x80, v42
	s_waitcnt vmcnt(0)
	s_nop 1
	v_mov_b32_e32 v60, v132
	v_mov_b32_e32 v61, v133
	v_mov_b32_e32 v62, v134
	v_mov_b32_e32 v63, v135
	s_nop 1
	v_mov_b32_e32 v64, v136
	v_mov_b32_e32 v65, v137
	v_mov_b32_e32 v66, v138
	v_mov_b32_e32 v67, v139
	v_lshlrev_b32_e32 v68, 16, v49
	v_and_b32_e32 v69, 0xffff0000, v49
	v_lshlrev_b32_e32 v76, 16, v47
	v_and_b32_e32 v77, 0xffff0000, v47
	v_lshlrev_b32_e32 v80, 16, v46
	v_and_b32_e32 v81, 0xffff0000, v46
	v_pk_mul_f32 v[70:71], v[68:69], v[68:69]
	v_lshlrev_b32_e32 v72, 16, v48
	v_and_b32_e32 v73, 0xffff0000, v48
	v_pk_mul_f32 v[78:79], v[76:77], v[76:77]
	v_pk_mul_f32 v[82:83], v[80:81], v[80:81]
	v_pk_mul_f32 v[74:75], v[72:73], v[72:73]
	v_add_f32_e32 v70, v70, v71
	v_add_f32_e32 v71, v78, v79
	v_add_f32_e32 v78, v82, v83
	v_lshlrev_b32_e32 v58, 16, v24
	v_and_b32_e32 v59, 0xffff0000, v24
	v_add_f32_e32 v71, v78, v71
	v_add_f32_e32 v74, v74, v75
	v_lshlrev_b32_e32 v54, 16, v25
	v_and_b32_e32 v55, 0xffff0000, v25
	v_pk_mul_f32 v[24:25], v[58:59], v[58:59]
	v_add_f32_e32 v71, v74, v71
	v_lshlrev_b32_e32 v50, 16, v26
	v_and_b32_e32 v51, 0xffff0000, v26
	v_pk_mul_f32 v[86:87], v[54:55], v[54:55]
	v_add_f32_e32 v70, v70, v71
	v_add_f32_e32 v24, v24, v25
	v_lshlrev_b32_e32 v46, 16, v27
	v_and_b32_e32 v47, 0xffff0000, v27
	v_pk_mul_f32 v[26:27], v[50:51], v[50:51]
	v_add_f32_e32 v24, v24, v70
	v_add_f32_e32 v25, v86, v87
	v_pk_mul_f32 v[84:85], v[46:47], v[46:47]
	v_lshlrev_b32_e32 v56, 16, v20
	v_and_b32_e32 v57, 0xffff0000, v20
	v_add_f32_e32 v24, v25, v24
	v_add_f32_e32 v25, v26, v27
	v_lshlrev_b32_e32 v52, 16, v21
	v_and_b32_e32 v53, 0xffff0000, v21
	v_pk_mul_f32 v[94:95], v[56:57], v[56:57]
	v_add_f32_e32 v24, v25, v24
	v_add_f32_e32 v25, v84, v85
	v_lshlrev_b32_e32 v48, 16, v22
	v_and_b32_e32 v49, 0xffff0000, v22
	v_pk_mul_f32 v[92:93], v[52:53], v[52:53]
	v_add_f32_e32 v24, v25, v24
	v_add_f32_e32 v25, v94, v95
	v_lshlrev_b32_e32 v42, 16, v23
	v_and_b32_e32 v43, 0xffff0000, v23
	v_pk_mul_f32 v[90:91], v[48:49], v[48:49]
	v_add_f32_e32 v24, v25, v24
	v_add_f32_e32 v25, v92, v93
	v_pk_mul_f32 v[88:89], v[42:43], v[42:43]
	v_lshlrev_b32_e32 v20, 16, v16
	v_and_b32_e32 v21, 0xffff0000, v16
	v_add_f32_e32 v24, v25, v24
	v_add_f32_e32 v25, v90, v91
	v_lshlrev_b32_e32 v22, 16, v17
	v_and_b32_e32 v23, 0xffff0000, v17
	v_pk_mul_f32 v[16:17], v[20:21], v[20:21]
	v_add_f32_e32 v24, v25, v24
	v_add_f32_e32 v25, v88, v89
	v_and_b32_e32 v41, 0xffff0000, v19
	v_and_b32_e32 v40, 0xffff0000, v18
	v_pk_mul_f32 v[96:97], v[22:23], v[22:23]
	v_add_f32_e32 v24, v25, v24
	v_add_f32_e32 v16, v16, v17
	v_lshlrev_b32_e32 v39, 16, v19
	v_lshlrev_b32_e32 v38, 16, v18
	v_pk_mul_f32 v[18:19], v[40:41], v[40:41]
	v_add_f32_e32 v16, v16, v24
	v_add_f32_e32 v17, v96, v97
	v_pk_fma_f32 v[18:19], v[38:39], v[38:39], v[18:19]
	v_add_f32_e32 v16, v17, v16
	v_add_f32_e32 v16, v18, v16
	v_add_f32_e32 v16, v19, v16
	ds_bpermute_b32 v17, v98, v16
	v_lshlrev_b32_e32 v35, 16, v3
	v_lshlrev_b32_e32 v34, 16, v2
	v_and_b32_e32 v3, 0xffff0000, v3
	v_and_b32_e32 v2, 0xffff0000, v2
	s_waitcnt lgkmcnt(0)
	v_add_f32_e32 v16, v16, v17
	ds_bpermute_b32 v17, v99, v16
	v_pk_mul_f32 v[36:37], v[2:3], v[2:3]
	s_waitcnt lgkmcnt(0)
	v_add_f32_e32 v16, v16, v17
	ds_bpermute_b32 v17, v100, v16
	v_pk_fma_f32 v[36:37], v[34:35], v[34:35], v[36:37]
	s_waitcnt lgkmcnt(0)
	v_add_f32_e32 v16, v16, v17
	ds_bpermute_b32 v17, v101, v16
	s_waitcnt lgkmcnt(0)
	v_add_f32_e32 v16, v16, v17
	ds_bpermute_b32 v17, v102, v16
	s_waitcnt lgkmcnt(0)
	v_add_f32_e32 v16, v16, v17
	ds_bpermute_b32 v17, v103, v16
	s_waitcnt lgkmcnt(0)
; __device__ __forceinline__ unsigned pk2(float lo, float hi) { return cvt_pk_bf16(lo, hi); }
; __device__ __forceinline__ void phase_norm(const Frame& F, const bf16* x, const float* gain, bf16* xn) {
;     ...
;         const f32x4* gr = (const f32x4*)gain + 2 * F.lane;
; #pragma unroll
;         for (int r = 0; r < 2; ++r) {
;             const float rstd = 1.0f / sqrtf(wave_sum(s[r]) * (1.0f / D) + 1e-6f);
;             v4u* o = (v4u*)(xn + (size_t)(m + r) * D) + F.lane;
; #pragma unroll
;             for (int j = 0; j < 4; ++j) { const f32x4 g0 = gr[128 * j], g1 = gr[128 * j + 1]; const v4u w = v[r][j]; v4u ow;
;                 ow.x = pk2(bf_lo(w.x) * rstd * g0.x, bf_hi(w.x) * rstd * g0.y); ow.y = pk2(bf_lo(w.y) * rstd * g0.z, bf_hi(w.y) * rstd * g0.w);
;                 ow.z = pk2(bf_lo(w.z) * rstd * g1.x, bf_hi(w.z) * rstd * g1.y); ow.w = pk2(bf_lo(w.w) * rstd * g1.z, bf_hi(w.w) * rstd * g1.w);
;                 o[64 * j] = ow; }
	v_add_f32_e32 v16, v16, v17
	v_fmamk_f32 v16, v16, 0x3a000000, v208
	v_cmp_gt_f32_e32 vcc, s86, v16
	v_mul_f32_e32 v17, 0x4f800000, v16
	s_nop 0
	v_cndmask_b32_e32 v16, v16, v17, vcc
	v_sqrt_f32_e32 v17, v16
	s_nop 0
	v_add_u32_e32 v18, -1, v17
	v_fma_f32 v19, -v18, v17, v16
	v_cmp_ge_f32_e64 s[4:5], 0, v19
	v_add_u32_e32 v19, 1, v17
	s_nop 0
	v_cndmask_b32_e64 v18, v17, v18, s[4:5]
	v_fma_f32 v17, -v19, v17, v16
	v_cmp_lt_f32_e64 s[4:5], 0, v17
	s_nop 1
	v_cndmask_b32_e64 v17, v18, v19, s[4:5]
	v_mul_f32_e32 v18, 0x37800000, v17
	v_cndmask_b32_e32 v17, v17, v18, vcc
	v_cmp_class_f32_e32 vcc, v16, v204
	s_nop 1
	v_cndmask_b32_e32 v16, v17, v16, vcc
	v_div_scale_f32 v17, s[4:5], v16, v16, 1.0
	v_rcp_f32_e32 v18, v17
	s_nop 0
	v_fma_f32 v19, -v17, v18, 1.0
	v_fmac_f32_e32 v18, v19, v18
	v_div_scale_f32 v19, vcc, 1.0, v16, 1.0
	v_mul_f32_e32 v24, v19, v18
	v_fma_f32 v25, -v17, v24, v19
	v_fmac_f32_e32 v24, v25, v18
	v_fma_f32 v17, -v17, v24, v19
	v_div_fmas_f32 v17, v17, v18, v24
	v_div_fixup_f32 v26, v17, v16, 1.0
	v_pk_mul_f32 v[16:17], v[26:27], v[80:81] op_sel_hi:[0,1]
	v_pk_mul_f32 v[18:19], v[26:27], v[76:77] op_sel_hi:[0,1]
	v_pk_mul_f32 v[16:17], v[64:65], v[16:17]
	v_pk_mul_f32 v[18:19], v[66:67], v[18:19]
	v_cvt_pk_bf16_f32 v16, v16, v17
	v_cvt_pk_bf16_f32 v17, v18, v19
	v_pk_mul_f32 v[18:19], v[26:27], v[72:73] op_sel_hi:[0,1]
	v_pk_mul_f32 v[18:19], v[60:61], v[18:19]
	v_pk_mul_f32 v[24:25], v[26:27], v[68:69] op_sel_hi:[0,1]
	v_add_co_u32_e32 v60, vcc, s56, v44
	v_pk_mul_f32 v[24:25], v[62:63], v[24:25]
	s_nop 0
	v_addc_co_u32_e32 v61, vcc, 0, v45, vcc
	v_cvt_pk_bf16_f32 v18, v18, v19
	v_cvt_pk_bf16_f32 v19, v24, v25
	v_add_co_u32_e32 v24, vcc, s54, v44
	v_pk_mul_f32 v[20:21], v[26:27], v[20:21] op_sel_hi:[0,1]
	s_nop 0
	v_addc_co_u32_e32 v25, vcc, 0, v45, vcc
	global_store_dwordx4 v[24:25], v[16:19], off offset:-4096
	s_nop 0
	s_nop 1
	v_mov_b32_e32 v16, v140
	v_mov_b32_e32 v17, v141
	v_mov_b32_e32 v18, v142
	v_mov_b32_e32 v19, v143
	s_nop 0
	s_nop 0
	s_nop 1
	v_mov_b32_e32 v62, v144
	v_mov_b32_e32 v63, v145
	v_mov_b32_e32 v64, v146
	v_mov_b32_e32 v65, v147
	v_pk_mul_f32 v[44:45], v[26:27], v[58:59] op_sel_hi:[0,1]
	v_pk_mul_f32 v[22:23], v[26:27], v[22:23] op_sel_hi:[0,1]
	s_nop 0
	v_pk_mul_f32 v[44:45], v[62:63], v[44:45]
	s_nop 0
	v_cvt_pk_bf16_f32 v62, v44, v45
	v_pk_mul_f32 v[44:45], v[26:27], v[54:55] op_sel_hi:[0,1]
	v_pk_mul_f32 v[44:45], v[64:65], v[44:45]
	s_nop 0
	v_cvt_pk_bf16_f32 v63, v44, v45
	v_pk_mul_f32 v[44:45], v[26:27], v[50:51] op_sel_hi:[0,1]
	v_pk_mul_f32 v[16:17], v[16:17], v[44:45]
	v_pk_mul_f32 v[50:51], v[26:27], v[56:57] op_sel_hi:[0,1]
	v_cvt_pk_bf16_f32 v64, v16, v17
	v_pk_mul_f32 v[16:17], v[26:27], v[46:47] op_sel_hi:[0,1]
	v_pk_mul_f32 v[16:17], v[18:19], v[16:17]
	s_nop 0
	v_cvt_pk_bf16_f32 v65, v16, v17
	global_store_dwordx4 v[60:61], v[62:65], off offset:1024
	s_nop 0
	s_nop 1
	v_mov_b32_e32 v16, v148
	v_mov_b32_e32 v17, v149
	v_mov_b32_e32 v18, v150
	v_mov_b32_e32 v19, v151
	s_nop 0
	s_nop 1
	v_mov_b32_e32 v44, v152
	v_mov_b32_e32 v45, v153
	v_mov_b32_e32 v46, v154
	v_mov_b32_e32 v47, v155
	s_nop 0
	v_pk_mul_f32 v[44:45], v[44:45], v[50:51]
	v_pk_mul_f32 v[50:51], v[26:27], v[52:53] op_sel_hi:[0,1]
	v_pk_mul_f32 v[46:47], v[46:47], v[50:51]
	v_cvt_pk_bf16_f32 v44, v44, v45
	v_cvt_pk_bf16_f32 v45, v46, v47
	v_pk_mul_f32 v[46:47], v[26:27], v[48:49] op_sel_hi:[0,1]
	v_pk_mul_f32 v[16:17], v[16:17], v[46:47]
	v_lshlrev_b32_e32 v50, 16, v8
	v_cvt_pk_bf16_f32 v46, v16, v17
	v_pk_mul_f32 v[16:17], v[26:27], v[42:43] op_sel_hi:[0,1]
	v_pk_mul_f32 v[16:17], v[18:19], v[16:17]
	v_and_b32_e32 v51, 0xffff0000, v8
	v_cvt_pk_bf16_f32 v47, v16, v17
	global_store_dwordx4 v[60:61], v[44:47], off offset:2048
	s_nop 0
	s_nop 1
	v_mov_b32_e32 v16, v156
	v_mov_b32_e32 v17, v157
	v_mov_b32_e32 v18, v158
	v_mov_b32_e32 v19, v159
	s_nop 0
	s_nop 0
	s_nop 1
	v_mov_b32_e32 v42, v160
	v_mov_b32_e32 v43, v161
	v_mov_b32_e32 v44, v162
	v_mov_b32_e32 v45, v163
	v_lshlrev_b32_e32 v48, 16, v9
	v_and_b32_e32 v49, 0xffff0000, v9
	v_pk_mul_f32 v[72:73], v[50:51], v[50:51]
	v_pk_mul_f32 v[68:69], v[48:49], v[48:49]
	v_lshlrev_b32_e32 v8, 16, v7
	v_and_b32_e32 v9, 0xffff0000, v7
	v_and_b32_e32 v7, 0xffff0000, v5
	v_pk_mul_f32 v[62:63], v[8:9], v[8:9]
	v_lshlrev_b32_e32 v46, 16, v0
	v_and_b32_e32 v47, 0xffff0000, v0
	s_nop 0
	v_pk_mul_f32 v[20:21], v[42:43], v[20:21]
	v_pk_mul_f32 v[22:23], v[44:45], v[22:23]
	v_cvt_pk_bf16_f32 v20, v20, v21
	v_cvt_pk_bf16_f32 v21, v22, v23
	v_mov_b32_e32 v22, v38
	v_mov_b32_e32 v23, v40
	v_pk_mul_f32 v[22:23], v[26:27], v[22:23] op_sel_hi:[0,1]
	v_pk_mul_f32 v[16:17], v[16:17], v[22:23]
	v_mov_b32_e32 v40, v39
	v_cvt_pk_bf16_f32 v22, v16, v17
	v_pk_mul_f32 v[16:17], v[26:27], v[40:41] op_sel_hi:[0,1]
	v_pk_mul_f32 v[16:17], v[18:19], v[16:17]
	v_lshlrev_b32_e32 v26, 16, v15
	v_cvt_pk_bf16_f32 v23, v16, v17
	global_store_dwordx4 v[60:61], v[20:23], off offset:3072
	v_mbcnt_lo_u32_b32 v16, -1, 0
	v_mbcnt_hi_u32_b32 v16, -1, v16
	v_and_b32_e32 v27, 0xffff0000, v15
	v_lshlrev_b32_e32 v16, 2, v16
	v_xor_b32_e32 v74, 4, v16
	v_mbcnt_lo_u32_b32 v16, -1, 0
	v_mbcnt_hi_u32_b32 v16, -1, v16
	v_lshlrev_b32_e32 v38, 16, v14
	v_lshlrev_b32_e32 v16, 2, v16
	v_xor_b32_e32 v75, 8, v16
	v_mbcnt_lo_u32_b32 v16, -1, 0
	v_mbcnt_hi_u32_b32 v16, -1, v16
	v_and_b32_e32 v39, 0xffff0000, v14
	v_lshlrev_b32_e32 v16, 2, v16
	v_xor_b32_e32 v76, 16, v16
	v_mbcnt_lo_u32_b32 v16, -1, 0
	v_mbcnt_hi_u32_b32 v16, -1, v16
	v_lshlrev_b32_e32 v14, 16, v13
	v_lshlrev_b32_e32 v16, 2, v16
	v_xor_b32_e32 v77, 32, v16
	v_mbcnt_lo_u32_b32 v16, -1, 0
	v_mbcnt_hi_u32_b32 v16, -1, v16
	v_and_b32_e32 v15, 0xffff0000, v13
; __device__ __forceinline__ unsigned pk2(float lo, float hi) { return cvt_pk_bf16(lo, hi); }
; __device__ __forceinline__ void phase_norm(const Frame& F, const bf16* x, const float* gain, bf16* xn) {
;     ...
;                 for (int q = 0; q < 4; ++q) { const float a = bf_lo(v[r][j][q]), b = bf_hi(v[r][j][q]); s[r] += a * a + b * b; }
;         const f32x4* gr = (const f32x4*)gain + 2 * F.lane;
; #pragma unroll
;         for (int r = 0; r < 2; ++r) {
;             const float rstd = 1.0f / sqrtf(wave_sum(s[r]) * (1.0f / D) + 1e-6f);
;             v4u* o = (v4u*)(xn + (size_t)(m + r) * D) + F.lane;
; #pragma unroll
;             for (int j = 0; j < 4; ++j) { const f32x4 g0 = gr[128 * j], g1 = gr[128 * j + 1]; const v4u w = v[r][j]; v4u ow;
;                 ow.x = pk2(bf_lo(w.x) * rstd * g0.x, bf_hi(w.x) * rstd * g0.y); ow.y = pk2(bf_lo(w.y) * rstd * g0.z, bf_hi(w.y) * rstd * g0.w);
;                 ow.z = pk2(bf_lo(w.z) * rstd * g1.x, bf_hi(w.z) * rstd * g1.y); ow.w = pk2(bf_lo(w.w) * rstd * g1.z, bf_hi(w.w) * rstd * g1.w);
;                 o[64 * j] = ow; }
	v_lshlrev_b32_e32 v40, 16, v12
	v_and_b32_e32 v41, 0xffff0000, v12
	v_lshlrev_b32_e32 v16, 2, v16
	v_pk_mul_f32 v[54:55], v[26:27], v[26:27]
	v_pk_mul_f32 v[56:57], v[14:15], v[14:15]
	v_pk_mul_f32 v[60:61], v[40:41], v[40:41]
	v_xor_b32_e32 v78, 64, v16
	v_mbcnt_lo_u32_b32 v16, -1, 0
	v_mbcnt_hi_u32_b32 v16, -1, v16
	v_pk_mul_f32 v[52:53], v[38:39], v[38:39]
	v_add_f32_e32 v54, v54, v55
	v_add_f32_e32 v55, v56, v57
	v_add_f32_e32 v56, v60, v61
	v_lshlrev_b32_e32 v16, 2, v16
	v_add_f32_e32 v55, v56, v55
	v_add_f32_e32 v52, v52, v53
	v_xor_b32_e32 v79, 0x80, v16
	s_nop 0
	s_nop 1
	v_mov_b32_e32 v16, v132
	v_mov_b32_e32 v17, v133
	v_mov_b32_e32 v18, v134
	v_mov_b32_e32 v19, v135
	s_nop 0
	s_nop 1
	v_mov_b32_e32 v20, v136
	v_mov_b32_e32 v21, v137
	v_mov_b32_e32 v22, v138
	v_mov_b32_e32 v23, v139
	v_add_f32_e32 v52, v52, v55
	v_lshlrev_b32_e32 v44, 16, v10
	v_and_b32_e32 v45, 0xffff0000, v10
	v_add_f32_e32 v52, v54, v52
	v_add_f32_e32 v53, v72, v73
	v_lshlrev_b32_e32 v12, 16, v11
	v_and_b32_e32 v13, 0xffff0000, v11
	v_pk_mul_f32 v[64:65], v[44:45], v[44:45]
	v_add_f32_e32 v52, v53, v52
	v_add_f32_e32 v53, v68, v69
	v_pk_mul_f32 v[58:59], v[12:13], v[12:13]
	v_lshlrev_b32_e32 v42, 16, v4
	v_and_b32_e32 v43, 0xffff0000, v4
	v_add_f32_e32 v52, v53, v52
	v_add_f32_e32 v53, v64, v65
	v_lshlrev_b32_e32 v10, 16, v6
	v_and_b32_e32 v11, 0xffff0000, v6
	v_lshlrev_b32_e32 v6, 16, v5
	v_pk_mul_f32 v[80:81], v[42:43], v[42:43]
	v_add_f32_e32 v52, v53, v52
	v_add_f32_e32 v53, v58, v59
	v_pk_mul_f32 v[70:71], v[6:7], v[6:7]
	v_add_f32_e32 v52, v53, v52
	v_add_f32_e32 v53, v80, v81
	v_pk_mul_f32 v[66:67], v[10:11], v[10:11]
	v_add_f32_e32 v52, v53, v52
	v_add_f32_e32 v53, v70, v71
	v_add_f32_e32 v52, v53, v52
	v_add_f32_e32 v53, v66, v67
	v_lshlrev_b32_e32 v4, 16, v1
	v_and_b32_e32 v5, 0xffff0000, v1
	v_pk_mul_f32 v[0:1], v[46:47], v[46:47]
	v_add_f32_e32 v52, v53, v52
	v_add_f32_e32 v53, v62, v63
	v_pk_mul_f32 v[82:83], v[4:5], v[4:5]
	v_add_f32_e32 v52, v53, v52
	v_add_f32_e32 v0, v0, v1
	v_add_f32_e32 v0, v0, v52
	v_add_f32_e32 v1, v82, v83
	v_add_f32_e32 v0, v1, v0
	v_add_f32_e32 v0, v36, v0
	v_add_f32_e32 v0, v37, v0
	ds_bpermute_b32 v1, v74, v0
	s_waitcnt lgkmcnt(0)
	v_add_f32_e32 v0, v0, v1
	ds_bpermute_b32 v1, v75, v0
	s_waitcnt lgkmcnt(0)
	v_add_f32_e32 v0, v0, v1
	ds_bpermute_b32 v1, v76, v0
	s_waitcnt lgkmcnt(0)
	v_add_f32_e32 v0, v0, v1
	ds_bpermute_b32 v1, v77, v0
	s_waitcnt lgkmcnt(0)
	v_add_f32_e32 v0, v0, v1
	ds_bpermute_b32 v1, v78, v0
	s_waitcnt lgkmcnt(0)
	v_add_f32_e32 v0, v0, v1
	ds_bpermute_b32 v1, v79, v0
	s_waitcnt lgkmcnt(0)
	v_add_f32_e32 v0, v0, v1
	v_fmamk_f32 v0, v0, 0x3a000000, v208
	v_cmp_gt_f32_e32 vcc, s86, v0
	v_mul_f32_e32 v1, 0x4f800000, v0
	s_nop 0
	v_cndmask_b32_e32 v0, v0, v1, vcc
	v_sqrt_f32_e32 v1, v0
	s_nop 0
	v_add_u32_e32 v36, -1, v1
	v_fma_f32 v37, -v36, v1, v0
	v_cmp_ge_f32_e64 s[4:5], 0, v37
	v_add_u32_e32 v37, 1, v1
	s_nop 0
	v_cndmask_b32_e64 v36, v1, v36, s[4:5]
	v_fma_f32 v1, -v37, v1, v0
	v_cmp_lt_f32_e64 s[4:5], 0, v1
	s_nop 1
	v_cndmask_b32_e64 v1, v36, v37, s[4:5]
	v_mul_f32_e32 v36, 0x37800000, v1
	v_cndmask_b32_e32 v1, v1, v36, vcc
	v_cmp_class_f32_e32 vcc, v0, v204
	s_nop 1
	v_cndmask_b32_e32 v0, v1, v0, vcc
	v_div_scale_f32 v1, s[4:5], v0, v0, 1.0
	v_rcp_f32_e32 v36, v1
	s_nop 0
	v_fma_f32 v37, -v1, v36, 1.0
	v_fmac_f32_e32 v36, v37, v36
	v_div_scale_f32 v37, vcc, 1.0, v0, 1.0
	v_mul_f32_e32 v52, v37, v36
	v_fma_f32 v53, -v1, v52, v37
	v_fmac_f32_e32 v52, v53, v36
	v_fma_f32 v1, -v1, v52, v37
	v_div_fmas_f32 v1, v1, v36, v52
	v_div_fixup_f32 v0, v1, v0, 1.0
	v_pk_mul_f32 v[36:37], v[0:1], v[40:41] op_sel_hi:[0,1]
	v_pk_mul_f32 v[14:15], v[0:1], v[14:15] op_sel_hi:[0,1]
	s_nop 0
	v_pk_mul_f32 v[20:21], v[20:21], v[36:37]
	v_pk_mul_f32 v[14:15], v[22:23], v[14:15]
	v_cvt_pk_bf16_f32 v20, v20, v21
	v_cvt_pk_bf16_f32 v21, v14, v15
	v_pk_mul_f32 v[14:15], v[0:1], v[38:39] op_sel_hi:[0,1]
	v_pk_mul_f32 v[14:15], v[16:17], v[14:15]
	v_pk_mul_f32 v[12:13], v[0:1], v[12:13] op_sel_hi:[0,1]
	v_cvt_pk_bf16_f32 v22, v14, v15
	v_pk_mul_f32 v[14:15], v[0:1], v[26:27] op_sel_hi:[0,1]
	v_pk_mul_f32 v[14:15], v[18:19], v[14:15]
	v_pk_mul_f32 v[6:7], v[0:1], v[6:7] op_sel_hi:[0,1]
	v_cvt_pk_bf16_f32 v23, v14, v15
	global_store_dwordx4 v[24:25], v[20:23], off
	s_nop 0
	s_nop 1
	v_mov_b32_e32 v14, v140
	v_mov_b32_e32 v15, v141
	v_mov_b32_e32 v16, v142
	v_mov_b32_e32 v17, v143
	s_nop 0
	s_nop 0
	s_nop 1
	v_mov_b32_e32 v18, v144
	v_mov_b32_e32 v19, v145
	v_mov_b32_e32 v20, v146
	v_mov_b32_e32 v21, v147
	v_pk_mul_f32 v[22:23], v[0:1], v[50:51] op_sel_hi:[0,1]
	v_pk_mul_f32 v[4:5], v[0:1], v[4:5] op_sel_hi:[0,1]
	s_nop 0
	v_pk_mul_f32 v[12:13], v[16:17], v[12:13]
	s_nop 0
	v_pk_mul_f32 v[18:19], v[18:19], v[22:23]
	v_pk_mul_f32 v[22:23], v[0:1], v[48:49] op_sel_hi:[0,1]
	v_pk_mul_f32 v[20:21], v[20:21], v[22:23]
	v_cvt_pk_bf16_f32 v18, v18, v19
	v_cvt_pk_bf16_f32 v19, v20, v21
	v_pk_mul_f32 v[20:21], v[0:1], v[44:45] op_sel_hi:[0,1]
	v_pk_mul_f32 v[14:15], v[14:15], v[20:21]
	v_cvt_pk_bf16_f32 v21, v12, v13
	v_cvt_pk_bf16_f32 v20, v14, v15
	global_store_dwordx4 v[24:25], v[18:21], off offset:1024
	s_nop 0
	s_nop 1
	v_mov_b32_e32 v12, v148
	v_mov_b32_e32 v13, v149
	v_mov_b32_e32 v14, v150
	v_mov_b32_e32 v15, v151
	s_nop 0
	s_nop 0
	s_nop 1
	v_mov_b32_e32 v16, v152
	v_mov_b32_e32 v17, v153
	v_mov_b32_e32 v18, v154
	v_mov_b32_e32 v19, v155
	v_pk_mul_f32 v[20:21], v[0:1], v[42:43] op_sel_hi:[0,1]
	s_nop 0
	v_pk_mul_f32 v[16:17], v[20:21], v[16:17]
	v_pk_mul_f32 v[6:7], v[6:7], v[18:19]
	v_cvt_pk_bf16_f32 v16, v16, v17
	v_cvt_pk_bf16_f32 v17, v6, v7
	v_pk_mul_f32 v[6:7], v[0:1], v[10:11] op_sel_hi:[0,1]
	v_pk_mul_f32 v[6:7], v[6:7], v[12:13]
	s_nop 0
	v_cvt_pk_bf16_f32 v18, v6, v7
	v_pk_mul_f32 v[6:7], v[0:1], v[8:9] op_sel_hi:[0,1]
	v_pk_mul_f32 v[6:7], v[6:7], v[14:15]
	v_pk_mul_f32 v[14:15], v[0:1], v[46:47] op_sel_hi:[0,1]
	v_cvt_pk_bf16_f32 v19, v6, v7
	global_store_dwordx4 v[24:25], v[16:19], off offset:2048
	s_nop 0
	s_nop 1
	v_mov_b32_e32 v6, v156
	v_mov_b32_e32 v7, v157
	v_mov_b32_e32 v8, v158
	v_mov_b32_e32 v9, v159
	s_nop 0
	s_nop 1
	v_mov_b32_e32 v10, v160
	v_mov_b32_e32 v11, v161
	v_mov_b32_e32 v12, v162
	v_mov_b32_e32 v13, v163
	s_nop 0
	v_pk_mul_f32 v[10:11], v[14:15], v[10:11]
	v_pk_mul_f32 v[4:5], v[4:5], v[12:13]
	v_cvt_pk_bf16_f32 v10, v10, v11
	v_cvt_pk_bf16_f32 v11, v4, v5
	v_mov_b32_e32 v4, v34
	v_mov_b32_e32 v5, v2
	v_mov_b32_e32 v2, v35
	v_pk_mul_f32 v[4:5], v[0:1], v[4:5] op_sel_hi:[0,1]
	v_pk_mul_f32 v[0:1], v[0:1], v[2:3] op_sel_hi:[0,1]
	v_pk_mul_f32 v[4:5], v[4:5], v[6:7]
	v_pk_mul_f32 v[0:1], v[0:1], v[8:9]
	v_cvt_pk_bf16_f32 v12, v4, v5
	v_cvt_pk_bf16_f32 v13, v0, v1
	global_store_dwordx4 v[24:25], v[10:13], off offset:3072
	s_cbranch_scc1 .LBB0_335

; __device__ __forceinline__ void phase_rwkv_pre(const Frame& F, const Args& a, int l) {
;     ...
;             const v4u cur = *(const v4u*)(CF + (size_t)t * 2048 + cb);
;             const v4u prv = hp ? *(const v4u*)(CF + (size_t)(t - 1) * 2048 + cb) : zc;
;             const v4u nxt = hn ? *(const v4u*)(CF + (size_t)(t + 1) * 2048 + cb) : zc;
;             float o[8];
; #pragma unroll
;             for (int q = 0; q < 4; ++q) {
;                 const unsigned wc_ = cur[q], wp = prv[q], wn = nxt[q];
;                 const int c = cb + 2 * q;
;                 o[2 * q] = cw[c] * bf_lo(wp) + cw[1920 + c] * bf_lo(wc_) + cw[3840 + c] * bf_lo(wn);
;                 o[2 * q + 1] = cw[c + 1] * bf_hi(wp) + cw[1920 + c + 1] * bf_hi(wc_) + cw[3840 + c + 1] * bf_hi(wn);
;             }
;             if (j < 3) {
;                 v4u w; w.x = pkh2(o[0], o[1]); w.y = pkh2(o[2], o[3]); w.z = pkh2(o[4], o[5]); w.w = pkh2(o[6], o[7]);
;                 *(v4u*)(RK + (size_t)t * 2048 + cb) = w;
.LBB0_461:
	s_nop 0
	s_nop 0
	s_nop 0
	s_nop 0
	s_waitcnt vmcnt(0)
	s_nop 1
	v_mov_b32_e32 v44, v72
	v_mov_b32_e32 v45, v73
	v_mov_b32_e32 v46, v74
	v_mov_b32_e32 v47, v75
	s_nop 1
	v_mov_b32_e32 v48, v76
	v_mov_b32_e32 v49, v77
	v_mov_b32_e32 v50, v78
	v_mov_b32_e32 v51, v79
	s_nop 1
	v_mov_b32_e32 v52, v80
	v_mov_b32_e32 v53, v81
	v_mov_b32_e32 v54, v82
	v_mov_b32_e32 v55, v83
	s_nop 1
	v_mov_b32_e32 v56, v84
	v_mov_b32_e32 v57, v85
	v_mov_b32_e32 v58, v86
	v_mov_b32_e32 v59, v87
	v_lshlrev_b32_e32 v60, 16, v4
	v_and_b32_e32 v61, 0xffff0000, v4
	v_lshlrev_b32_e32 v0, 16, v8
	v_and_b32_e32 v1, 0xffff0000, v8
	v_lshlrev_b32_e32 v8, 16, v5
	v_mov_b32_e32 v3, 0
	v_pk_mul_f32 v[56:57], v[56:57], v[60:61]
	s_nop 0
	s_nop 0
	v_pk_fma_f32 v[0:1], v[48:49], v[0:1], v[56:57]
	v_lshlrev_b32_e32 v48, 16, v12
	v_and_b32_e32 v49, 0xffff0000, v12
	s_nop 0
	s_nop 1
	v_mov_b32_e32 v60, v88
	v_mov_b32_e32 v61, v89
	v_mov_b32_e32 v62, v90
	v_mov_b32_e32 v63, v91
	s_nop 1
	v_mov_b32_e32 v64, v92
	v_mov_b32_e32 v65, v93
	v_mov_b32_e32 v66, v94
	v_mov_b32_e32 v67, v95
	v_pk_fma_f32 v[0:1], v[64:65], v[48:49], v[0:1]
	s_nop 0
	v_cvt_pk_f16_f32 v4, v0, v1
	v_lshlrev_b32_e32 v0, 16, v9
	v_and_b32_e32 v1, 0xffff0000, v9
	v_and_b32_e32 v9, 0xffff0000, v5
	v_pk_mul_f32 v[8:9], v[58:59], v[8:9]
	s_nop 0
	v_pk_fma_f32 v[0:1], v[50:51], v[0:1], v[8:9]
	v_lshlrev_b32_e32 v8, 16, v13
	v_and_b32_e32 v9, 0xffff0000, v13
	v_pk_fma_f32 v[0:1], v[66:67], v[8:9], v[0:1]
	v_lshlrev_b32_e32 v8, 16, v6
	v_and_b32_e32 v9, 0xffff0000, v6
	v_cvt_pk_f16_f32 v5, v0, v1
	v_lshlrev_b32_e32 v0, 16, v10
	v_and_b32_e32 v1, 0xffff0000, v10
	v_pk_mul_f32 v[8:9], v[52:53], v[8:9]
	s_nop 0
	v_pk_fma_f32 v[0:1], v[44:45], v[0:1], v[8:9]
	v_lshlrev_b32_e32 v8, 16, v14
	v_and_b32_e32 v9, 0xffff0000, v14
	v_pk_fma_f32 v[0:1], v[60:61], v[8:9], v[0:1]
	v_lshlrev_b32_e32 v8, 16, v7
	v_and_b32_e32 v9, 0xffff0000, v7
	v_cvt_pk_f16_f32 v6, v0, v1
	v_lshlrev_b32_e32 v0, 16, v11
	v_and_b32_e32 v1, 0xffff0000, v11
	v_pk_mul_f32 v[8:9], v[54:55], v[8:9]
	s_nop 0
	v_pk_fma_f32 v[0:1], v[46:47], v[0:1], v[8:9]
	v_lshlrev_b32_e32 v8, 16, v15
	v_and_b32_e32 v9, 0xffff0000, v15
	v_pk_fma_f32 v[0:1], v[62:63], v[8:9], v[0:1]
	s_nop 0
	v_cvt_pk_f16_f32 v7, v0, v1
	v_add_co_u32_e32 v0, vcc, 0x2b600000, v42
	s_nop 1
	v_addc_co_u32_e32 v1, vcc, 0, v43, vcc
	global_store_dwordx4 v[0:1], v[4:7], off
	v_add_co_u32_e32 v0, vcc, 0x21600000, v42
	s_nop 0
	v_mov_b32_e32 v4, 0
	v_addc_co_u32_e32 v1, vcc, 0, v43, vcc
	global_load_dwordx4 v[6:9], v[0:1], off offset:1024
	v_cndmask_b32_e64 v0, 0, 1, s[12:13]
	v_cmp_ne_u32_e64 s[10:11], 1, v0
	s_andn2_b64 vcc, exec, s[12:13]
	v_mov_b32_e32 v5, 0
	s_cbranch_vccnz .LBB0_463
	global_load_dwordx4 v[2:5], v17, s[28:29] offset:1024

; __device__ __forceinline__ float shfl_xor_(float v, int m) { return __builtin_bit_cast(float, __builtin_amdgcn_ds_bpermute((lane_id() ^ m) << 2, __builtin_bit_cast(int, v))); }
; __device__ __forceinline__ void phase_rwkv_pre(const Frame& F, const Args& a, int l) {
;     ...
;             const v4u cur = *(const v4u*)(CF + (size_t)t * 2048 + cb);
;             const v4u prv = hp ? *(const v4u*)(CF + (size_t)(t - 1) * 2048 + cb) : zc;
;             const v4u nxt = hn ? *(const v4u*)(CF + (size_t)(t + 1) * 2048 + cb) : zc;
;             float o[8];
; #pragma unroll
;             for (int q = 0; q < 4; ++q) {
;                 const unsigned wc_ = cur[q], wp = prv[q], wn = nxt[q];
;                 const int c = cb + 2 * q;
;                 o[2 * q] = cw[c] * bf_lo(wp) + cw[1920 + c] * bf_lo(wc_) + cw[3840 + c] * bf_lo(wn);
;                 o[2 * q + 1] = cw[c + 1] * bf_hi(wp) + cw[1920 + c + 1] * bf_hi(wc_) + cw[3840 + c + 1] * bf_hi(wn);
;             }
;             if (j < 3) {
;                 v4u w; w.x = pkh2(o[0], o[1]); w.y = pkh2(o[2], o[3]); w.z = pkh2(o[4], o[5]); w.w = pkh2(o[6], o[7]);
;                 *(v4u*)(RK + (size_t)t * 2048 + cb) = w;
;                 if (j == 1) {
;                     float kv[8]; float ss = 0.f;
; #pragma unroll
;                     for (int e = 0; e < 8; ++e) { kv[e] = o[e] * kk_w[8 * lane + e]; ss += kv[e] * kv[e]; }
;                     ss += shfl_xor_(ss, 1); ss += shfl_xor_(ss, 2); ss += shfl_xor_(ss, 4);
;                     const float rn = 1.0f / sqrtf(ss + 1e-12f);
;                     v4u w2; w2.x = pkh2(kv[0] * rn, kv[1] * rn); w2.y = pkh2(kv[2] * rn, kv[3] * rn); w2.z = pkh2(kv[4] * rn, kv[5] * rn); w2.w = pkh2(kv[6] * rn, kv[7] * rn);
;                     *(v4u*)(RK + (size_t)t * 2048 + 1536 + 8 * lane) = w2;
.LBB0_465:
	s_nop 0
	s_nop 0
	s_nop 0
	s_nop 0
	s_waitcnt vmcnt(0)
	s_nop 1
	v_mov_b32_e32 v44, v96
	v_mov_b32_e32 v45, v97
	v_mov_b32_e32 v46, v98
	v_mov_b32_e32 v47, v99
	s_nop 1
	v_mov_b32_e32 v48, v100
	v_mov_b32_e32 v49, v101
	v_mov_b32_e32 v50, v102
	v_mov_b32_e32 v51, v103
	s_nop 1
	v_mov_b32_e32 v52, v104
	v_mov_b32_e32 v53, v105
	v_mov_b32_e32 v54, v106
	v_mov_b32_e32 v55, v107
	s_nop 1
	v_mov_b32_e32 v56, v108
	v_mov_b32_e32 v57, v109
	v_mov_b32_e32 v58, v110
	v_mov_b32_e32 v59, v111
	v_lshlrev_b32_e32 v60, 16, v6
	v_and_b32_e32 v61, 0xffff0000, v6
	v_lshlrev_b32_e32 v14, 16, v2
	v_and_b32_e32 v15, 0xffff0000, v2
	v_lshlrev_b32_e32 v2, 16, v3
	v_and_b32_e32 v3, 0xffff0000, v3
	s_waitcnt vmcnt(0)
	v_pk_mul_f32 v[56:57], v[56:57], v[60:61]
	s_nop 0
	s_nop 0
	v_pk_fma_f32 v[14:15], v[48:49], v[14:15], v[56:57]
	v_lshlrev_b32_e32 v48, 16, v10
	v_and_b32_e32 v49, 0xffff0000, v10
	v_lshlrev_b32_e32 v10, 16, v11
	v_and_b32_e32 v11, 0xffff0000, v11
	s_nop 0
	s_nop 1
	v_mov_b32_e32 v60, v112
	v_mov_b32_e32 v61, v113
	v_mov_b32_e32 v62, v114
	v_mov_b32_e32 v63, v115
	s_nop 1
	v_mov_b32_e32 v64, v116
	v_mov_b32_e32 v65, v117
	v_mov_b32_e32 v66, v118
	v_mov_b32_e32 v67, v119
	v_pk_fma_f32 v[14:15], v[64:65], v[48:49], v[14:15]
	v_lshlrev_b32_e32 v48, 16, v7
	v_and_b32_e32 v49, 0xffff0000, v7
	v_pk_mul_f32 v[48:49], v[58:59], v[48:49]
	v_cvt_pk_f16_f32 v6, v14, v15
	v_pk_fma_f32 v[2:3], v[50:51], v[2:3], v[48:49]
	s_nop 0
	v_pk_fma_f32 v[48:49], v[66:67], v[10:11], v[2:3]
	v_lshlrev_b32_e32 v10, 16, v8
	v_and_b32_e32 v11, 0xffff0000, v8
	v_lshlrev_b32_e32 v2, 16, v4
	v_and_b32_e32 v3, 0xffff0000, v4
	v_pk_mul_f32 v[10:11], v[52:53], v[10:11]
	v_lshlrev_b32_e32 v4, 16, v9
	v_pk_fma_f32 v[2:3], v[44:45], v[2:3], v[10:11]
	v_lshlrev_b32_e32 v10, 16, v12
	v_and_b32_e32 v11, 0xffff0000, v12
	v_pk_fma_f32 v[44:45], v[60:61], v[10:11], v[2:3]
	v_lshlrev_b32_e32 v2, 16, v5
	v_and_b32_e32 v3, 0xffff0000, v5
	v_and_b32_e32 v5, 0xffff0000, v9
	v_pk_mul_f32 v[4:5], v[54:55], v[4:5]
	v_cvt_pk_f16_f32 v7, v48, v49
	v_pk_fma_f32 v[2:3], v[46:47], v[2:3], v[4:5]
	v_lshlrev_b32_e32 v4, 16, v13
	v_and_b32_e32 v5, 0xffff0000, v13
	v_pk_fma_f32 v[4:5], v[62:63], v[4:5], v[2:3]
	v_add_co_u32_e32 v2, vcc, s68, v42
	v_cvt_pk_f16_f32 v8, v44, v45
	v_cvt_pk_f16_f32 v9, v4, v5
	v_addc_co_u32_e32 v3, vcc, 0, v43, vcc
	global_store_dwordx4 v[2:3], v[6:9], off offset:1024
	s_nop 0
	s_nop 0
	s_nop 0
	s_nop 0
	s_nop 1
	v_mov_b32_e32 v6, v120
	v_mov_b32_e32 v7, v121
	v_mov_b32_e32 v8, v122
	v_mov_b32_e32 v9, v123
	s_nop 1
	v_mov_b32_e32 v10, v124
	v_mov_b32_e32 v11, v125
	v_mov_b32_e32 v12, v126
	v_mov_b32_e32 v13, v127
	v_pk_mul_f32 v[4:5], v[4:5], v[8:9]
	s_nop 0
	v_pk_mul_f32 v[10:11], v[14:15], v[10:11]
	v_pk_mul_f32 v[8:9], v[48:49], v[12:13]
	v_pk_mul_f32 v[14:15], v[10:11], v[10:11]
	v_pk_mul_f32 v[12:13], v[8:9], v[8:9]
	v_add_f32_e32 v1, v14, v15
	v_pk_mul_f32 v[6:7], v[44:45], v[6:7]
	v_add_f32_e32 v1, v1, v12
	v_pk_mul_f32 v[44:45], v[6:7], v[6:7]
	v_add_f32_e32 v1, v1, v13
	v_add_f32_e32 v1, v1, v44
	v_pk_mul_f32 v[46:47], v[4:5], v[4:5]
	v_add_f32_e32 v1, v1, v45
	v_mbcnt_lo_u32_b32 v12, -1, 0
	v_mbcnt_hi_u32_b32 v12, -1, v12
	v_add_f32_e32 v1, v1, v46
	v_lshlrev_b32_e32 v12, 2, v12
	v_add_f32_e32 v1, v1, v47
	v_xor_b32_e32 v12, 4, v12
	ds_bpermute_b32 v12, v12, v1
	s_waitcnt lgkmcnt(0)
	v_add_f32_e32 v1, v1, v12
	v_mbcnt_lo_u32_b32 v12, -1, 0
	v_mbcnt_hi_u32_b32 v12, -1, v12
	s_nop 0
	v_lshlrev_b32_e32 v12, 2, v12
	v_xor_b32_e32 v12, 8, v12
	ds_bpermute_b32 v12, v12, v1
	s_waitcnt lgkmcnt(0)
	v_add_f32_e32 v1, v1, v12
	v_mbcnt_lo_u32_b32 v12, -1, 0
	v_mbcnt_hi_u32_b32 v12, -1, v12
	s_nop 0
	v_lshlrev_b32_e32 v12, 2, v12
	v_xor_b32_e32 v12, 16, v12
	ds_bpermute_b32 v12, v12, v1
	s_waitcnt lgkmcnt(0)
	v_add_f32_e32 v1, v1, v12
	v_add_f32_e32 v1, 0x2b8cbccc, v1
	v_cmp_gt_f32_e32 vcc, s86, v1
	v_mul_f32_e32 v12, 0x4f800000, v1
	s_nop 0
	v_cndmask_b32_e32 v1, v1, v12, vcc
	v_sqrt_f32_e32 v12, v1
	s_nop 0
	v_add_u32_e32 v13, -1, v12
	v_fma_f32 v14, -v13, v12, v1
	v_cmp_ge_f32_e64 s[14:15], 0, v14
	v_add_u32_e32 v14, 1, v12
	s_nop 0
	v_cndmask_b32_e64 v13, v12, v13, s[14:15]
	v_fma_f32 v12, -v14, v12, v1
	v_cmp_lt_f32_e64 s[14:15], 0, v12
	s_nop 1
	v_cndmask_b32_e64 v12, v13, v14, s[14:15]
	v_mul_f32_e32 v13, 0x37800000, v12
	v_cndmask_b32_e32 v12, v12, v13, vcc
	v_cmp_class_f32_e32 vcc, v1, v204
	s_nop 1
	v_cndmask_b32_e32 v1, v12, v1, vcc
	v_div_scale_f32 v12, s[14:15], v1, v1, 1.0
	v_rcp_f32_e32 v13, v12
	s_nop 0
	v_fma_f32 v14, -v12, v13, 1.0
	v_fmac_f32_e32 v13, v14, v13
	v_div_scale_f32 v14, vcc, 1.0, v1, 1.0
	v_mul_f32_e32 v15, v14, v13
	v_fma_f32 v44, -v12, v15, v14
	v_fmac_f32_e32 v15, v44, v13
	v_fma_f32 v12, -v12, v15, v14
	v_div_fmas_f32 v12, v12, v13, v15
	v_div_fixup_f32 v14, v12, v1, 1.0
	v_pk_mul_f32 v[10:11], v[10:11], v[14:15] op_sel_hi:[1,0]
	v_pk_mul_f32 v[8:9], v[8:9], v[14:15] op_sel_hi:[1,0]
	v_pk_mul_f32 v[6:7], v[6:7], v[14:15] op_sel_hi:[1,0]
	v_pk_mul_f32 v[4:5], v[4:5], v[14:15] op_sel_hi:[1,0]
	v_cvt_pk_f16_f32 v10, v10, v11
	v_cvt_pk_f16_f32 v11, v8, v9
	v_cvt_pk_f16_f32 v12, v6, v7
	v_cvt_pk_f16_f32 v13, v4, v5
	global_store_dwordx4 v[2:3], v[10:13], off offset:3072
	v_add_co_u32_e32 v2, vcc, 0x21600000, v42
	v_mov_b32_e32 v1, 0
	s_nop 0
	v_addc_co_u32_e32 v3, vcc, 0, v43, vcc
	global_load_dwordx4 v[4:7], v[2:3], off offset:2048
	s_and_b64 vcc, exec, s[10:11]
	v_mov_b32_e32 v2, 0
	v_mov_b32_e32 v3, 0
	s_cbranch_vccnz .LBB0_467
	global_load_dwordx4 v[0:3], v17, s[28:29] offset:2048

; __device__ __forceinline__ void phase_rwkv_pre(const Frame& F, const Args& a, int l) {
;     ...
;             const v4u cur = *(const v4u*)(CF + (size_t)t * 2048 + cb);
;             const v4u prv = hp ? *(const v4u*)(CF + (size_t)(t - 1) * 2048 + cb) : zc;
;             const v4u nxt = hn ? *(const v4u*)(CF + (size_t)(t + 1) * 2048 + cb) : zc;
;             float o[8];
; #pragma unroll
;             for (int q = 0; q < 4; ++q) {
;                 const unsigned wc_ = cur[q], wp = prv[q], wn = nxt[q];
;                 const int c = cb + 2 * q;
;                 o[2 * q] = cw[c] * bf_lo(wp) + cw[1920 + c] * bf_lo(wc_) + cw[3840 + c] * bf_lo(wn);
;                 o[2 * q + 1] = cw[c + 1] * bf_hi(wp) + cw[1920 + c + 1] * bf_hi(wc_) + cw[3840 + c + 1] * bf_hi(wn);
;             }
;             if (j < 3) {
;                 v4u w; w.x = pkh2(o[0], o[1]); w.y = pkh2(o[2], o[3]); w.z = pkh2(o[4], o[5]); w.w = pkh2(o[6], o[7]);
;                 *(v4u*)(RK + (size_t)t * 2048 + cb) = w;
.LBB0_469:
	s_nop 0
	s_nop 0
	s_nop 0
	s_nop 0
	s_waitcnt vmcnt(0)
	s_nop 1
	v_mov_b32_e32 v12, v132
	v_mov_b32_e32 v13, v133
	v_mov_b32_e32 v14, v134
	v_mov_b32_e32 v15, v135
	s_nop 1
	v_mov_b32_e32 v44, v136
	v_mov_b32_e32 v45, v137
	v_mov_b32_e32 v46, v138
	v_mov_b32_e32 v47, v139
	s_nop 1
	v_mov_b32_e32 v48, v140
	v_mov_b32_e32 v49, v141
	v_mov_b32_e32 v50, v142
	v_mov_b32_e32 v51, v143
	s_nop 1
	v_mov_b32_e32 v52, v144
	v_mov_b32_e32 v53, v145
	v_mov_b32_e32 v54, v146
	v_mov_b32_e32 v55, v147
	v_lshlrev_b32_e32 v58, 16, v4
	v_and_b32_e32 v59, 0xffff0000, v4
	v_lshlrev_b32_e32 v56, 16, v0
	v_and_b32_e32 v57, 0xffff0000, v0
	v_lshlrev_b32_e32 v4, 16, v5
	v_and_b32_e32 v5, 0xffff0000, v5
	s_waitcnt vmcnt(0)
	v_pk_mul_f32 v[52:53], v[52:53], v[58:59]
	s_nop 0
	v_pk_fma_f32 v[44:45], v[44:45], v[56:57], v[52:53]
	s_nop 0
	s_nop 0
	v_lshlrev_b32_e32 v52, 16, v8
	v_and_b32_e32 v53, 0xffff0000, v8
	v_pk_mul_f32 v[4:5], v[54:55], v[4:5]
	v_lshlrev_b32_e32 v8, 16, v9
	v_and_b32_e32 v9, 0xffff0000, v9
	s_nop 0
	s_nop 1
	v_mov_b32_e32 v56, v148
	v_mov_b32_e32 v57, v149
	v_mov_b32_e32 v58, v150
	v_mov_b32_e32 v59, v151
	s_nop 1
	v_mov_b32_e32 v60, v152
	v_mov_b32_e32 v61, v153
	v_mov_b32_e32 v62, v154
	v_mov_b32_e32 v63, v155
	v_pk_fma_f32 v[44:45], v[60:61], v[52:53], v[44:45]
	s_nop 0
	v_cvt_pk_f16_f32 v0, v44, v45
	v_lshlrev_b32_e32 v44, 16, v1
	v_and_b32_e32 v45, 0xffff0000, v1
	v_pk_fma_f32 v[4:5], v[46:47], v[44:45], v[4:5]
	s_nop 0
	v_pk_fma_f32 v[4:5], v[62:63], v[8:9], v[4:5]
	v_lshlrev_b32_e32 v8, 16, v6
	v_and_b32_e32 v9, 0xffff0000, v6
	v_cvt_pk_f16_f32 v1, v4, v5
	v_lshlrev_b32_e32 v4, 16, v2
	v_and_b32_e32 v5, 0xffff0000, v2
	v_pk_mul_f32 v[8:9], v[48:49], v[8:9]
	v_lshlrev_b32_e32 v6, 16, v7
	v_pk_fma_f32 v[4:5], v[12:13], v[4:5], v[8:9]
	v_lshlrev_b32_e32 v8, 16, v10
	v_and_b32_e32 v9, 0xffff0000, v10
	v_pk_fma_f32 v[4:5], v[56:57], v[8:9], v[4:5]
	v_and_b32_e32 v7, 0xffff0000, v7
	v_cvt_pk_f16_f32 v2, v4, v5
	v_lshlrev_b32_e32 v4, 16, v3
	v_and_b32_e32 v5, 0xffff0000, v3
	v_pk_mul_f32 v[6:7], v[50:51], v[6:7]
	s_nop 0
	v_pk_fma_f32 v[4:5], v[14:15], v[4:5], v[6:7]
	v_lshlrev_b32_e32 v6, 16, v11
	v_and_b32_e32 v7, 0xffff0000, v11
	v_pk_fma_f32 v[4:5], v[58:59], v[6:7], v[4:5]
	s_nop 0
	v_cvt_pk_f16_f32 v3, v4, v5
	v_add_co_u32_e32 v4, vcc, 0x2b600000, v42
	s_nop 1
	v_addc_co_u32_e32 v5, vcc, 0, v43, vcc
	global_store_dwordx4 v[4:5], v[0:3], off offset:2048
	s_and_saveexec_b64 s[14:15], s[4:5]
	s_cbranch_execz .LBB0_455
	v_add_co_u32_e32 v0, vcc, 0x21600000, v42
	v_mov_b32_e32 v8, 0
	s_nop 0
	v_addc_co_u32_e32 v1, vcc, 0, v43, vcc
	global_load_dwordx4 v[4:7], v[0:1], off offset:3072
	v_mov_b32_e32 v0, 0
	s_and_b64 vcc, exec, s[10:11]
	v_mov_b32_e32 v9, 0
	v_mov_b32_e32 v10, 0
	v_mov_b32_e32 v11, 0
	s_cbranch_vccnz .LBB0_472
	global_load_dwordx4 v[8:11], v17, s[28:29] offset:3072

; __device__ __forceinline__ float fexp(float x) { return __builtin_amdgcn_exp2f(x * 1.44269504089f); }
; __device__ __forceinline__ float fsigmoid(float x) { return __builtin_amdgcn_rcpf(1.0f + fexp(-x)); }
; __device__ __forceinline__ void phase_rwkv_pre(const Frame& F, const Args& a, int l) {
;     ...
;                 }
;             } else {
;                 if (lane < 16) {
; #pragma unroll
;                     for (int e = 0; e < 8; ++e) { const float ex = fexp(2.0f * o[e]); o[e] = 1.0f - 2.0f / (ex + 1.0f); }
;                 } else if (lane >= 32) {
; #pragma unroll
;                     for (int e = 0; e < 8; ++e) o[e] = fsigmoid(o[e]);
;                 }
.LBB0_474:
	s_nop 0
	s_nop 0
	s_nop 0
	s_nop 0
	s_waitcnt vmcnt(0)
	s_nop 1
	v_mov_b32_e32 v42, v156
	v_mov_b32_e32 v43, v157
	v_mov_b32_e32 v44, v158
	v_mov_b32_e32 v45, v159
	s_nop 1
	v_mov_b32_e32 v12, v160
	v_mov_b32_e32 v13, v161
	v_mov_b32_e32 v14, v162
	v_mov_b32_e32 v15, v163
	s_nop 1
	v_mov_b32_e32 v46, v164
	v_mov_b32_e32 v47, v165
	v_mov_b32_e32 v48, v166
	v_mov_b32_e32 v49, v167
	s_nop 1
	v_mov_b32_e32 v50, v168
	v_mov_b32_e32 v51, v169
	v_mov_b32_e32 v52, v170
	v_mov_b32_e32 v53, v171
	v_lshlrev_b32_e32 v56, 16, v4
	v_and_b32_e32 v57, 0xffff0000, v4
	v_lshlrev_b32_e32 v54, 16, v8
	v_and_b32_e32 v55, 0xffff0000, v8
	v_lshlrev_b32_e32 v4, 16, v5
	v_and_b32_e32 v5, 0xffff0000, v5
	v_lshlrev_b32_e32 v8, 16, v9
	v_and_b32_e32 v9, 0xffff0000, v9
	s_waitcnt vmcnt(0)
	v_pk_mul_f32 v[50:51], v[50:51], v[56:57]
	s_nop 0
	v_pk_fma_f32 v[12:13], v[12:13], v[54:55], v[50:51]
	s_nop 0
	s_nop 0
	v_pk_mul_f32 v[4:5], v[52:53], v[4:5]
	v_lshlrev_b32_e32 v50, 16, v0
	v_and_b32_e32 v51, 0xffff0000, v0
	v_pk_fma_f32 v[4:5], v[14:15], v[8:9], v[4:5]
	v_lshlrev_b32_e32 v0, 16, v1
	v_and_b32_e32 v1, 0xffff0000, v1
	v_lshlrev_b32_e32 v8, 16, v6
	v_and_b32_e32 v9, 0xffff0000, v6
	v_pk_mul_f32 v[8:9], v[46:47], v[8:9]
	v_lshlrev_b32_e32 v6, 16, v7
	v_and_b32_e32 v7, 0xffff0000, v7
	v_pk_mul_f32 v[6:7], v[48:49], v[6:7]
	s_nop 0
	s_nop 1
	v_mov_b32_e32 v54, v172
	v_mov_b32_e32 v55, v173
	v_mov_b32_e32 v56, v174
	v_mov_b32_e32 v57, v175
	s_nop 1
	v_mov_b32_e32 v58, v176
	v_mov_b32_e32 v59, v177
	v_mov_b32_e32 v60, v178
	v_mov_b32_e32 v61, v179
	v_pk_fma_f32 v[0:1], v[60:61], v[0:1], v[4:5]
	v_lshlrev_b32_e32 v4, 16, v10
	v_and_b32_e32 v5, 0xffff0000, v10
	v_pk_fma_f32 v[4:5], v[42:43], v[4:5], v[8:9]
	v_lshlrev_b32_e32 v8, 16, v2
	v_and_b32_e32 v9, 0xffff0000, v2
	v_pk_fma_f32 v[4:5], v[54:55], v[8:9], v[4:5]
	v_lshlrev_b32_e32 v8, 16, v11
	v_and_b32_e32 v9, 0xffff0000, v11
	v_pk_fma_f32 v[6:7], v[44:45], v[8:9], v[6:7]
	v_lshlrev_b32_e32 v2, 16, v3
	v_and_b32_e32 v3, 0xffff0000, v3
	v_pk_fma_f32 v[12:13], v[58:59], v[50:51], v[12:13]
	v_pk_fma_f32 v[6:7], v[56:57], v[2:3], v[6:7]
	s_and_saveexec_b64 s[10:11], s[6:7]
	s_xor_b64 s[10:11], exec, s[10:11]
	s_cbranch_execz .LBB0_478
	s_and_saveexec_b64 s[12:13], s[8:9]
	s_cbranch_execz .LBB0_477
	v_mul_f32_e32 v2, 0xbfb8aa3b, v12
	v_exp_f32_e32 v2, v2
	v_mul_f32_e32 v3, 0xbfb8aa3b, v13
	v_exp_f32_e32 v3, v3
	v_mul_f32_e32 v0, 0xbfb8aa3b, v0
	v_add_f32_e32 v2, 1.0, v2
	v_rcp_f32_e32 v12, v2
	v_add_f32_e32 v3, 1.0, v3
	v_mul_f32_e32 v2, 0xbfb8aa3b, v4
	v_rcp_f32_e32 v13, v3
	v_exp_f32_e32 v2, v2
	v_mul_f32_e32 v3, 0xbfb8aa3b, v5
	v_exp_f32_e32 v3, v3
	v_mul_f32_e32 v1, 0xbfb8aa3b, v1
	v_add_f32_e32 v2, 1.0, v2
	v_rcp_f32_e32 v4, v2
	v_add_f32_e32 v2, 1.0, v3
	v_mul_f32_e32 v3, 0xbfb8aa3b, v6
	v_exp_f32_e32 v3, v3
	v_mul_f32_e32 v5, 0xbfb8aa3b, v7
	v_exp_f32_e32 v0, v0
	v_exp_f32_e32 v1, v1
	v_exp_f32_e32 v7, v5
	v_rcp_f32_e32 v5, v2
	v_add_f32_e32 v2, 1.0, v3
	v_add_f32_e32 v0, 1.0, v0
	v_add_f32_e32 v1, 1.0, v1
	v_rcp_f32_e32 v6, v2
	v_add_f32_e32 v2, 1.0, v7
	v_rcp_f32_e32 v0, v0
	v_rcp_f32_e32 v1, v1
	v_rcp_f32_e32 v7, v2

; __device__ __forceinline__ unsigned cvt_pk_bf16(float lo, float hi) { f32x2 v = {lo, hi}; bf16v2_t r = __builtin_convertvector(v, bf16v2_t); return __builtin_bit_cast(unsigned, r); }
; __device__ __forceinline__ float fexp(float x) { return __builtin_amdgcn_exp2f(x * 1.44269504089f); }
; __device__ __forceinline__ float fsigmoid(float x) { return __builtin_amdgcn_rcpf(1.0f + fexp(-x)); }
;     template <int KIND>
;     __device__ __forceinline__ void run(const f32x4 (&acc)[2][2][4][2], const UnitG& u, int wr, int wc, int fr, int fq) const {
;     ...
;                     } else if (KIND == 4) {
;                         const int c = u.x1 * 256 + bj * 128 + col0;
; #pragma unroll
;                         for (int e = 0; e < 8; ++e) { const float xx = -(v[e] + b0[c + e]); const float sp = (xx > 15.f) ? xx : __builtin_amdgcn_logf(1.0f + fexp(xx)) * 0.69314718056f; v[e] = fexp(-sp - 0.5f); }
;                     } else if (KIND == 5) {
;                         const int c = u.x1 * 256 + bj * 128 + col0 - 1024;
; #pragma unroll
;                         for (int e = 0; e < 8; ++e) v[e] = fsigmoid(v[e] + b1[c + e]);
;                     }
;                     if (KIND == 4 || KIND == 5) { w.x = pkh2(v[0], v[1]); w.y = pkh2(v[2], v[3]); w.z = pkh2(v[4], v[5]); w.w = pkh2(v[6], v[7]); }
;                     else { w.x = cvt_pk_bf16(v[0], v[1]); w.y = cvt_pk_bf16(v[2], v[3]); w.z = cvt_pk_bf16(v[4], v[5]); w.w = cvt_pk_bf16(v[6], v[7]); }
;                     *(v4u*)dst = w; }
.LBB0_543:
	v_mbcnt_lo_u32_b32 v129, -1, 0
	v_mbcnt_hi_u32_b32 v129, -1, v129
	s_mov_b64 s[24:25], -1
	v_and_b32_e32 v128, 15, v129
	v_ashrrev_i32_e32 v129, 4, v129
	s_mov_b64 s[20:21], 0
	v_lshl_add_u32 v138, v129, 3, s58
	v_ashrrev_i32_e32 v139, 31, v138
	v_add_u32_e32 v146, s56, v128
	v_lshl_add_u64 v[136:137], v[138:139], 1, v[132:133]
	s_cmp_lt_i32 s48, 5
	s_mov_b64 s[22:23], 0
	s_cbranch_scc1 .LBB0_547
	s_cmp_eq_u32 s48, 5
	s_mov_b64 s[22:23], -1
	s_cbranch_scc0 .LBB0_546
	v_mad_i64_i32 v[140:141], s[22:23], v146, s50, 0
	s_lshl_b32 s22, s34, 8
	s_add_i32 s23, s22, 0xfffffc00
	v_add_u32_e32 v128, s23, v138
	v_ashrrev_i32_e32 v129, 31, v128
	v_lshl_add_u64 v[142:143], v[128:129], 2, s[12:13]
	global_load_dwordx4 v[160:163], v[142:143], off offset:16
	global_load_dwordx4 v[164:167], v[142:143], off
	s_addk_i32 s22, 0xfc80
	s_waitcnt vmcnt(0)
	s_nop 1
	v_mov_b32_e32 v128, v160
	v_mov_b32_e32 v129, v161
	v_mov_b32_e32 v130, v162
	v_mov_b32_e32 v131, v163
	s_nop 1
	v_mov_b32_e32 v148, v164
	v_mov_b32_e32 v149, v165
	v_mov_b32_e32 v150, v166
	v_mov_b32_e32 v151, v167
	v_add_f32_e32 v128, v120, v128
	v_mul_f32_e32 v128, 0xbfb8aa3b, v128
	v_exp_f32_e32 v128, v128
	v_add_f32_e32 v139, v125, v149
	v_add_f32_e32 v144, v126, v150
	v_mul_f32_e32 v144, 0xbfb8aa3b, v144
	v_add_f32_e32 v128, 1.0, v128
	v_rcp_f32_e32 v149, v128
	v_add_f32_e32 v128, v121, v129
	v_mul_f32_e32 v128, 0xbfb8aa3b, v128
	v_exp_f32_e32 v128, v128
	v_exp_f32_e32 v144, v144
	v_add_f32_e32 v135, v124, v148
	v_mul_f32_e32 v135, 0xbfb8aa3b, v135
	v_add_f32_e32 v128, 1.0, v128
	v_rcp_f32_e32 v150, v128
	v_add_f32_e32 v128, v122, v130
	v_mul_f32_e32 v128, 0xbfb8aa3b, v128
	v_exp_f32_e32 v128, v128
	v_add_f32_e32 v144, 1.0, v144
	v_rcp_f32_e32 v147, v144
	v_add_f32_e32 v144, v127, v151
	v_add_f32_e32 v128, 1.0, v128
	v_rcp_f32_e32 v151, v128
	v_add_f32_e32 v128, v123, v131
	v_mul_f32_e32 v139, 0xbfb8aa3b, v139
	v_mul_f32_e32 v144, 0xbfb8aa3b, v144
	v_mul_f32_e32 v128, 0xbfb8aa3b, v128
	v_exp_f32_e32 v135, v135
	v_exp_f32_e32 v139, v139
	v_exp_f32_e32 v144, v144
	v_exp_f32_e32 v128, v128
	v_add_f32_e32 v135, 1.0, v135
	v_add_f32_e32 v139, 1.0, v139
	v_add_f32_e32 v144, 1.0, v144
	v_add_f32_e32 v128, 1.0, v128
	v_rcp_f32_e32 v135, v135
	v_rcp_f32_e32 v139, v139
	v_rcp_f32_e32 v148, v144
	v_rcp_f32_e32 v131, v128
	v_lshl_add_u64 v[144:145], v[140:141], 1, v[136:137]
	v_cvt_pk_f16_f32 v128, v135, v139
	v_cvt_pk_f16_f32 v129, v147, v148
	v_cvt_pk_f16_f32 v130, v149, v150
	v_cvt_pk_f16_f32 v131, v151, v131
	global_store_dwordx4 v[144:145], v[128:131], off
	s_nop 1
	v_add_u32_e32 v128, s22, v138
	v_ashrrev_i32_e32 v129, 31, v128
	v_lshl_add_u64 v[140:141], v[128:129], 2, s[12:13]
	global_load_dwordx4 v[168:171], v[140:141], off offset:16
	global_load_dwordx4 v[172:175], v[140:141], off
	s_waitcnt vmcnt(1)
	s_nop 1
	v_mov_b32_e32 v128, v168
	v_mov_b32_e32 v129, v169
	v_mov_b32_e32 v130, v170
	v_mov_b32_e32 v131, v171
	v_add_f32_e32 v128, v112, v128
	v_mul_f32_e32 v128, 0xbfb8aa3b, v128
	v_exp_f32_e32 v128, v128
	s_waitcnt vmcnt(0)
	s_nop 1
	v_mov_b32_e32 v148, v172
	v_mov_b32_e32 v149, v173
	v_mov_b32_e32 v150, v174
	v_mov_b32_e32 v151, v175
	v_add_f32_e32 v139, v117, v149
	v_add_f32_e32 v147, v118, v150
	v_add_f32_e32 v135, v116, v148
	v_add_f32_e32 v128, 1.0, v128
	v_rcp_f32_e32 v149, v128
	v_add_f32_e32 v128, v113, v129
	v_mul_f32_e32 v128, 0xbfb8aa3b, v128
	v_exp_f32_e32 v128, v128
	v_add_f32_e32 v148, v119, v151
	v_mul_f32_e32 v135, 0xbfb8aa3b, v135
	v_mul_f32_e32 v139, 0xbfb8aa3b, v139
	v_add_f32_e32 v128, 1.0, v128
	v_rcp_f32_e32 v150, v128
	v_add_f32_e32 v128, v114, v130
	v_mul_f32_e32 v128, 0xbfb8aa3b, v128
	v_exp_f32_e32 v128, v128
	v_mul_f32_e32 v147, 0xbfb8aa3b, v147
	v_mul_f32_e32 v148, 0xbfb8aa3b, v148
	v_exp_f32_e32 v135, v135
	v_add_f32_e32 v128, 1.0, v128
	v_rcp_f32_e32 v151, v128
	v_add_f32_e32 v128, v115, v131
	v_mul_f32_e32 v128, 0xbfb8aa3b, v128
	v_exp_f32_e32 v139, v139
	v_exp_f32_e32 v147, v147
	v_exp_f32_e32 v148, v148
	v_exp_f32_e32 v128, v128
	v_add_f32_e32 v135, 1.0, v135
	v_add_f32_e32 v139, 1.0, v139
	v_add_f32_e32 v147, 1.0, v147
	v_add_f32_e32 v148, 1.0, v148
	v_add_f32_e32 v128, 1.0, v128
	v_rcp_f32_e32 v135, v135
	v_rcp_f32_e32 v139, v139
	v_rcp_f32_e32 v147, v147
	v_rcp_f32_e32 v148, v148
	v_rcp_f32_e32 v131, v128
	v_cvt_pk_f16_f32 v128, v135, v139
	v_cvt_pk_f16_f32 v130, v149, v150
	v_cvt_pk_f16_f32 v129, v147, v148
	v_cvt_pk_f16_f32 v131, v151, v131
	global_store_dwordx4 v[144:145], v[128:131], off offset:256
	s_nop 1
	v_add_u32_e32 v128, 16, v146
	v_mad_i64_i32 v[144:145], s[22:23], v128, s50, 0
	s_nop 0
	s_nop 0
	s_nop 0
	s_nop 1
	v_mov_b32_e32 v128, v160
	v_mov_b32_e32 v129, v161
	v_mov_b32_e32 v130, v162
	v_mov_b32_e32 v131, v163
	s_nop 1
	v_mov_b32_e32 v148, v164
	v_mov_b32_e32 v149, v165
	v_mov_b32_e32 v150, v166
	v_mov_b32_e32 v151, v167
	v_add_f32_e32 v128, v104, v128
	v_mul_f32_e32 v128, 0xbfb8aa3b, v128
	v_exp_f32_e32 v128, v128
	s_nop 0
	v_add_f32_e32 v147, v110, v150
	v_add_f32_e32 v135, v108, v148
	v_add_f32_e32 v148, v111, v151
	v_add_f32_e32 v128, 1.0, v128
	v_rcp_f32_e32 v150, v128
	v_add_f32_e32 v128, v105, v129
	v_mul_f32_e32 v128, 0xbfb8aa3b, v128
	v_exp_f32_e32 v128, v128
	v_add_f32_e32 v139, v109, v149
	v_mul_f32_e32 v135, 0xbfb8aa3b, v135
	v_mul_f32_e32 v139, 0xbfb8aa3b, v139
	v_add_f32_e32 v128, 1.0, v128
	v_rcp_f32_e32 v151, v128
	v_add_f32_e32 v128, v106, v130
	v_mul_f32_e32 v128, 0xbfb8aa3b, v128
	v_exp_f32_e32 v128, v128
	v_mul_f32_e32 v147, 0xbfb8aa3b, v147
	v_mul_f32_e32 v148, 0xbfb8aa3b, v148
	v_exp_f32_e32 v135, v135
	v_add_f32_e32 v128, 1.0, v128
	v_rcp_f32_e32 v130, v128
	v_add_f32_e32 v128, v107, v131
; __device__ __forceinline__ unsigned cvt_pk_bf16(float lo, float hi) { f32x2 v = {lo, hi}; bf16v2_t r = __builtin_convertvector(v, bf16v2_t); return __builtin_bit_cast(unsigned, r); }
; __device__ __forceinline__ float fexp(float x) { return __builtin_amdgcn_exp2f(x * 1.44269504089f); }
; __device__ __forceinline__ float fsigmoid(float x) { return __builtin_amdgcn_rcpf(1.0f + fexp(-x)); }
;     template <int KIND>
;     __device__ __forceinline__ void run(const f32x4 (&acc)[2][2][4][2], const UnitG& u, int wr, int wc, int fr, int fq) const {
;     ...
;                     } else if (KIND == 4) {
;                         const int c = u.x1 * 256 + bj * 128 + col0;
; #pragma unroll
;                         for (int e = 0; e < 8; ++e) { const float xx = -(v[e] + b0[c + e]); const float sp = (xx > 15.f) ? xx : __builtin_amdgcn_logf(1.0f + fexp(xx)) * 0.69314718056f; v[e] = fexp(-sp - 0.5f); }
;                     } else if (KIND == 5) {
;                         const int c = u.x1 * 256 + bj * 128 + col0 - 1024;
; #pragma unroll
;                         for (int e = 0; e < 8; ++e) v[e] = fsigmoid(v[e] + b1[c + e]);
;                     }
;                     if (KIND == 4 || KIND == 5) { w.x = pkh2(v[0], v[1]); w.y = pkh2(v[2], v[3]); w.z = pkh2(v[4], v[5]); w.w = pkh2(v[6], v[7]); }
;                     else { w.x = cvt_pk_bf16(v[0], v[1]); w.y = cvt_pk_bf16(v[2], v[3]); w.z = cvt_pk_bf16(v[4], v[5]); w.w = cvt_pk_bf16(v[6], v[7]); }
;                     *(v4u*)dst = w; }
	v_mul_f32_e32 v128, 0xbfb8aa3b, v128
	v_exp_f32_e32 v139, v139
	v_exp_f32_e32 v147, v147
	v_exp_f32_e32 v148, v148
	v_exp_f32_e32 v128, v128
	v_add_f32_e32 v135, 1.0, v135
	v_add_f32_e32 v139, 1.0, v139
	v_add_f32_e32 v147, 1.0, v147
	v_add_f32_e32 v148, 1.0, v148
	v_add_f32_e32 v128, 1.0, v128
	v_rcp_f32_e32 v135, v135
	v_rcp_f32_e32 v139, v139
	v_rcp_f32_e32 v147, v147
	v_rcp_f32_e32 v149, v148
	v_rcp_f32_e32 v131, v128
	v_lshl_add_u64 v[128:129], v[144:145], 1, v[136:137]
	v_cvt_pk_f16_f32 v148, v135, v139
	v_cvt_pk_f16_f32 v149, v147, v149
	v_cvt_pk_f16_f32 v150, v150, v151
	v_cvt_pk_f16_f32 v151, v130, v131
	global_store_dwordx4 v[128:129], v[148:151], off
	s_nop 0
	s_nop 0
	s_nop 0
	s_nop 0
	s_nop 1
	v_mov_b32_e32 v148, v168
	v_mov_b32_e32 v149, v169
	v_mov_b32_e32 v150, v170
	v_mov_b32_e32 v151, v171
	s_nop 1
	v_mov_b32_e32 v152, v172
	v_mov_b32_e32 v153, v173
	v_mov_b32_e32 v154, v174
	v_mov_b32_e32 v155, v175
	v_add_f32_e32 v144, v96, v148
	s_nop 0
	v_add_f32_e32 v130, v100, v152
	v_add_f32_e32 v131, v101, v153
	v_add_f32_e32 v135, v102, v154
	v_add_f32_e32 v139, v103, v155
	v_add_f32_e32 v145, v97, v149
	v_add_f32_e32 v147, v98, v150
	v_add_f32_e32 v148, v99, v151
	v_mul_f32_e32 v130, 0xbfb8aa3b, v130
	v_mul_f32_e32 v131, 0xbfb8aa3b, v131
	v_mul_f32_e32 v135, 0xbfb8aa3b, v135
	v_mul_f32_e32 v139, 0xbfb8aa3b, v139
	v_mul_f32_e32 v144, 0xbfb8aa3b, v144
	v_mul_f32_e32 v145, 0xbfb8aa3b, v145
	v_mul_f32_e32 v147, 0xbfb8aa3b, v147
	v_mul_f32_e32 v148, 0xbfb8aa3b, v148
	v_exp_f32_e32 v130, v130
	v_exp_f32_e32 v131, v131
	v_exp_f32_e32 v135, v135
	v_exp_f32_e32 v139, v139
	v_exp_f32_e32 v144, v144
	v_exp_f32_e32 v145, v145
	v_exp_f32_e32 v147, v147
	v_exp_f32_e32 v148, v148
	v_add_f32_e32 v130, 1.0, v130
	v_add_f32_e32 v131, 1.0, v131
	v_add_f32_e32 v135, 1.0, v135
	v_add_f32_e32 v139, 1.0, v139
	v_add_f32_e32 v144, 1.0, v144
	v_add_f32_e32 v145, 1.0, v145
	v_add_f32_e32 v147, 1.0, v147
	v_add_f32_e32 v148, 1.0, v148
	v_rcp_f32_e32 v130, v130
	v_rcp_f32_e32 v131, v131
	v_rcp_f32_e32 v135, v135
	v_rcp_f32_e32 v139, v139
	v_rcp_f32_e32 v144, v144
	v_rcp_f32_e32 v145, v145
	v_rcp_f32_e32 v147, v147
	v_rcp_f32_e32 v151, v148
	v_cvt_pk_f16_f32 v148, v130, v131
	v_cvt_pk_f16_f32 v149, v135, v139
	v_cvt_pk_f16_f32 v150, v144, v145
	v_cvt_pk_f16_f32 v151, v147, v151
	global_store_dwordx4 v[128:129], v[148:151], off offset:256
	v_add_u32_e32 v128, 32, v146
	v_mad_i64_i32 v[144:145], s[22:23], v128, s50, 0
	s_nop 0
	s_nop 0
	s_nop 0
	s_nop 1
	v_mov_b32_e32 v128, v160
	v_mov_b32_e32 v129, v161
	v_mov_b32_e32 v130, v162
	v_mov_b32_e32 v131, v163
	s_nop 1
	v_mov_b32_e32 v148, v164
	v_mov_b32_e32 v149, v165
	v_mov_b32_e32 v150, v166
	v_mov_b32_e32 v151, v167
	v_add_f32_e32 v128, v88, v128
	v_mul_f32_e32 v128, 0xbfb8aa3b, v128
	v_exp_f32_e32 v128, v128
	s_nop 0
	v_add_f32_e32 v147, v94, v150
	v_add_f32_e32 v135, v92, v148
	v_add_f32_e32 v148, v95, v151
	v_add_f32_e32 v128, 1.0, v128
	v_rcp_f32_e32 v150, v128
	v_add_f32_e32 v128, v89, v129
	v_mul_f32_e32 v128, 0xbfb8aa3b, v128
	v_exp_f32_e32 v128, v128
	v_add_f32_e32 v139, v93, v149
	v_mul_f32_e32 v135, 0xbfb8aa3b, v135
	v_mul_f32_e32 v139, 0xbfb8aa3b, v139
	v_add_f32_e32 v128, 1.0, v128
	v_rcp_f32_e32 v151, v128
	v_add_f32_e32 v128, v90, v130
	v_mul_f32_e32 v128, 0xbfb8aa3b, v128
	v_exp_f32_e32 v128, v128
	v_mul_f32_e32 v147, 0xbfb8aa3b, v147
	v_mul_f32_e32 v148, 0xbfb8aa3b, v148
	v_exp_f32_e32 v135, v135
	v_add_f32_e32 v128, 1.0, v128
	v_rcp_f32_e32 v130, v128
	v_add_f32_e32 v128, v91, v131
	v_mul_f32_e32 v128, 0xbfb8aa3b, v128
	v_exp_f32_e32 v139, v139
	v_exp_f32_e32 v147, v147
	v_exp_f32_e32 v148, v148
	v_exp_f32_e32 v128, v128
	v_add_f32_e32 v135, 1.0, v135
	v_add_f32_e32 v139, 1.0, v139
	v_add_f32_e32 v147, 1.0, v147
	v_add_f32_e32 v148, 1.0, v148
	v_add_f32_e32 v128, 1.0, v128
	v_rcp_f32_e32 v135, v135
	v_rcp_f32_e32 v139, v139
	v_rcp_f32_e32 v147, v147
	v_rcp_f32_e32 v149, v148
	v_rcp_f32_e32 v131, v128
	v_lshl_add_u64 v[128:129], v[144:145], 1, v[136:137]
	v_cvt_pk_f16_f32 v148, v135, v139
	v_cvt_pk_f16_f32 v149, v147, v149
	v_cvt_pk_f16_f32 v150, v150, v151
	v_cvt_pk_f16_f32 v151, v130, v131
	global_store_dwordx4 v[128:129], v[148:151], off
	s_nop 0
	s_nop 0
	s_nop 0
	s_nop 0
	s_nop 1
	v_mov_b32_e32 v148, v168
	v_mov_b32_e32 v149, v169
	v_mov_b32_e32 v150, v170
	v_mov_b32_e32 v151, v171
	s_nop 1
	v_mov_b32_e32 v152, v172
	v_mov_b32_e32 v153, v173
	v_mov_b32_e32 v154, v174
	v_mov_b32_e32 v155, v175
	v_add_f32_e32 v144, v80, v148
	s_nop 0
	v_add_f32_e32 v130, v84, v152
	v_add_f32_e32 v131, v85, v153
	v_add_f32_e32 v135, v86, v154
	v_add_f32_e32 v139, v87, v155
	v_add_f32_e32 v145, v81, v149
	v_add_f32_e32 v147, v82, v150
	v_add_f32_e32 v148, v83, v151
	v_mul_f32_e32 v130, 0xbfb8aa3b, v130
	v_mul_f32_e32 v131, 0xbfb8aa3b, v131
	v_mul_f32_e32 v135, 0xbfb8aa3b, v135
	v_mul_f32_e32 v139, 0xbfb8aa3b, v139
	v_mul_f32_e32 v144, 0xbfb8aa3b, v144
	v_mul_f32_e32 v145, 0xbfb8aa3b, v145
	v_mul_f32_e32 v147, 0xbfb8aa3b, v147
	v_mul_f32_e32 v148, 0xbfb8aa3b, v148
	v_exp_f32_e32 v130, v130
	v_exp_f32_e32 v131, v131
	v_exp_f32_e32 v135, v135
	v_exp_f32_e32 v139, v139
	v_exp_f32_e32 v144, v144
	v_exp_f32_e32 v145, v145
	v_exp_f32_e32 v147, v147
	v_exp_f32_e32 v148, v148
	v_add_f32_e32 v130, 1.0, v130
	v_add_f32_e32 v131, 1.0, v131
	v_add_f32_e32 v135, 1.0, v135
	v_add_f32_e32 v139, 1.0, v139
	v_add_f32_e32 v144, 1.0, v144
	v_add_f32_e32 v145, 1.0, v145
	v_add_f32_e32 v147, 1.0, v147
	v_add_f32_e32 v148, 1.0, v148
	v_rcp_f32_e32 v130, v130
	v_rcp_f32_e32 v131, v131
	v_rcp_f32_e32 v135, v135
	v_rcp_f32_e32 v139, v139
	v_rcp_f32_e32 v144, v144
	v_rcp_f32_e32 v145, v145
	v_rcp_f32_e32 v147, v147
	v_rcp_f32_e32 v151, v148
; __device__ __forceinline__ unsigned cvt_pk_bf16(float lo, float hi) { f32x2 v = {lo, hi}; bf16v2_t r = __builtin_convertvector(v, bf16v2_t); return __builtin_bit_cast(unsigned, r); }
; __device__ __forceinline__ float fexp(float x) { return __builtin_amdgcn_exp2f(x * 1.44269504089f); }
; __device__ __forceinline__ float fsigmoid(float x) { return __builtin_amdgcn_rcpf(1.0f + fexp(-x)); }
;     template <int KIND>
;     __device__ __forceinline__ void run(const f32x4 (&acc)[2][2][4][2], const UnitG& u, int wr, int wc, int fr, int fq) const {
;     ...
;                     } else if (KIND == 4) {
;                         const int c = u.x1 * 256 + bj * 128 + col0;
; #pragma unroll
;                         for (int e = 0; e < 8; ++e) { const float xx = -(v[e] + b0[c + e]); const float sp = (xx > 15.f) ? xx : __builtin_amdgcn_logf(1.0f + fexp(xx)) * 0.69314718056f; v[e] = fexp(-sp - 0.5f); }
;                     } else if (KIND == 5) {
;                         const int c = u.x1 * 256 + bj * 128 + col0 - 1024;
; #pragma unroll
;                         for (int e = 0; e < 8; ++e) v[e] = fsigmoid(v[e] + b1[c + e]);
;                     }
;                     if (KIND == 4 || KIND == 5) { w.x = pkh2(v[0], v[1]); w.y = pkh2(v[2], v[3]); w.z = pkh2(v[4], v[5]); w.w = pkh2(v[6], v[7]); }
;                     else { w.x = cvt_pk_bf16(v[0], v[1]); w.y = cvt_pk_bf16(v[2], v[3]); w.z = cvt_pk_bf16(v[4], v[5]); w.w = cvt_pk_bf16(v[6], v[7]); }
;                     *(v4u*)dst = w; }
	v_cvt_pk_f16_f32 v148, v130, v131
	v_cvt_pk_f16_f32 v149, v135, v139
	v_cvt_pk_f16_f32 v150, v144, v145
	v_cvt_pk_f16_f32 v151, v147, v151
	global_store_dwordx4 v[128:129], v[148:151], off offset:256
	v_add_u32_e32 v128, 48, v146
	v_mad_i64_i32 v[144:145], s[22:23], v128, s50, 0
	s_nop 0
	s_nop 0
	s_nop 0
	s_nop 1
	v_mov_b32_e32 v128, v160
	v_mov_b32_e32 v129, v161
	v_mov_b32_e32 v130, v162
	v_mov_b32_e32 v131, v163
	s_nop 1
	v_mov_b32_e32 v148, v164
	v_mov_b32_e32 v149, v165
	v_mov_b32_e32 v150, v166
	v_mov_b32_e32 v151, v167
	v_add_f32_e32 v128, v72, v128
	v_mul_f32_e32 v128, 0xbfb8aa3b, v128
	v_exp_f32_e32 v128, v128
	s_nop 0
	v_add_f32_e32 v147, v78, v150
	v_add_f32_e32 v135, v76, v148
	v_add_f32_e32 v148, v79, v151
	v_add_f32_e32 v128, 1.0, v128
	v_rcp_f32_e32 v150, v128
	v_add_f32_e32 v128, v73, v129
	v_mul_f32_e32 v128, 0xbfb8aa3b, v128
	v_exp_f32_e32 v128, v128
	v_add_f32_e32 v139, v77, v149
	v_mul_f32_e32 v135, 0xbfb8aa3b, v135
	v_mul_f32_e32 v139, 0xbfb8aa3b, v139
	v_add_f32_e32 v128, 1.0, v128
	v_rcp_f32_e32 v151, v128
	v_add_f32_e32 v128, v74, v130
	v_mul_f32_e32 v128, 0xbfb8aa3b, v128
	v_exp_f32_e32 v128, v128
	v_mul_f32_e32 v147, 0xbfb8aa3b, v147
	v_mul_f32_e32 v148, 0xbfb8aa3b, v148
	v_exp_f32_e32 v135, v135
	v_add_f32_e32 v128, 1.0, v128
	v_rcp_f32_e32 v130, v128
	v_add_f32_e32 v128, v75, v131
	v_mul_f32_e32 v128, 0xbfb8aa3b, v128
	v_exp_f32_e32 v139, v139
	v_exp_f32_e32 v147, v147
	v_exp_f32_e32 v148, v148
	v_exp_f32_e32 v128, v128
	v_add_f32_e32 v135, 1.0, v135
	v_add_f32_e32 v139, 1.0, v139
	v_add_f32_e32 v147, 1.0, v147
	v_add_f32_e32 v148, 1.0, v148
	v_add_f32_e32 v128, 1.0, v128
	v_rcp_f32_e32 v135, v135
	v_rcp_f32_e32 v139, v139
	v_rcp_f32_e32 v147, v147
	v_rcp_f32_e32 v149, v148
	v_rcp_f32_e32 v131, v128
	v_lshl_add_u64 v[128:129], v[144:145], 1, v[136:137]
	v_cvt_pk_f16_f32 v148, v135, v139
	v_cvt_pk_f16_f32 v149, v147, v149
	v_cvt_pk_f16_f32 v150, v150, v151
	v_cvt_pk_f16_f32 v151, v130, v131
	global_store_dwordx4 v[128:129], v[148:151], off
	s_nop 0
	s_nop 0
	s_nop 0
	s_nop 0
	s_nop 1
	v_mov_b32_e32 v148, v168
	v_mov_b32_e32 v149, v169
	v_mov_b32_e32 v150, v170
	v_mov_b32_e32 v151, v171
	s_nop 1
	v_mov_b32_e32 v152, v172
	v_mov_b32_e32 v153, v173
	v_mov_b32_e32 v154, v174
	v_mov_b32_e32 v155, v175
	v_add_f32_e32 v144, v64, v148
	s_nop 0
	v_add_f32_e32 v130, v68, v152
	v_add_f32_e32 v131, v69, v153
	v_add_f32_e32 v135, v70, v154
	v_add_f32_e32 v139, v71, v155
	v_add_f32_e32 v145, v65, v149
	v_add_f32_e32 v147, v66, v150
	v_add_f32_e32 v148, v67, v151
	v_mul_f32_e32 v130, 0xbfb8aa3b, v130
	v_mul_f32_e32 v131, 0xbfb8aa3b, v131
	v_mul_f32_e32 v135, 0xbfb8aa3b, v135
	v_mul_f32_e32 v139, 0xbfb8aa3b, v139
	v_mul_f32_e32 v144, 0xbfb8aa3b, v144
	v_mul_f32_e32 v145, 0xbfb8aa3b, v145
	v_mul_f32_e32 v147, 0xbfb8aa3b, v147
	v_mul_f32_e32 v148, 0xbfb8aa3b, v148
	v_exp_f32_e32 v130, v130
	v_exp_f32_e32 v131, v131
	v_exp_f32_e32 v135, v135
	v_exp_f32_e32 v139, v139
	v_exp_f32_e32 v144, v144
	v_exp_f32_e32 v145, v145
	v_exp_f32_e32 v147, v147
	v_exp_f32_e32 v148, v148
	v_add_f32_e32 v130, 1.0, v130
	v_add_f32_e32 v131, 1.0, v131
	v_add_f32_e32 v135, 1.0, v135
	v_add_f32_e32 v139, 1.0, v139
	v_add_f32_e32 v144, 1.0, v144
	v_add_f32_e32 v145, 1.0, v145
	v_add_f32_e32 v147, 1.0, v147
	v_add_f32_e32 v148, 1.0, v148
	v_rcp_f32_e32 v130, v130
	v_rcp_f32_e32 v131, v131
	v_rcp_f32_e32 v135, v135
	v_rcp_f32_e32 v139, v139
	v_rcp_f32_e32 v144, v144
	v_rcp_f32_e32 v145, v145
	v_rcp_f32_e32 v147, v147
	v_rcp_f32_e32 v151, v148
	v_cvt_pk_f16_f32 v148, v130, v131
	v_cvt_pk_f16_f32 v149, v135, v139
	v_cvt_pk_f16_f32 v150, v144, v145
	v_cvt_pk_f16_f32 v151, v147, v151
	global_store_dwordx4 v[128:129], v[148:151], off offset:256
	v_add_u32_e32 v128, 0x80, v146
	v_mad_i64_i32 v[144:145], s[22:23], v128, s50, 0
	s_nop 0
	s_nop 0
	s_nop 0
	s_nop 1
	v_mov_b32_e32 v128, v160
	v_mov_b32_e32 v129, v161
	v_mov_b32_e32 v130, v162
	v_mov_b32_e32 v131, v163
	s_nop 1
	v_mov_b32_e32 v148, v164
	v_mov_b32_e32 v149, v165
	v_mov_b32_e32 v150, v166
	v_mov_b32_e32 v151, v167
	v_add_f32_e32 v128, v56, v128
	v_mul_f32_e32 v128, 0xbfb8aa3b, v128
	v_exp_f32_e32 v128, v128
	s_nop 0
	v_add_f32_e32 v147, v62, v150
	v_add_f32_e32 v135, v60, v148
	v_add_f32_e32 v148, v63, v151
	v_add_f32_e32 v128, 1.0, v128
	v_rcp_f32_e32 v150, v128
	v_add_f32_e32 v128, v57, v129
	v_mul_f32_e32 v128, 0xbfb8aa3b, v128
	v_exp_f32_e32 v128, v128
	v_add_f32_e32 v139, v61, v149
	v_mul_f32_e32 v135, 0xbfb8aa3b, v135
	v_mul_f32_e32 v139, 0xbfb8aa3b, v139
	v_add_f32_e32 v128, 1.0, v128
	v_rcp_f32_e32 v151, v128
	v_add_f32_e32 v128, v58, v130
	v_mul_f32_e32 v128, 0xbfb8aa3b, v128
	v_exp_f32_e32 v128, v128
	v_mul_f32_e32 v147, 0xbfb8aa3b, v147
	v_mul_f32_e32 v148, 0xbfb8aa3b, v148
	v_exp_f32_e32 v135, v135
	v_add_f32_e32 v128, 1.0, v128
	v_rcp_f32_e32 v130, v128
	v_add_f32_e32 v128, v59, v131
	v_mul_f32_e32 v128, 0xbfb8aa3b, v128
	v_exp_f32_e32 v139, v139
	v_exp_f32_e32 v147, v147
	v_exp_f32_e32 v148, v148
	v_exp_f32_e32 v128, v128
	v_add_f32_e32 v135, 1.0, v135
	v_add_f32_e32 v139, 1.0, v139
	v_add_f32_e32 v147, 1.0, v147
	v_add_f32_e32 v148, 1.0, v148
	v_add_f32_e32 v128, 1.0, v128
	v_rcp_f32_e32 v135, v135
	v_rcp_f32_e32 v139, v139
	v_rcp_f32_e32 v147, v147
	v_rcp_f32_e32 v149, v148
	v_rcp_f32_e32 v131, v128
	v_lshl_add_u64 v[128:129], v[144:145], 1, v[136:137]
	v_cvt_pk_f16_f32 v148, v135, v139
	v_cvt_pk_f16_f32 v149, v147, v149
	v_cvt_pk_f16_f32 v150, v150, v151
	v_cvt_pk_f16_f32 v151, v130, v131
	global_store_dwordx4 v[128:129], v[148:151], off
	s_nop 0
	s_nop 0
	s_nop 0
	s_nop 0
	s_nop 1
	v_mov_b32_e32 v148, v168
	v_mov_b32_e32 v149, v169
	v_mov_b32_e32 v150, v170
	v_mov_b32_e32 v151, v171
; __device__ __forceinline__ unsigned cvt_pk_bf16(float lo, float hi) { f32x2 v = {lo, hi}; bf16v2_t r = __builtin_convertvector(v, bf16v2_t); return __builtin_bit_cast(unsigned, r); }
; __device__ __forceinline__ float fexp(float x) { return __builtin_amdgcn_exp2f(x * 1.44269504089f); }
; __device__ __forceinline__ float fsigmoid(float x) { return __builtin_amdgcn_rcpf(1.0f + fexp(-x)); }
;     template <int KIND>
;     __device__ __forceinline__ void run(const f32x4 (&acc)[2][2][4][2], const UnitG& u, int wr, int wc, int fr, int fq) const {
;     ...
;                     } else if (KIND == 4) {
;                         const int c = u.x1 * 256 + bj * 128 + col0;
; #pragma unroll
;                         for (int e = 0; e < 8; ++e) { const float xx = -(v[e] + b0[c + e]); const float sp = (xx > 15.f) ? xx : __builtin_amdgcn_logf(1.0f + fexp(xx)) * 0.69314718056f; v[e] = fexp(-sp - 0.5f); }
;                     } else if (KIND == 5) {
;                         const int c = u.x1 * 256 + bj * 128 + col0 - 1024;
; #pragma unroll
;                         for (int e = 0; e < 8; ++e) v[e] = fsigmoid(v[e] + b1[c + e]);
;                     }
;                     if (KIND == 4 || KIND == 5) { w.x = pkh2(v[0], v[1]); w.y = pkh2(v[2], v[3]); w.z = pkh2(v[4], v[5]); w.w = pkh2(v[6], v[7]); }
;                     else { w.x = cvt_pk_bf16(v[0], v[1]); w.y = cvt_pk_bf16(v[2], v[3]); w.z = cvt_pk_bf16(v[4], v[5]); w.w = cvt_pk_bf16(v[6], v[7]); }
;                     *(v4u*)dst = w; }
	s_nop 1
	v_mov_b32_e32 v152, v172
	v_mov_b32_e32 v153, v173
	v_mov_b32_e32 v154, v174
	v_mov_b32_e32 v155, v175
	v_add_f32_e32 v144, v48, v148
	s_nop 0
	v_add_f32_e32 v130, v52, v152
	v_add_f32_e32 v131, v53, v153
	v_add_f32_e32 v135, v54, v154
	v_add_f32_e32 v139, v55, v155
	v_add_f32_e32 v145, v49, v149
	v_add_f32_e32 v147, v50, v150
	v_add_f32_e32 v148, v51, v151
	v_mul_f32_e32 v130, 0xbfb8aa3b, v130
	v_mul_f32_e32 v131, 0xbfb8aa3b, v131
	v_mul_f32_e32 v135, 0xbfb8aa3b, v135
	v_mul_f32_e32 v139, 0xbfb8aa3b, v139
	v_mul_f32_e32 v144, 0xbfb8aa3b, v144
	v_mul_f32_e32 v145, 0xbfb8aa3b, v145
	v_mul_f32_e32 v147, 0xbfb8aa3b, v147
	v_mul_f32_e32 v148, 0xbfb8aa3b, v148
	v_exp_f32_e32 v130, v130
	v_exp_f32_e32 v131, v131
	v_exp_f32_e32 v135, v135
	v_exp_f32_e32 v139, v139
	v_exp_f32_e32 v144, v144
	v_exp_f32_e32 v145, v145
	v_exp_f32_e32 v147, v147
	v_exp_f32_e32 v148, v148
	v_add_f32_e32 v130, 1.0, v130
	v_add_f32_e32 v131, 1.0, v131
	v_add_f32_e32 v135, 1.0, v135
	v_add_f32_e32 v139, 1.0, v139
	v_add_f32_e32 v144, 1.0, v144
	v_add_f32_e32 v145, 1.0, v145
	v_add_f32_e32 v147, 1.0, v147
	v_add_f32_e32 v148, 1.0, v148
	v_rcp_f32_e32 v130, v130
	v_rcp_f32_e32 v131, v131
	v_rcp_f32_e32 v135, v135
	v_rcp_f32_e32 v139, v139
	v_rcp_f32_e32 v144, v144
	v_rcp_f32_e32 v145, v145
	v_rcp_f32_e32 v147, v147
	v_rcp_f32_e32 v151, v148
	v_cvt_pk_f16_f32 v148, v130, v131
	v_cvt_pk_f16_f32 v149, v135, v139
	v_cvt_pk_f16_f32 v150, v144, v145
	v_cvt_pk_f16_f32 v151, v147, v151
	global_store_dwordx4 v[128:129], v[148:151], off offset:256
	v_add_u32_e32 v128, 0x90, v146
	v_mad_i64_i32 v[144:145], s[22:23], v128, s50, 0
	s_nop 0
	s_nop 0
	s_nop 0
	s_nop 1
	v_mov_b32_e32 v128, v160
	v_mov_b32_e32 v129, v161
	v_mov_b32_e32 v130, v162
	v_mov_b32_e32 v131, v163
	s_nop 1
	v_mov_b32_e32 v148, v164
	v_mov_b32_e32 v149, v165
	v_mov_b32_e32 v150, v166
	v_mov_b32_e32 v151, v167
	v_add_f32_e32 v128, v40, v128
	v_mul_f32_e32 v128, 0xbfb8aa3b, v128
	v_exp_f32_e32 v128, v128
	s_nop 0
	v_add_f32_e32 v147, v46, v150
	v_add_f32_e32 v135, v44, v148
	v_add_f32_e32 v148, v47, v151
	v_add_f32_e32 v128, 1.0, v128
	v_rcp_f32_e32 v150, v128
	v_add_f32_e32 v128, v41, v129
	v_mul_f32_e32 v128, 0xbfb8aa3b, v128
	v_exp_f32_e32 v128, v128
	v_add_f32_e32 v139, v45, v149
	v_mul_f32_e32 v135, 0xbfb8aa3b, v135
	v_mul_f32_e32 v139, 0xbfb8aa3b, v139
	v_add_f32_e32 v128, 1.0, v128
	v_rcp_f32_e32 v151, v128
	v_add_f32_e32 v128, v42, v130
	v_mul_f32_e32 v128, 0xbfb8aa3b, v128
	v_exp_f32_e32 v128, v128
	v_mul_f32_e32 v147, 0xbfb8aa3b, v147
	v_mul_f32_e32 v148, 0xbfb8aa3b, v148
	v_exp_f32_e32 v135, v135
	v_add_f32_e32 v128, 1.0, v128
	v_rcp_f32_e32 v130, v128
	v_add_f32_e32 v128, v43, v131
	v_mul_f32_e32 v128, 0xbfb8aa3b, v128
	v_exp_f32_e32 v139, v139
	v_exp_f32_e32 v147, v147
	v_exp_f32_e32 v148, v148
	v_exp_f32_e32 v128, v128
	v_add_f32_e32 v135, 1.0, v135
	v_add_f32_e32 v139, 1.0, v139
	v_add_f32_e32 v147, 1.0, v147
	v_add_f32_e32 v148, 1.0, v148
	v_add_f32_e32 v128, 1.0, v128
	v_rcp_f32_e32 v135, v135
	v_rcp_f32_e32 v139, v139
	v_rcp_f32_e32 v147, v147
	v_rcp_f32_e32 v149, v148
	v_rcp_f32_e32 v131, v128
	v_lshl_add_u64 v[128:129], v[144:145], 1, v[136:137]
	v_cvt_pk_f16_f32 v148, v135, v139
	v_cvt_pk_f16_f32 v149, v147, v149
	v_cvt_pk_f16_f32 v150, v150, v151
	v_cvt_pk_f16_f32 v151, v130, v131
	global_store_dwordx4 v[128:129], v[148:151], off
	s_nop 0
	s_nop 0
	s_nop 0
	s_nop 0
	s_nop 1
	v_mov_b32_e32 v148, v168
	v_mov_b32_e32 v149, v169
	v_mov_b32_e32 v150, v170
	v_mov_b32_e32 v151, v171
	s_nop 1
	v_mov_b32_e32 v152, v172
	v_mov_b32_e32 v153, v173
	v_mov_b32_e32 v154, v174
	v_mov_b32_e32 v155, v175
	v_add_f32_e32 v144, v32, v148
	s_nop 0
	v_add_f32_e32 v130, v36, v152
	v_add_f32_e32 v131, v37, v153
	v_add_f32_e32 v135, v38, v154
	v_add_f32_e32 v139, v39, v155
	v_add_f32_e32 v145, v33, v149
	v_add_f32_e32 v147, v34, v150
	v_add_f32_e32 v148, v35, v151
	v_mul_f32_e32 v130, 0xbfb8aa3b, v130
	v_mul_f32_e32 v131, 0xbfb8aa3b, v131
	v_mul_f32_e32 v135, 0xbfb8aa3b, v135
	v_mul_f32_e32 v139, 0xbfb8aa3b, v139
	v_mul_f32_e32 v144, 0xbfb8aa3b, v144
	v_mul_f32_e32 v145, 0xbfb8aa3b, v145
	v_mul_f32_e32 v147, 0xbfb8aa3b, v147
	v_mul_f32_e32 v148, 0xbfb8aa3b, v148
	v_exp_f32_e32 v130, v130
	v_exp_f32_e32 v131, v131
	v_exp_f32_e32 v135, v135
	v_exp_f32_e32 v139, v139
	v_exp_f32_e32 v144, v144
	v_exp_f32_e32 v145, v145
	v_exp_f32_e32 v147, v147
	v_exp_f32_e32 v148, v148
	v_add_f32_e32 v130, 1.0, v130
	v_add_f32_e32 v131, 1.0, v131
	v_add_f32_e32 v135, 1.0, v135
	v_add_f32_e32 v139, 1.0, v139
	v_add_f32_e32 v144, 1.0, v144
	v_add_f32_e32 v145, 1.0, v145
	v_add_f32_e32 v147, 1.0, v147
	v_add_f32_e32 v148, 1.0, v148
	v_rcp_f32_e32 v130, v130
	v_rcp_f32_e32 v131, v131
	v_rcp_f32_e32 v135, v135
	v_rcp_f32_e32 v139, v139
	v_rcp_f32_e32 v144, v144
	v_rcp_f32_e32 v145, v145
	v_rcp_f32_e32 v147, v147
	v_rcp_f32_e32 v151, v148
	v_cvt_pk_f16_f32 v148, v130, v131
	v_cvt_pk_f16_f32 v149, v135, v139
	v_cvt_pk_f16_f32 v150, v144, v145
	v_cvt_pk_f16_f32 v151, v147, v151
	global_store_dwordx4 v[128:129], v[148:151], off offset:256
	v_add_u32_e32 v128, 0xa0, v146
	v_mad_i64_i32 v[144:145], s[22:23], v128, s50, 0
	s_nop 0
	s_nop 0
	s_nop 0
	s_nop 1
	v_mov_b32_e32 v128, v160
	v_mov_b32_e32 v129, v161
	v_mov_b32_e32 v130, v162
	v_mov_b32_e32 v131, v163
	s_nop 1
	v_mov_b32_e32 v148, v164
	v_mov_b32_e32 v149, v165
	v_mov_b32_e32 v150, v166
	v_mov_b32_e32 v151, v167
	v_add_f32_e32 v128, v24, v128
	v_mul_f32_e32 v128, 0xbfb8aa3b, v128
	v_exp_f32_e32 v128, v128
	s_nop 0
	v_add_f32_e32 v147, v30, v150
	v_add_f32_e32 v135, v28, v148
	v_add_f32_e32 v148, v31, v151
	v_add_f32_e32 v128, 1.0, v128
	v_rcp_f32_e32 v150, v128
	v_add_f32_e32 v128, v25, v129
; __device__ __forceinline__ unsigned cvt_pk_bf16(float lo, float hi) { f32x2 v = {lo, hi}; bf16v2_t r = __builtin_convertvector(v, bf16v2_t); return __builtin_bit_cast(unsigned, r); }
; __device__ __forceinline__ float fexp(float x) { return __builtin_amdgcn_exp2f(x * 1.44269504089f); }
; __device__ __forceinline__ float fsigmoid(float x) { return __builtin_amdgcn_rcpf(1.0f + fexp(-x)); }
;     template <int KIND>
;     __device__ __forceinline__ void run(const f32x4 (&acc)[2][2][4][2], const UnitG& u, int wr, int wc, int fr, int fq) const {
;     ...
;                     } else if (KIND == 4) {
;                         const int c = u.x1 * 256 + bj * 128 + col0;
; #pragma unroll
;                         for (int e = 0; e < 8; ++e) { const float xx = -(v[e] + b0[c + e]); const float sp = (xx > 15.f) ? xx : __builtin_amdgcn_logf(1.0f + fexp(xx)) * 0.69314718056f; v[e] = fexp(-sp - 0.5f); }
;                     } else if (KIND == 5) {
;                         const int c = u.x1 * 256 + bj * 128 + col0 - 1024;
; #pragma unroll
;                         for (int e = 0; e < 8; ++e) v[e] = fsigmoid(v[e] + b1[c + e]);
;                     }
;                     if (KIND == 4 || KIND == 5) { w.x = pkh2(v[0], v[1]); w.y = pkh2(v[2], v[3]); w.z = pkh2(v[4], v[5]); w.w = pkh2(v[6], v[7]); }
;                     else { w.x = cvt_pk_bf16(v[0], v[1]); w.y = cvt_pk_bf16(v[2], v[3]); w.z = cvt_pk_bf16(v[4], v[5]); w.w = cvt_pk_bf16(v[6], v[7]); }
;                     *(v4u*)dst = w; }
	v_mul_f32_e32 v128, 0xbfb8aa3b, v128
	v_exp_f32_e32 v128, v128
	v_add_f32_e32 v139, v29, v149
	v_mul_f32_e32 v135, 0xbfb8aa3b, v135
	v_mul_f32_e32 v139, 0xbfb8aa3b, v139
	v_add_f32_e32 v128, 1.0, v128
	v_rcp_f32_e32 v151, v128
	v_add_f32_e32 v128, v26, v130
	v_mul_f32_e32 v128, 0xbfb8aa3b, v128
	v_exp_f32_e32 v128, v128
	v_mul_f32_e32 v147, 0xbfb8aa3b, v147
	v_mul_f32_e32 v148, 0xbfb8aa3b, v148
	v_exp_f32_e32 v135, v135
	v_add_f32_e32 v128, 1.0, v128
	v_rcp_f32_e32 v130, v128
	v_add_f32_e32 v128, v27, v131
	v_mul_f32_e32 v128, 0xbfb8aa3b, v128
	v_exp_f32_e32 v139, v139
	v_exp_f32_e32 v147, v147
	v_exp_f32_e32 v148, v148
	v_exp_f32_e32 v128, v128
	v_add_f32_e32 v135, 1.0, v135
	v_add_f32_e32 v139, 1.0, v139
	v_add_f32_e32 v147, 1.0, v147
	v_add_f32_e32 v148, 1.0, v148
	v_add_f32_e32 v128, 1.0, v128
	v_rcp_f32_e32 v135, v135
	v_rcp_f32_e32 v139, v139
	v_rcp_f32_e32 v147, v147
	v_rcp_f32_e32 v149, v148
	v_rcp_f32_e32 v131, v128
	v_lshl_add_u64 v[128:129], v[144:145], 1, v[136:137]
	v_cvt_pk_f16_f32 v148, v135, v139
	v_cvt_pk_f16_f32 v149, v147, v149
	v_cvt_pk_f16_f32 v150, v150, v151
	v_cvt_pk_f16_f32 v151, v130, v131
	global_store_dwordx4 v[128:129], v[148:151], off
	s_nop 0
	s_nop 0
	s_nop 0
	s_nop 0
	s_nop 1
	v_mov_b32_e32 v148, v168
	v_mov_b32_e32 v149, v169
	v_mov_b32_e32 v150, v170
	v_mov_b32_e32 v151, v171
	s_nop 1
	v_mov_b32_e32 v152, v172
	v_mov_b32_e32 v153, v173
	v_mov_b32_e32 v154, v174
	v_mov_b32_e32 v155, v175
	v_add_f32_e32 v144, v16, v148
	s_nop 0
	v_add_f32_e32 v130, v20, v152
	v_add_f32_e32 v131, v21, v153
	v_add_f32_e32 v135, v22, v154
	v_add_f32_e32 v139, v23, v155
	v_add_f32_e32 v145, v17, v149
	v_add_f32_e32 v147, v18, v150
	v_add_f32_e32 v148, v19, v151
	v_mul_f32_e32 v130, 0xbfb8aa3b, v130
	v_mul_f32_e32 v131, 0xbfb8aa3b, v131
	v_mul_f32_e32 v135, 0xbfb8aa3b, v135
	v_mul_f32_e32 v139, 0xbfb8aa3b, v139
	v_mul_f32_e32 v144, 0xbfb8aa3b, v144
	v_mul_f32_e32 v145, 0xbfb8aa3b, v145
	v_mul_f32_e32 v147, 0xbfb8aa3b, v147
	v_mul_f32_e32 v148, 0xbfb8aa3b, v148
	v_exp_f32_e32 v130, v130
	v_exp_f32_e32 v131, v131
	v_exp_f32_e32 v135, v135
	v_exp_f32_e32 v139, v139
	v_exp_f32_e32 v144, v144
	v_exp_f32_e32 v145, v145
	v_exp_f32_e32 v147, v147
	v_exp_f32_e32 v148, v148
	v_add_f32_e32 v130, 1.0, v130
	v_add_f32_e32 v131, 1.0, v131
	v_add_f32_e32 v135, 1.0, v135
	v_add_f32_e32 v139, 1.0, v139
	v_add_f32_e32 v144, 1.0, v144
	v_add_f32_e32 v145, 1.0, v145
	v_add_f32_e32 v147, 1.0, v147
	v_add_f32_e32 v148, 1.0, v148
	v_rcp_f32_e32 v130, v130
	v_rcp_f32_e32 v131, v131
	v_rcp_f32_e32 v135, v135
	v_rcp_f32_e32 v139, v139
	v_rcp_f32_e32 v144, v144
	v_rcp_f32_e32 v145, v145
	v_rcp_f32_e32 v147, v147
	v_rcp_f32_e32 v151, v148
	v_cvt_pk_f16_f32 v148, v130, v131
	v_cvt_pk_f16_f32 v149, v135, v139
	v_cvt_pk_f16_f32 v150, v144, v145
	v_cvt_pk_f16_f32 v151, v147, v151
	global_store_dwordx4 v[128:129], v[148:151], off offset:256
	v_add_u32_e32 v128, 0xb0, v146
	s_nop 0
	v_mad_i64_i32 v[148:149], s[22:23], v128, s50, 0
	s_nop 0
	s_nop 0
	s_nop 0
	s_mov_b64 s[22:23], 0
	s_nop 0
	s_nop 1
	v_mov_b32_e32 v128, v160
	v_mov_b32_e32 v129, v161
	v_mov_b32_e32 v130, v162
	v_mov_b32_e32 v131, v163
	s_nop 1
	v_mov_b32_e32 v142, v164
	v_mov_b32_e32 v143, v165
	v_mov_b32_e32 v144, v166
	v_mov_b32_e32 v145, v167
	v_add_f32_e32 v128, v8, v128
	s_nop 0
	v_add_f32_e32 v135, v12, v142
	v_add_f32_e32 v142, v14, v144
	v_mul_f32_e32 v142, 0xbfb8aa3b, v142
	v_mul_f32_e32 v128, 0xbfb8aa3b, v128
	v_exp_f32_e32 v142, v142
	v_exp_f32_e32 v128, v128
	v_add_f32_e32 v139, v13, v143
	v_mul_f32_e32 v135, 0xbfb8aa3b, v135
	v_add_f32_e32 v142, 1.0, v142
	v_add_f32_e32 v128, 1.0, v128
	v_rcp_f32_e32 v143, v142
	v_add_f32_e32 v142, v15, v145
	v_rcp_f32_e32 v145, v128
	v_add_f32_e32 v128, v9, v129
	v_mul_f32_e32 v128, 0xbfb8aa3b, v128
	v_exp_f32_e32 v128, v128
	v_mul_f32_e32 v139, 0xbfb8aa3b, v139
	v_mul_f32_e32 v142, 0xbfb8aa3b, v142
	v_exp_f32_e32 v135, v135
	v_add_f32_e32 v128, 1.0, v128
	v_rcp_f32_e32 v147, v128
	v_add_f32_e32 v128, v10, v130
	v_mul_f32_e32 v128, 0xbfb8aa3b, v128
	v_exp_f32_e32 v128, v128
	v_exp_f32_e32 v139, v139
	v_exp_f32_e32 v142, v142
	v_add_f32_e32 v135, 1.0, v135
	v_add_f32_e32 v128, 1.0, v128
	v_rcp_f32_e32 v130, v128
	v_add_f32_e32 v128, v11, v131
	v_mul_f32_e32 v128, 0xbfb8aa3b, v128
	v_exp_f32_e32 v128, v128
	v_add_f32_e32 v139, 1.0, v139
	v_add_f32_e32 v142, 1.0, v142
	v_rcp_f32_e32 v135, v135
	v_add_f32_e32 v128, 1.0, v128
	v_rcp_f32_e32 v139, v139
	v_rcp_f32_e32 v144, v142
	v_rcp_f32_e32 v131, v128
	v_lshl_add_u64 v[128:129], v[148:149], 1, v[136:137]
	v_cvt_pk_f16_f32 v142, v135, v139
	v_cvt_pk_f16_f32 v143, v143, v144
	v_cvt_pk_f16_f32 v144, v145, v147
	v_cvt_pk_f16_f32 v145, v130, v131
	global_store_dwordx4 v[128:129], v[142:145], off
	s_nop 0
	s_nop 0
	s_nop 0
	s_nop 0
	s_nop 1
	v_mov_b32_e32 v142, v168
	v_mov_b32_e32 v143, v169
	v_mov_b32_e32 v144, v170
	v_mov_b32_e32 v145, v171
	s_nop 1
	v_mov_b32_e32 v148, v172
	v_mov_b32_e32 v149, v173
	v_mov_b32_e32 v150, v174
	v_mov_b32_e32 v151, v175
	v_add_f32_e32 v140, v0, v142
	v_mul_f32_e32 v140, 0xbfb8aa3b, v140
	v_exp_f32_e32 v140, v140
	s_nop 0
	v_add_f32_e32 v130, v4, v148
	v_add_f32_e32 v131, v5, v149
	v_add_f32_e32 v135, v6, v150
	v_add_f32_e32 v140, 1.0, v140
	v_rcp_f32_e32 v142, v140
	v_add_f32_e32 v140, v1, v143
	v_mul_f32_e32 v140, 0xbfb8aa3b, v140
	v_exp_f32_e32 v140, v140
	v_add_f32_e32 v139, v7, v151
	v_mul_f32_e32 v130, 0xbfb8aa3b, v130
	v_mul_f32_e32 v131, 0xbfb8aa3b, v131
	v_add_f32_e32 v140, 1.0, v140
	v_rcp_f32_e32 v143, v140
	v_add_f32_e32 v140, v2, v144
	v_mul_f32_e32 v140, 0xbfb8aa3b, v140
	v_exp_f32_e32 v140, v140
	v_mul_f32_e32 v135, 0xbfb8aa3b, v135
	v_mul_f32_e32 v139, 0xbfb8aa3b, v139
	v_exp_f32_e32 v130, v130
	v_add_f32_e32 v140, 1.0, v140
	v_rcp_f32_e32 v144, v140
	v_add_f32_e32 v140, v3, v145
	v_mul_f32_e32 v140, 0xbfb8aa3b, v140
	v_exp_f32_e32 v131, v131
	v_exp_f32_e32 v135, v135
	v_exp_f32_e32 v139, v139
	v_exp_f32_e32 v140, v140
	v_add_f32_e32 v130, 1.0, v130
	v_add_f32_e32 v131, 1.0, v131
	v_add_f32_e32 v135, 1.0, v135
	v_add_f32_e32 v139, 1.0, v139
	v_add_f32_e32 v140, 1.0, v140
	v_rcp_f32_e32 v130, v130
	v_rcp_f32_e32 v131, v131
	v_rcp_f32_e32 v135, v135
	v_rcp_f32_e32 v139, v139
	v_rcp_f32_e32 v145, v140
	v_cvt_pk_f16_f32 v140, v130, v131
	v_cvt_pk_f16_f32 v142, v142, v143
	v_cvt_pk_f16_f32 v141, v135, v139
	v_cvt_pk_f16_f32 v143, v144, v145
	global_store_dwordx4 v[128:129], v[140:143], off offset:256

; __device__ __forceinline__ unsigned cvt_pk_bf16(float lo, float hi) { f32x2 v = {lo, hi}; bf16v2_t r = __builtin_convertvector(v, bf16v2_t); return __builtin_bit_cast(unsigned, r); }
; __device__ __forceinline__ float fexp(float x) { return __builtin_amdgcn_exp2f(x * 1.44269504089f); }
; __device__ __forceinline__ float fsigmoid(float x) { return __builtin_amdgcn_rcpf(1.0f + fexp(-x)); }
;     template <int KIND>
;     __device__ __forceinline__ void run(const f32x4 (&acc)[2][2][4][2], const UnitG& u, int wr, int wc, int fr, int fq) const {
;     ...
;                     } else if (KIND == 4) {
;                         const int c = u.x1 * 256 + bj * 128 + col0;
; #pragma unroll
;                         for (int e = 0; e < 8; ++e) { const float xx = -(v[e] + b0[c + e]); const float sp = (xx > 15.f) ? xx : __builtin_amdgcn_logf(1.0f + fexp(xx)) * 0.69314718056f; v[e] = fexp(-sp - 0.5f); }
;                     } else if (KIND == 5) {
;                         const int c = u.x1 * 256 + bj * 128 + col0 - 1024;
; #pragma unroll
;                         for (int e = 0; e < 8; ++e) v[e] = fsigmoid(v[e] + b1[c + e]);
;                     }
;                     if (KIND == 4 || KIND == 5) { w.x = pkh2(v[0], v[1]); w.y = pkh2(v[2], v[3]); w.z = pkh2(v[4], v[5]); w.w = pkh2(v[6], v[7]); }
;                     else { w.x = cvt_pk_bf16(v[0], v[1]); w.y = cvt_pk_bf16(v[2], v[3]); w.z = cvt_pk_bf16(v[4], v[5]); w.w = cvt_pk_bf16(v[6], v[7]); }
;                     *(v4u*)dst = w; }
.LBB0_560:
	s_nop 0
	v_lshl_add_u32 v130, s34, 8, v138
	v_ashrrev_i32_e32 v131, 31, v130
	v_lshl_add_u64 v[128:129], v[130:131], 2, s[10:11]
	global_load_dwordx4 v[160:163], v[128:129], off offset:16
	global_load_dwordx4 v[164:167], v[128:129], off
	s_mov_b32 s22, 0xc1700000
	v_mad_i64_i32 v[140:141], s[20:21], v146, s50, 0
	s_waitcnt vmcnt(0)
	s_nop 1
	v_mov_b32_e32 v148, v160
	v_mov_b32_e32 v149, v161
	v_mov_b32_e32 v150, v162
	v_mov_b32_e32 v151, v163
	s_nop 1
	v_mov_b32_e32 v152, v164
	v_mov_b32_e32 v153, v165
	v_mov_b32_e32 v154, v166
	v_mov_b32_e32 v155, v167
	v_add_f32_e32 v120, v120, v148
	v_add_f32_e32 v124, v124, v152
	v_mul_f32_e32 v131, 0xbfb8aa3b, v124
	v_exp_f32_e32 v131, v131
	v_cmp_gt_f32_e32 vcc, s22, v124
	v_add_f32_e32 v125, v125, v153
	v_add_f32_e32 v126, v126, v154
	v_add_f32_e32 v131, 1.0, v131
	v_log_f32_e32 v131, v131
	s_nop 0
	v_mul_f32_e32 v131, 0x3f317218, v131
	v_cndmask_b32_e64 v124, v131, -v124, vcc
	v_mul_f32_e32 v131, 0xbfb8aa3b, v125
	v_exp_f32_e32 v131, v131
	v_cmp_gt_f32_e32 vcc, s22, v125
	v_sub_f32_e32 v124, -0.5, v124
	v_mul_f32_e32 v124, 0x3fb8aa3b, v124
	v_add_f32_e32 v131, 1.0, v131
	v_log_f32_e32 v131, v131
	v_exp_f32_e32 v124, v124
	v_mul_f32_e32 v131, 0x3f317218, v131
	v_cndmask_b32_e64 v125, v131, -v125, vcc
	v_mul_f32_e32 v131, 0xbfb8aa3b, v126
	v_exp_f32_e32 v131, v131
	v_cmp_gt_f32_e32 vcc, s22, v126
	v_sub_f32_e32 v125, -0.5, v125
	v_mul_f32_e32 v125, 0x3fb8aa3b, v125
	v_add_f32_e32 v131, 1.0, v131
	v_log_f32_e32 v131, v131
	v_exp_f32_e32 v125, v125
	v_mul_f32_e32 v131, 0x3f317218, v131
	v_cndmask_b32_e64 v126, v131, -v126, vcc
	v_sub_f32_e32 v126, -0.5, v126
	v_mul_f32_e32 v126, 0x3fb8aa3b, v126
	v_exp_f32_e32 v131, v126
	v_add_f32_e32 v126, v127, v155
	v_mul_f32_e32 v127, 0xbfb8aa3b, v126
	v_exp_f32_e32 v127, v127
	v_cmp_gt_f32_e32 vcc, s22, v126
	v_add_f32_e32 v127, 1.0, v127
	v_log_f32_e32 v127, v127
	s_nop 0
	v_mul_f32_e32 v127, 0x3f317218, v127
	v_cndmask_b32_e64 v126, v127, -v126, vcc
	v_sub_f32_e32 v126, -0.5, v126
	v_mul_f32_e32 v126, 0x3fb8aa3b, v126
	v_exp_f32_e32 v138, v126
	v_mul_f32_e32 v126, 0xbfb8aa3b, v120
	v_exp_f32_e32 v126, v126
	v_cmp_gt_f32_e32 vcc, s22, v120
	v_add_f32_e32 v126, 1.0, v126
	v_log_f32_e32 v126, v126
	s_nop 0
	v_mul_f32_e32 v126, 0x3f317218, v126
	v_cndmask_b32_e64 v120, v126, -v120, vcc
	v_sub_f32_e32 v120, -0.5, v120
	v_mul_f32_e32 v120, 0x3fb8aa3b, v120
	v_exp_f32_e32 v146, v120
	v_add_f32_e32 v120, v121, v149
	v_mul_f32_e32 v121, 0xbfb8aa3b, v120
	v_exp_f32_e32 v121, v121
	v_cmp_gt_f32_e32 vcc, s22, v120
	v_lshl_add_u64 v[126:127], v[140:141], 1, v[136:137]
	v_add_f32_e32 v121, 1.0, v121
	v_log_f32_e32 v121, v121
	s_nop 0
	v_mul_f32_e32 v121, 0x3f317218, v121
	v_cndmask_b32_e64 v120, v121, -v120, vcc
	v_sub_f32_e32 v120, -0.5, v120
	v_mul_f32_e32 v120, 0x3fb8aa3b, v120
	v_exp_f32_e32 v148, v120
	v_add_f32_e32 v120, v122, v150
	v_mul_f32_e32 v121, 0xbfb8aa3b, v120
	v_exp_f32_e32 v121, v121
	v_cmp_gt_f32_e32 vcc, s22, v120
	v_cvt_pk_f16_f32 v122, v146, v148
	v_add_f32_e32 v121, 1.0, v121
	v_log_f32_e32 v121, v121
	s_nop 0
	v_mul_f32_e32 v121, 0x3f317218, v121
	v_cndmask_b32_e64 v120, v121, -v120, vcc
	v_sub_f32_e32 v120, -0.5, v120
	v_mul_f32_e32 v120, 0x3fb8aa3b, v120
	v_exp_f32_e32 v149, v120
	v_add_f32_e32 v120, v123, v151
	v_mul_f32_e32 v121, 0xbfb8aa3b, v120
	v_exp_f32_e32 v121, v121
	v_cmp_gt_f32_e32 vcc, s22, v120
	v_add_f32_e32 v121, 1.0, v121
	v_log_f32_e32 v121, v121
	s_nop 0
	v_mul_f32_e32 v121, 0x3f317218, v121
	v_cndmask_b32_e64 v120, v121, -v120, vcc
	v_sub_f32_e32 v120, -0.5, v120
	v_mul_f32_e32 v120, 0x3fb8aa3b, v120
	v_exp_f32_e32 v123, v120
	v_cvt_pk_f16_f32 v120, v124, v125
	v_cvt_pk_f16_f32 v121, v131, v138
	v_cvt_pk_f16_f32 v123, v149, v123
	global_store_dwordx4 v[126:127], v[120:123], off
	s_nop 1
	v_add_u32_e32 v120, 0x80, v130
	v_ashrrev_i32_e32 v121, 31, v120
	v_lshl_add_u64 v[124:125], v[120:121], 2, s[10:11]
	global_load_dwordx4 v[168:171], v[124:125], off offset:16
	global_load_dwordx4 v[172:175], v[124:125], off
	s_waitcnt vmcnt(1)
	s_nop 1
	v_mov_b32_e32 v120, v168
	v_mov_b32_e32 v121, v169
	v_mov_b32_e32 v122, v170
	v_mov_b32_e32 v123, v171
	v_add_f32_e32 v112, v112, v120
	s_waitcnt vmcnt(0)
	s_nop 1
	v_mov_b32_e32 v148, v172
	v_mov_b32_e32 v149, v173
	v_mov_b32_e32 v150, v174
	v_mov_b32_e32 v151, v175
	v_add_f32_e32 v116, v116, v148
	v_mul_f32_e32 v130, 0xbfb8aa3b, v116
	v_exp_f32_e32 v130, v130
	v_cmp_gt_f32_e32 vcc, s22, v116
	v_add_f32_e32 v117, v117, v149
	v_add_f32_e32 v118, v118, v150
	v_add_f32_e32 v130, 1.0, v130
	v_log_f32_e32 v130, v130
	v_add_f32_e32 v119, v119, v151
	v_mul_f32_e32 v120, 0xbfb8aa3b, v112
	v_exp_f32_e32 v120, v120
	v_mul_f32_e32 v130, 0x3f317218, v130
	v_cndmask_b32_e64 v116, v130, -v116, vcc
	v_mul_f32_e32 v130, 0xbfb8aa3b, v117
	v_exp_f32_e32 v130, v130
	v_cmp_gt_f32_e32 vcc, s22, v117
	v_add_f32_e32 v120, 1.0, v120
	v_log_f32_e32 v120, v120
	v_add_f32_e32 v130, 1.0, v130
	v_log_f32_e32 v130, v130
	v_sub_f32_e32 v116, -0.5, v116
	v_mul_f32_e32 v120, 0x3f317218, v120
	v_mul_f32_e32 v116, 0x3fb8aa3b, v116
	v_mul_f32_e32 v130, 0x3f317218, v130
	v_cndmask_b32_e64 v117, v130, -v117, vcc
	v_mul_f32_e32 v130, 0xbfb8aa3b, v118
	v_exp_f32_e32 v130, v130
	v_cmp_gt_f32_e32 vcc, s22, v118
	v_sub_f32_e32 v117, -0.5, v117
	v_mul_f32_e32 v117, 0x3fb8aa3b, v117
	v_add_f32_e32 v130, 1.0, v130
	v_log_f32_e32 v130, v130
	v_exp_f32_e32 v116, v116
	v_exp_f32_e32 v117, v117
	v_mul_f32_e32 v130, 0x3f317218, v130
	v_cndmask_b32_e64 v118, v130, -v118, vcc
	v_mul_f32_e32 v130, 0xbfb8aa3b, v119
	v_exp_f32_e32 v130, v130
	v_cmp_gt_f32_e32 vcc, s22, v119
	v_sub_f32_e32 v118, -0.5, v118
	v_mul_f32_e32 v118, 0x3fb8aa3b, v118
; __device__ __forceinline__ unsigned cvt_pk_bf16(float lo, float hi) { f32x2 v = {lo, hi}; bf16v2_t r = __builtin_convertvector(v, bf16v2_t); return __builtin_bit_cast(unsigned, r); }
; __device__ __forceinline__ float fexp(float x) { return __builtin_amdgcn_exp2f(x * 1.44269504089f); }
; __device__ __forceinline__ float fsigmoid(float x) { return __builtin_amdgcn_rcpf(1.0f + fexp(-x)); }
;     template <int KIND>
;     __device__ __forceinline__ void run(const f32x4 (&acc)[2][2][4][2], const UnitG& u, int wr, int wc, int fr, int fq) const {
;     ...
;                     } else if (KIND == 4) {
;                         const int c = u.x1 * 256 + bj * 128 + col0;
; #pragma unroll
;                         for (int e = 0; e < 8; ++e) { const float xx = -(v[e] + b0[c + e]); const float sp = (xx > 15.f) ? xx : __builtin_amdgcn_logf(1.0f + fexp(xx)) * 0.69314718056f; v[e] = fexp(-sp - 0.5f); }
;                     } else if (KIND == 5) {
;                         const int c = u.x1 * 256 + bj * 128 + col0 - 1024;
; #pragma unroll
;                         for (int e = 0; e < 8; ++e) v[e] = fsigmoid(v[e] + b1[c + e]);
;                     }
;                     if (KIND == 4 || KIND == 5) { w.x = pkh2(v[0], v[1]); w.y = pkh2(v[2], v[3]); w.z = pkh2(v[4], v[5]); w.w = pkh2(v[6], v[7]); }
;                     else { w.x = cvt_pk_bf16(v[0], v[1]); w.y = cvt_pk_bf16(v[2], v[3]); w.z = cvt_pk_bf16(v[4], v[5]); w.w = cvt_pk_bf16(v[6], v[7]); }
;                     *(v4u*)dst = w; }
	v_add_f32_e32 v130, 1.0, v130
	v_log_f32_e32 v130, v130
	v_exp_f32_e32 v118, v118
	v_mul_f32_e32 v130, 0x3f317218, v130
	v_cndmask_b32_e64 v119, v130, -v119, vcc
	v_cmp_gt_f32_e32 vcc, s22, v112
	v_sub_f32_e32 v119, -0.5, v119
	v_mul_f32_e32 v119, 0x3fb8aa3b, v119
	v_cndmask_b32_e64 v112, v120, -v112, vcc
	v_sub_f32_e32 v112, -0.5, v112
	v_mul_f32_e32 v112, 0x3fb8aa3b, v112
	v_exp_f32_e32 v120, v112
	v_add_f32_e32 v112, v113, v121
	v_mul_f32_e32 v113, 0xbfb8aa3b, v112
	v_exp_f32_e32 v113, v113
	v_cmp_gt_f32_e32 vcc, s22, v112
	v_exp_f32_e32 v119, v119
	v_add_f32_e32 v113, 1.0, v113
	v_log_f32_e32 v113, v113
	s_nop 0
	v_mul_f32_e32 v113, 0x3f317218, v113
	v_cndmask_b32_e64 v112, v113, -v112, vcc
	v_sub_f32_e32 v112, -0.5, v112
	v_mul_f32_e32 v112, 0x3fb8aa3b, v112
	v_exp_f32_e32 v121, v112
	v_add_f32_e32 v112, v114, v122
	v_mul_f32_e32 v113, 0xbfb8aa3b, v112
	v_exp_f32_e32 v113, v113
	v_cmp_gt_f32_e32 vcc, s22, v112
	v_cvt_pk_f16_f32 v114, v120, v121
	v_add_f32_e32 v113, 1.0, v113
	v_log_f32_e32 v113, v113
	s_nop 0
	v_mul_f32_e32 v113, 0x3f317218, v113
	v_cndmask_b32_e64 v112, v113, -v112, vcc
	v_sub_f32_e32 v112, -0.5, v112
	v_mul_f32_e32 v112, 0x3fb8aa3b, v112
	v_exp_f32_e32 v122, v112
	v_add_f32_e32 v112, v115, v123
	v_mul_f32_e32 v113, 0xbfb8aa3b, v112
	v_exp_f32_e32 v113, v113
	v_cmp_gt_f32_e32 vcc, s22, v112
	v_add_f32_e32 v113, 1.0, v113
	v_log_f32_e32 v113, v113
	s_nop 0
	v_mul_f32_e32 v113, 0x3f317218, v113
	v_cndmask_b32_e64 v112, v113, -v112, vcc
	v_sub_f32_e32 v112, -0.5, v112
	v_mul_f32_e32 v112, 0x3fb8aa3b, v112
	v_exp_f32_e32 v115, v112
	v_cvt_pk_f16_f32 v112, v116, v117
	v_cvt_pk_f16_f32 v113, v118, v119
	v_cvt_pk_f16_f32 v115, v122, v115
	global_store_dwordx4 v[126:127], v[112:115], off offset:256
	s_nop 0
	s_nop 0
	v_mad_i64_i32 v[112:113], s[20:21], v147, s50, 0
	s_nop 0
	s_nop 1
	v_mov_b32_e32 v116, v160
	v_mov_b32_e32 v117, v161
	v_mov_b32_e32 v118, v162
	v_mov_b32_e32 v119, v163
	s_nop 1
	v_mov_b32_e32 v120, v164
	v_mov_b32_e32 v121, v165
	v_mov_b32_e32 v122, v166
	v_mov_b32_e32 v123, v167
	v_add_f32_e32 v104, v104, v116
	s_nop 0
	v_add_f32_e32 v108, v108, v120
	v_mul_f32_e32 v114, 0xbfb8aa3b, v108
	v_exp_f32_e32 v114, v114
	v_cmp_gt_f32_e32 vcc, s22, v108
	v_add_f32_e32 v105, v105, v117
	v_add_f32_e32 v106, v106, v118
	v_add_f32_e32 v114, 1.0, v114
	v_log_f32_e32 v114, v114
	v_add_f32_e32 v107, v107, v119
	v_mul_f32_e32 v114, 0x3f317218, v114
	v_cndmask_b32_e64 v108, v114, -v108, vcc
	v_sub_f32_e32 v108, -0.5, v108
	v_mul_f32_e32 v108, 0x3fb8aa3b, v108
	v_exp_f32_e32 v114, v108
	v_add_f32_e32 v108, v109, v121
	v_mul_f32_e32 v109, 0xbfb8aa3b, v108
	v_exp_f32_e32 v109, v109
	v_cmp_gt_f32_e32 vcc, s22, v108
	v_add_f32_e32 v109, 1.0, v109
	v_log_f32_e32 v109, v109
	s_nop 0
	v_mul_f32_e32 v109, 0x3f317218, v109
	v_cndmask_b32_e64 v108, v109, -v108, vcc
	v_sub_f32_e32 v108, -0.5, v108
	v_mul_f32_e32 v108, 0x3fb8aa3b, v108
	v_exp_f32_e32 v115, v108
	v_add_f32_e32 v108, v110, v122
	v_mul_f32_e32 v109, 0xbfb8aa3b, v108
	v_exp_f32_e32 v109, v109
	v_cmp_gt_f32_e32 vcc, s22, v108
	v_add_f32_e32 v109, 1.0, v109
	v_log_f32_e32 v109, v109
	s_nop 0
	v_mul_f32_e32 v109, 0x3f317218, v109
	v_cndmask_b32_e64 v108, v109, -v108, vcc
	v_sub_f32_e32 v108, -0.5, v108
	v_mul_f32_e32 v108, 0x3fb8aa3b, v108
	v_exp_f32_e32 v110, v108
	v_add_f32_e32 v108, v111, v123
	v_mul_f32_e32 v109, 0xbfb8aa3b, v108
	v_exp_f32_e32 v109, v109
	v_cmp_gt_f32_e32 vcc, s22, v108
	v_add_f32_e32 v109, 1.0, v109
	v_log_f32_e32 v109, v109
	s_nop 0
	v_mul_f32_e32 v109, 0x3f317218, v109
	v_cndmask_b32_e64 v108, v109, -v108, vcc
	v_sub_f32_e32 v108, -0.5, v108
	v_mul_f32_e32 v108, 0x3fb8aa3b, v108
	v_exp_f32_e32 v111, v108
	v_mul_f32_e32 v108, 0xbfb8aa3b, v104
	v_exp_f32_e32 v108, v108
	v_cmp_gt_f32_e32 vcc, s22, v104
	v_add_f32_e32 v108, 1.0, v108
	v_log_f32_e32 v108, v108
	s_nop 0
	v_mul_f32_e32 v108, 0x3f317218, v108
	v_cndmask_b32_e64 v104, v108, -v104, vcc
	v_mul_f32_e32 v108, 0xbfb8aa3b, v105
	v_exp_f32_e32 v108, v108
	v_cmp_gt_f32_e32 vcc, s22, v105
	v_sub_f32_e32 v104, -0.5, v104
	v_mul_f32_e32 v104, 0x3fb8aa3b, v104
	v_add_f32_e32 v108, 1.0, v108
	v_log_f32_e32 v108, v108
	v_exp_f32_e32 v104, v104
	v_mul_f32_e32 v108, 0x3f317218, v108
	v_cndmask_b32_e64 v105, v108, -v105, vcc
	v_mul_f32_e32 v108, 0xbfb8aa3b, v106
	v_exp_f32_e32 v108, v108
	v_cmp_gt_f32_e32 vcc, s22, v106
	v_sub_f32_e32 v105, -0.5, v105
	v_mul_f32_e32 v105, 0x3fb8aa3b, v105
	v_add_f32_e32 v108, 1.0, v108
	v_log_f32_e32 v108, v108
	v_exp_f32_e32 v105, v105
	v_mul_f32_e32 v108, 0x3f317218, v108
	v_cndmask_b32_e64 v106, v108, -v106, vcc
	v_mul_f32_e32 v108, 0xbfb8aa3b, v107
	v_exp_f32_e32 v108, v108
	v_cmp_gt_f32_e32 vcc, s22, v107
	v_sub_f32_e32 v106, -0.5, v106
	v_mul_f32_e32 v106, 0x3fb8aa3b, v106
	v_add_f32_e32 v108, 1.0, v108
	v_log_f32_e32 v108, v108
	v_exp_f32_e32 v106, v106
	v_mul_f32_e32 v108, 0x3f317218, v108
	v_cndmask_b32_e64 v107, v108, -v107, vcc
	v_sub_f32_e32 v107, -0.5, v107
	v_mul_f32_e32 v107, 0x3fb8aa3b, v107
	v_exp_f32_e32 v107, v107
	v_lshl_add_u64 v[108:109], v[112:113], 1, v[136:137]
	v_cvt_pk_f16_f32 v112, v114, v115
	v_cvt_pk_f16_f32 v113, v110, v111
	v_cvt_pk_f16_f32 v114, v104, v105
	v_cvt_pk_f16_f32 v115, v106, v107
	global_store_dwordx4 v[108:109], v[112:115], off
	s_nop 0
	s_nop 0
	s_nop 0
	s_nop 0
	s_nop 1
	v_mov_b32_e32 v104, v168
	v_mov_b32_e32 v105, v169
	v_mov_b32_e32 v106, v170
	v_mov_b32_e32 v107, v171
	s_nop 1
	v_mov_b32_e32 v110, v172
	v_mov_b32_e32 v111, v173
	v_mov_b32_e32 v112, v174
	v_mov_b32_e32 v113, v175
	v_add_f32_e32 v96, v96, v104
	s_nop 0
	v_add_f32_e32 v100, v100, v110
	v_mul_f32_e32 v110, 0xbfb8aa3b, v100
	v_exp_f32_e32 v110, v110
; __device__ __forceinline__ unsigned cvt_pk_bf16(float lo, float hi) { f32x2 v = {lo, hi}; bf16v2_t r = __builtin_convertvector(v, bf16v2_t); return __builtin_bit_cast(unsigned, r); }
; __device__ __forceinline__ float fexp(float x) { return __builtin_amdgcn_exp2f(x * 1.44269504089f); }
; __device__ __forceinline__ float fsigmoid(float x) { return __builtin_amdgcn_rcpf(1.0f + fexp(-x)); }
;     template <int KIND>
;     __device__ __forceinline__ void run(const f32x4 (&acc)[2][2][4][2], const UnitG& u, int wr, int wc, int fr, int fq) const {
;     ...
;                     } else if (KIND == 4) {
;                         const int c = u.x1 * 256 + bj * 128 + col0;
; #pragma unroll
;                         for (int e = 0; e < 8; ++e) { const float xx = -(v[e] + b0[c + e]); const float sp = (xx > 15.f) ? xx : __builtin_amdgcn_logf(1.0f + fexp(xx)) * 0.69314718056f; v[e] = fexp(-sp - 0.5f); }
;                     } else if (KIND == 5) {
;                         const int c = u.x1 * 256 + bj * 128 + col0 - 1024;
; #pragma unroll
;                         for (int e = 0; e < 8; ++e) v[e] = fsigmoid(v[e] + b1[c + e]);
;                     }
;                     if (KIND == 4 || KIND == 5) { w.x = pkh2(v[0], v[1]); w.y = pkh2(v[2], v[3]); w.z = pkh2(v[4], v[5]); w.w = pkh2(v[6], v[7]); }
;                     else { w.x = cvt_pk_bf16(v[0], v[1]); w.y = cvt_pk_bf16(v[2], v[3]); w.z = cvt_pk_bf16(v[4], v[5]); w.w = cvt_pk_bf16(v[6], v[7]); }
;                     *(v4u*)dst = w; }
	v_cmp_gt_f32_e32 vcc, s22, v100
	v_add_f32_e32 v101, v101, v111
	v_add_f32_e32 v102, v102, v112
	v_add_f32_e32 v110, 1.0, v110
	v_log_f32_e32 v110, v110
	v_add_f32_e32 v103, v103, v113
	v_mul_f32_e32 v104, 0xbfb8aa3b, v96
	v_exp_f32_e32 v104, v104
	v_mul_f32_e32 v110, 0x3f317218, v110
	v_cndmask_b32_e64 v100, v110, -v100, vcc
	v_mul_f32_e32 v110, 0xbfb8aa3b, v101
	v_exp_f32_e32 v110, v110
	v_cmp_gt_f32_e32 vcc, s22, v101
	v_add_f32_e32 v104, 1.0, v104
	v_log_f32_e32 v104, v104
	v_add_f32_e32 v110, 1.0, v110
	v_log_f32_e32 v110, v110
	v_sub_f32_e32 v100, -0.5, v100
	v_mul_f32_e32 v104, 0x3f317218, v104
	v_mul_f32_e32 v100, 0x3fb8aa3b, v100
	v_mul_f32_e32 v110, 0x3f317218, v110
	v_cndmask_b32_e64 v101, v110, -v101, vcc
	v_mul_f32_e32 v110, 0xbfb8aa3b, v102
	v_exp_f32_e32 v110, v110
	v_cmp_gt_f32_e32 vcc, s22, v102
	v_sub_f32_e32 v101, -0.5, v101
	v_mul_f32_e32 v101, 0x3fb8aa3b, v101
	v_add_f32_e32 v110, 1.0, v110
	v_log_f32_e32 v110, v110
	v_exp_f32_e32 v100, v100
	v_exp_f32_e32 v101, v101
	v_mul_f32_e32 v110, 0x3f317218, v110
	v_cndmask_b32_e64 v102, v110, -v102, vcc
	v_mul_f32_e32 v110, 0xbfb8aa3b, v103
	v_exp_f32_e32 v110, v110
	v_cmp_gt_f32_e32 vcc, s22, v103
	v_sub_f32_e32 v102, -0.5, v102
	v_mul_f32_e32 v102, 0x3fb8aa3b, v102
	v_add_f32_e32 v110, 1.0, v110
	v_log_f32_e32 v110, v110
	v_exp_f32_e32 v102, v102
	v_mul_f32_e32 v110, 0x3f317218, v110
	v_cndmask_b32_e64 v103, v110, -v103, vcc
	v_cmp_gt_f32_e32 vcc, s22, v96
	v_sub_f32_e32 v103, -0.5, v103
	v_mul_f32_e32 v103, 0x3fb8aa3b, v103
	v_cndmask_b32_e64 v96, v104, -v96, vcc
	v_sub_f32_e32 v96, -0.5, v96
	v_mul_f32_e32 v96, 0x3fb8aa3b, v96
	v_exp_f32_e32 v104, v96
	v_add_f32_e32 v96, v97, v105
	v_mul_f32_e32 v97, 0xbfb8aa3b, v96
	v_exp_f32_e32 v97, v97
	v_cmp_gt_f32_e32 vcc, s22, v96
	v_exp_f32_e32 v103, v103
	v_add_f32_e32 v97, 1.0, v97
	v_log_f32_e32 v97, v97
	s_nop 0
	v_mul_f32_e32 v97, 0x3f317218, v97
	v_cndmask_b32_e64 v96, v97, -v96, vcc
	v_sub_f32_e32 v96, -0.5, v96
	v_mul_f32_e32 v96, 0x3fb8aa3b, v96
	v_exp_f32_e32 v105, v96
	v_add_f32_e32 v96, v98, v106
	v_mul_f32_e32 v97, 0xbfb8aa3b, v96
	v_exp_f32_e32 v97, v97
	v_cmp_gt_f32_e32 vcc, s22, v96
	v_cvt_pk_f16_f32 v98, v104, v105
	v_add_f32_e32 v97, 1.0, v97
	v_log_f32_e32 v97, v97
	s_nop 0
	v_mul_f32_e32 v97, 0x3f317218, v97
	v_cndmask_b32_e64 v96, v97, -v96, vcc
	v_sub_f32_e32 v96, -0.5, v96
	v_mul_f32_e32 v96, 0x3fb8aa3b, v96
	v_exp_f32_e32 v106, v96
	v_add_f32_e32 v96, v99, v107
	v_mul_f32_e32 v97, 0xbfb8aa3b, v96
	v_exp_f32_e32 v97, v97
	v_cmp_gt_f32_e32 vcc, s22, v96
	v_add_f32_e32 v97, 1.0, v97
	v_log_f32_e32 v97, v97
	s_nop 0
	v_mul_f32_e32 v97, 0x3f317218, v97
	v_cndmask_b32_e64 v96, v97, -v96, vcc
	v_sub_f32_e32 v96, -0.5, v96
	v_mul_f32_e32 v96, 0x3fb8aa3b, v96
	v_exp_f32_e32 v99, v96
	v_cvt_pk_f16_f32 v96, v100, v101
	v_cvt_pk_f16_f32 v97, v102, v103
	v_cvt_pk_f16_f32 v99, v106, v99
	global_store_dwordx4 v[108:109], v[96:99], off offset:256
	s_nop 0
	s_nop 0
	v_mad_i64_i32 v[96:97], s[20:21], v145, s50, 0
	s_nop 0
	s_nop 1
	v_mov_b32_e32 v100, v160
	v_mov_b32_e32 v101, v161
	v_mov_b32_e32 v102, v162
	v_mov_b32_e32 v103, v163
	s_nop 1
	v_mov_b32_e32 v104, v164
	v_mov_b32_e32 v105, v165
	v_mov_b32_e32 v106, v166
	v_mov_b32_e32 v107, v167
	v_add_f32_e32 v88, v88, v100
	s_nop 0
	v_add_f32_e32 v92, v92, v104
	v_mul_f32_e32 v98, 0xbfb8aa3b, v92
	v_exp_f32_e32 v98, v98
	v_cmp_gt_f32_e32 vcc, s22, v92
	v_add_f32_e32 v89, v89, v101
	v_add_f32_e32 v90, v90, v102
	v_add_f32_e32 v98, 1.0, v98
	v_log_f32_e32 v98, v98
	v_add_f32_e32 v91, v91, v103
	v_mul_f32_e32 v98, 0x3f317218, v98
	v_cndmask_b32_e64 v92, v98, -v92, vcc
	v_sub_f32_e32 v92, -0.5, v92
	v_mul_f32_e32 v92, 0x3fb8aa3b, v92
	v_exp_f32_e32 v98, v92
	v_add_f32_e32 v92, v93, v105
	v_mul_f32_e32 v93, 0xbfb8aa3b, v92
	v_exp_f32_e32 v93, v93
	v_cmp_gt_f32_e32 vcc, s22, v92
	v_add_f32_e32 v93, 1.0, v93
	v_log_f32_e32 v93, v93
	s_nop 0
	v_mul_f32_e32 v93, 0x3f317218, v93
	v_cndmask_b32_e64 v92, v93, -v92, vcc
	v_sub_f32_e32 v92, -0.5, v92
	v_mul_f32_e32 v92, 0x3fb8aa3b, v92
	v_exp_f32_e32 v99, v92
	v_add_f32_e32 v92, v94, v106
	v_mul_f32_e32 v93, 0xbfb8aa3b, v92
	v_exp_f32_e32 v93, v93
	v_cmp_gt_f32_e32 vcc, s22, v92
	v_add_f32_e32 v93, 1.0, v93
	v_log_f32_e32 v93, v93
	s_nop 0
	v_mul_f32_e32 v93, 0x3f317218, v93
	v_cndmask_b32_e64 v92, v93, -v92, vcc
	v_sub_f32_e32 v92, -0.5, v92
	v_mul_f32_e32 v92, 0x3fb8aa3b, v92
	v_exp_f32_e32 v94, v92
	v_add_f32_e32 v92, v95, v107
	v_mul_f32_e32 v93, 0xbfb8aa3b, v92
	v_exp_f32_e32 v93, v93
	v_cmp_gt_f32_e32 vcc, s22, v92
	v_add_f32_e32 v93, 1.0, v93
	v_log_f32_e32 v93, v93
	s_nop 0
	v_mul_f32_e32 v93, 0x3f317218, v93
	v_cndmask_b32_e64 v92, v93, -v92, vcc
	v_sub_f32_e32 v92, -0.5, v92
	v_mul_f32_e32 v92, 0x3fb8aa3b, v92
	v_exp_f32_e32 v95, v92
	v_mul_f32_e32 v92, 0xbfb8aa3b, v88
	v_exp_f32_e32 v92, v92
	v_cmp_gt_f32_e32 vcc, s22, v88
	v_add_f32_e32 v92, 1.0, v92
	v_log_f32_e32 v92, v92
	s_nop 0
	v_mul_f32_e32 v92, 0x3f317218, v92
	v_cndmask_b32_e64 v88, v92, -v88, vcc
	v_mul_f32_e32 v92, 0xbfb8aa3b, v89
	v_exp_f32_e32 v92, v92
	v_cmp_gt_f32_e32 vcc, s22, v89
	v_sub_f32_e32 v88, -0.5, v88
	v_mul_f32_e32 v88, 0x3fb8aa3b, v88
	v_add_f32_e32 v92, 1.0, v92
	v_log_f32_e32 v92, v92
	v_exp_f32_e32 v88, v88
	v_mul_f32_e32 v92, 0x3f317218, v92
	v_cndmask_b32_e64 v89, v92, -v89, vcc
	v_mul_f32_e32 v92, 0xbfb8aa3b, v90
	v_exp_f32_e32 v92, v92
	v_cmp_gt_f32_e32 vcc, s22, v90
	v_sub_f32_e32 v89, -0.5, v89
	v_mul_f32_e32 v89, 0x3fb8aa3b, v89
	v_add_f32_e32 v92, 1.0, v92
	v_log_f32_e32 v92, v92
	v_exp_f32_e32 v89, v89
	v_mul_f32_e32 v92, 0x3f317218, v92
	v_cndmask_b32_e64 v90, v92, -v90, vcc
	v_mul_f32_e32 v92, 0xbfb8aa3b, v91
	v_exp_f32_e32 v92, v92
; __device__ __forceinline__ unsigned cvt_pk_bf16(float lo, float hi) { f32x2 v = {lo, hi}; bf16v2_t r = __builtin_convertvector(v, bf16v2_t); return __builtin_bit_cast(unsigned, r); }
; __device__ __forceinline__ float fexp(float x) { return __builtin_amdgcn_exp2f(x * 1.44269504089f); }
; __device__ __forceinline__ float fsigmoid(float x) { return __builtin_amdgcn_rcpf(1.0f + fexp(-x)); }
;     template <int KIND>
;     __device__ __forceinline__ void run(const f32x4 (&acc)[2][2][4][2], const UnitG& u, int wr, int wc, int fr, int fq) const {
;     ...
;                     } else if (KIND == 4) {
;                         const int c = u.x1 * 256 + bj * 128 + col0;
; #pragma unroll
;                         for (int e = 0; e < 8; ++e) { const float xx = -(v[e] + b0[c + e]); const float sp = (xx > 15.f) ? xx : __builtin_amdgcn_logf(1.0f + fexp(xx)) * 0.69314718056f; v[e] = fexp(-sp - 0.5f); }
;                     } else if (KIND == 5) {
;                         const int c = u.x1 * 256 + bj * 128 + col0 - 1024;
; #pragma unroll
;                         for (int e = 0; e < 8; ++e) v[e] = fsigmoid(v[e] + b1[c + e]);
;                     }
;                     if (KIND == 4 || KIND == 5) { w.x = pkh2(v[0], v[1]); w.y = pkh2(v[2], v[3]); w.z = pkh2(v[4], v[5]); w.w = pkh2(v[6], v[7]); }
;                     else { w.x = cvt_pk_bf16(v[0], v[1]); w.y = cvt_pk_bf16(v[2], v[3]); w.z = cvt_pk_bf16(v[4], v[5]); w.w = cvt_pk_bf16(v[6], v[7]); }
;                     *(v4u*)dst = w; }
	v_cmp_gt_f32_e32 vcc, s22, v91
	v_sub_f32_e32 v90, -0.5, v90
	v_mul_f32_e32 v90, 0x3fb8aa3b, v90
	v_add_f32_e32 v92, 1.0, v92
	v_log_f32_e32 v92, v92
	v_exp_f32_e32 v90, v90
	v_mul_f32_e32 v92, 0x3f317218, v92
	v_cndmask_b32_e64 v91, v92, -v91, vcc
	v_sub_f32_e32 v91, -0.5, v91
	v_mul_f32_e32 v91, 0x3fb8aa3b, v91
	v_exp_f32_e32 v91, v91
	v_lshl_add_u64 v[92:93], v[96:97], 1, v[136:137]
	v_cvt_pk_f16_f32 v96, v98, v99
	v_cvt_pk_f16_f32 v97, v94, v95
	v_cvt_pk_f16_f32 v98, v88, v89
	v_cvt_pk_f16_f32 v99, v90, v91
	global_store_dwordx4 v[92:93], v[96:99], off
	s_nop 0
	s_nop 0
	s_nop 0
	s_nop 0
	s_nop 1
	v_mov_b32_e32 v88, v168
	v_mov_b32_e32 v89, v169
	v_mov_b32_e32 v90, v170
	v_mov_b32_e32 v91, v171
	s_nop 1
	v_mov_b32_e32 v94, v172
	v_mov_b32_e32 v95, v173
	v_mov_b32_e32 v96, v174
	v_mov_b32_e32 v97, v175
	v_add_f32_e32 v80, v80, v88
	s_nop 0
	v_add_f32_e32 v84, v84, v94
	v_mul_f32_e32 v94, 0xbfb8aa3b, v84
	v_exp_f32_e32 v94, v94
	v_cmp_gt_f32_e32 vcc, s22, v84
	v_add_f32_e32 v85, v85, v95
	v_add_f32_e32 v86, v86, v96
	v_add_f32_e32 v94, 1.0, v94
	v_log_f32_e32 v94, v94
	v_add_f32_e32 v87, v87, v97
	v_mul_f32_e32 v88, 0xbfb8aa3b, v80
	v_exp_f32_e32 v88, v88
	v_mul_f32_e32 v94, 0x3f317218, v94
	v_cndmask_b32_e64 v84, v94, -v84, vcc
	v_mul_f32_e32 v94, 0xbfb8aa3b, v85
	v_exp_f32_e32 v94, v94
	v_cmp_gt_f32_e32 vcc, s22, v85
	v_add_f32_e32 v88, 1.0, v88
	v_log_f32_e32 v88, v88
	v_add_f32_e32 v94, 1.0, v94
	v_log_f32_e32 v94, v94
	v_sub_f32_e32 v84, -0.5, v84
	v_mul_f32_e32 v88, 0x3f317218, v88
	v_mul_f32_e32 v84, 0x3fb8aa3b, v84
	v_mul_f32_e32 v94, 0x3f317218, v94
	v_cndmask_b32_e64 v85, v94, -v85, vcc
	v_mul_f32_e32 v94, 0xbfb8aa3b, v86
	v_exp_f32_e32 v94, v94
	v_cmp_gt_f32_e32 vcc, s22, v86
	v_sub_f32_e32 v85, -0.5, v85
	v_mul_f32_e32 v85, 0x3fb8aa3b, v85
	v_add_f32_e32 v94, 1.0, v94
	v_log_f32_e32 v94, v94
	v_exp_f32_e32 v84, v84
	v_exp_f32_e32 v85, v85
	v_mul_f32_e32 v94, 0x3f317218, v94
	v_cndmask_b32_e64 v86, v94, -v86, vcc
	v_mul_f32_e32 v94, 0xbfb8aa3b, v87
	v_exp_f32_e32 v94, v94
	v_cmp_gt_f32_e32 vcc, s22, v87
	v_sub_f32_e32 v86, -0.5, v86
	v_mul_f32_e32 v86, 0x3fb8aa3b, v86
	v_add_f32_e32 v94, 1.0, v94
	v_log_f32_e32 v94, v94
	v_exp_f32_e32 v86, v86
	v_mul_f32_e32 v94, 0x3f317218, v94
	v_cndmask_b32_e64 v87, v94, -v87, vcc
	v_cmp_gt_f32_e32 vcc, s22, v80
	v_sub_f32_e32 v87, -0.5, v87
	v_mul_f32_e32 v87, 0x3fb8aa3b, v87
	v_cndmask_b32_e64 v80, v88, -v80, vcc
	v_sub_f32_e32 v80, -0.5, v80
	v_mul_f32_e32 v80, 0x3fb8aa3b, v80
	v_exp_f32_e32 v88, v80
	v_add_f32_e32 v80, v81, v89
	v_mul_f32_e32 v81, 0xbfb8aa3b, v80
	v_exp_f32_e32 v81, v81
	v_cmp_gt_f32_e32 vcc, s22, v80
	v_exp_f32_e32 v87, v87
	v_add_f32_e32 v81, 1.0, v81
	v_log_f32_e32 v81, v81
	s_nop 0
	v_mul_f32_e32 v81, 0x3f317218, v81
	v_cndmask_b32_e64 v80, v81, -v80, vcc
	v_sub_f32_e32 v80, -0.5, v80
	v_mul_f32_e32 v80, 0x3fb8aa3b, v80
	v_exp_f32_e32 v89, v80
	v_add_f32_e32 v80, v82, v90
	v_mul_f32_e32 v81, 0xbfb8aa3b, v80
	v_exp_f32_e32 v81, v81
	v_cmp_gt_f32_e32 vcc, s22, v80
	v_cvt_pk_f16_f32 v82, v88, v89
	v_add_f32_e32 v81, 1.0, v81
	v_log_f32_e32 v81, v81
	s_nop 0
	v_mul_f32_e32 v81, 0x3f317218, v81
	v_cndmask_b32_e64 v80, v81, -v80, vcc
	v_sub_f32_e32 v80, -0.5, v80
	v_mul_f32_e32 v80, 0x3fb8aa3b, v80
	v_exp_f32_e32 v90, v80
	v_add_f32_e32 v80, v83, v91
	v_mul_f32_e32 v81, 0xbfb8aa3b, v80
	v_exp_f32_e32 v81, v81
	v_cmp_gt_f32_e32 vcc, s22, v80
	v_add_f32_e32 v81, 1.0, v81
	v_log_f32_e32 v81, v81
	s_nop 0
	v_mul_f32_e32 v81, 0x3f317218, v81
	v_cndmask_b32_e64 v80, v81, -v80, vcc
	v_sub_f32_e32 v80, -0.5, v80
	v_mul_f32_e32 v80, 0x3fb8aa3b, v80
	v_exp_f32_e32 v83, v80
	v_cvt_pk_f16_f32 v80, v84, v85
	v_cvt_pk_f16_f32 v81, v86, v87
	v_cvt_pk_f16_f32 v83, v90, v83
	global_store_dwordx4 v[92:93], v[80:83], off offset:256
	s_nop 0
	s_nop 0
	v_mad_i64_i32 v[80:81], s[20:21], v144, s50, 0
	s_nop 0
	s_nop 1
	v_mov_b32_e32 v84, v160
	v_mov_b32_e32 v85, v161
	v_mov_b32_e32 v86, v162
	v_mov_b32_e32 v87, v163
	s_nop 1
	v_mov_b32_e32 v88, v164
	v_mov_b32_e32 v89, v165
	v_mov_b32_e32 v90, v166
	v_mov_b32_e32 v91, v167
	v_add_f32_e32 v72, v72, v84
	s_nop 0
	v_add_f32_e32 v76, v76, v88
	v_mul_f32_e32 v82, 0xbfb8aa3b, v76
	v_exp_f32_e32 v82, v82
	v_cmp_gt_f32_e32 vcc, s22, v76
	v_add_f32_e32 v73, v73, v85
	v_add_f32_e32 v74, v74, v86
	v_add_f32_e32 v82, 1.0, v82
	v_log_f32_e32 v82, v82
	v_add_f32_e32 v75, v75, v87
	v_mul_f32_e32 v82, 0x3f317218, v82
	v_cndmask_b32_e64 v76, v82, -v76, vcc
	v_sub_f32_e32 v76, -0.5, v76
	v_mul_f32_e32 v76, 0x3fb8aa3b, v76
	v_exp_f32_e32 v82, v76
	v_add_f32_e32 v76, v77, v89
	v_mul_f32_e32 v77, 0xbfb8aa3b, v76
	v_exp_f32_e32 v77, v77
	v_cmp_gt_f32_e32 vcc, s22, v76
	v_add_f32_e32 v77, 1.0, v77
	v_log_f32_e32 v77, v77
	s_nop 0
	v_mul_f32_e32 v77, 0x3f317218, v77
	v_cndmask_b32_e64 v76, v77, -v76, vcc
	v_sub_f32_e32 v76, -0.5, v76
	v_mul_f32_e32 v76, 0x3fb8aa3b, v76
	v_exp_f32_e32 v83, v76
	v_add_f32_e32 v76, v78, v90
	v_mul_f32_e32 v77, 0xbfb8aa3b, v76
	v_exp_f32_e32 v77, v77
	v_cmp_gt_f32_e32 vcc, s22, v76
	v_add_f32_e32 v77, 1.0, v77
	v_log_f32_e32 v77, v77
	s_nop 0
	v_mul_f32_e32 v77, 0x3f317218, v77
	v_cndmask_b32_e64 v76, v77, -v76, vcc
	v_sub_f32_e32 v76, -0.5, v76
	v_mul_f32_e32 v76, 0x3fb8aa3b, v76
	v_exp_f32_e32 v78, v76
	v_add_f32_e32 v76, v79, v91
	v_mul_f32_e32 v77, 0xbfb8aa3b, v76
	v_exp_f32_e32 v77, v77
	v_cmp_gt_f32_e32 vcc, s22, v76
	v_add_f32_e32 v77, 1.0, v77
	v_log_f32_e32 v77, v77
	s_nop 0
	v_mul_f32_e32 v77, 0x3f317218, v77
	v_cndmask_b32_e64 v76, v77, -v76, vcc
	v_sub_f32_e32 v76, -0.5, v76
	v_mul_f32_e32 v76, 0x3fb8aa3b, v76
	v_exp_f32_e32 v79, v76
	v_mul_f32_e32 v76, 0xbfb8aa3b, v72
	v_exp_f32_e32 v76, v76
	v_cmp_gt_f32_e32 vcc, s22, v72
; __device__ __forceinline__ unsigned cvt_pk_bf16(float lo, float hi) { f32x2 v = {lo, hi}; bf16v2_t r = __builtin_convertvector(v, bf16v2_t); return __builtin_bit_cast(unsigned, r); }
; __device__ __forceinline__ float fexp(float x) { return __builtin_amdgcn_exp2f(x * 1.44269504089f); }
; __device__ __forceinline__ float fsigmoid(float x) { return __builtin_amdgcn_rcpf(1.0f + fexp(-x)); }
;     template <int KIND>
;     __device__ __forceinline__ void run(const f32x4 (&acc)[2][2][4][2], const UnitG& u, int wr, int wc, int fr, int fq) const {
;     ...
;                     } else if (KIND == 4) {
;                         const int c = u.x1 * 256 + bj * 128 + col0;
; #pragma unroll
;                         for (int e = 0; e < 8; ++e) { const float xx = -(v[e] + b0[c + e]); const float sp = (xx > 15.f) ? xx : __builtin_amdgcn_logf(1.0f + fexp(xx)) * 0.69314718056f; v[e] = fexp(-sp - 0.5f); }
;                     } else if (KIND == 5) {
;                         const int c = u.x1 * 256 + bj * 128 + col0 - 1024;
; #pragma unroll
;                         for (int e = 0; e < 8; ++e) v[e] = fsigmoid(v[e] + b1[c + e]);
;                     }
;                     if (KIND == 4 || KIND == 5) { w.x = pkh2(v[0], v[1]); w.y = pkh2(v[2], v[3]); w.z = pkh2(v[4], v[5]); w.w = pkh2(v[6], v[7]); }
;                     else { w.x = cvt_pk_bf16(v[0], v[1]); w.y = cvt_pk_bf16(v[2], v[3]); w.z = cvt_pk_bf16(v[4], v[5]); w.w = cvt_pk_bf16(v[6], v[7]); }
;                     *(v4u*)dst = w; }
	v_add_f32_e32 v76, 1.0, v76
	v_log_f32_e32 v76, v76
	s_nop 0
	v_mul_f32_e32 v76, 0x3f317218, v76
	v_cndmask_b32_e64 v72, v76, -v72, vcc
	v_mul_f32_e32 v76, 0xbfb8aa3b, v73
	v_exp_f32_e32 v76, v76
	v_cmp_gt_f32_e32 vcc, s22, v73
	v_sub_f32_e32 v72, -0.5, v72
	v_mul_f32_e32 v72, 0x3fb8aa3b, v72
	v_add_f32_e32 v76, 1.0, v76
	v_log_f32_e32 v76, v76
	v_exp_f32_e32 v72, v72
	v_mul_f32_e32 v76, 0x3f317218, v76
	v_cndmask_b32_e64 v73, v76, -v73, vcc
	v_mul_f32_e32 v76, 0xbfb8aa3b, v74
	v_exp_f32_e32 v76, v76
	v_cmp_gt_f32_e32 vcc, s22, v74
	v_sub_f32_e32 v73, -0.5, v73
	v_mul_f32_e32 v73, 0x3fb8aa3b, v73
	v_add_f32_e32 v76, 1.0, v76
	v_log_f32_e32 v76, v76
	v_exp_f32_e32 v73, v73
	v_mul_f32_e32 v76, 0x3f317218, v76
	v_cndmask_b32_e64 v74, v76, -v74, vcc
	v_mul_f32_e32 v76, 0xbfb8aa3b, v75
	v_exp_f32_e32 v76, v76
	v_cmp_gt_f32_e32 vcc, s22, v75
	v_sub_f32_e32 v74, -0.5, v74
	v_mul_f32_e32 v74, 0x3fb8aa3b, v74
	v_add_f32_e32 v76, 1.0, v76
	v_log_f32_e32 v76, v76
	v_exp_f32_e32 v74, v74
	v_mul_f32_e32 v76, 0x3f317218, v76
	v_cndmask_b32_e64 v75, v76, -v75, vcc
	v_sub_f32_e32 v75, -0.5, v75
	v_mul_f32_e32 v75, 0x3fb8aa3b, v75
	v_exp_f32_e32 v75, v75
	v_lshl_add_u64 v[76:77], v[80:81], 1, v[136:137]
	v_cvt_pk_f16_f32 v80, v82, v83
	v_cvt_pk_f16_f32 v81, v78, v79
	v_cvt_pk_f16_f32 v82, v72, v73
	v_cvt_pk_f16_f32 v83, v74, v75
	global_store_dwordx4 v[76:77], v[80:83], off
	s_nop 0
	s_nop 0
	s_nop 0
	s_nop 0
	s_nop 1
	v_mov_b32_e32 v72, v168
	v_mov_b32_e32 v73, v169
	v_mov_b32_e32 v74, v170
	v_mov_b32_e32 v75, v171
	s_nop 1
	v_mov_b32_e32 v78, v172
	v_mov_b32_e32 v79, v173
	v_mov_b32_e32 v80, v174
	v_mov_b32_e32 v81, v175
	v_add_f32_e32 v64, v64, v72
	s_nop 0
	v_add_f32_e32 v68, v68, v78
	v_mul_f32_e32 v78, 0xbfb8aa3b, v68
	v_exp_f32_e32 v78, v78
	v_cmp_gt_f32_e32 vcc, s22, v68
	v_add_f32_e32 v69, v69, v79
	v_add_f32_e32 v70, v70, v80
	v_add_f32_e32 v78, 1.0, v78
	v_log_f32_e32 v78, v78
	v_add_f32_e32 v71, v71, v81
	v_mul_f32_e32 v72, 0xbfb8aa3b, v64
	v_exp_f32_e32 v72, v72
	v_mul_f32_e32 v78, 0x3f317218, v78
	v_cndmask_b32_e64 v68, v78, -v68, vcc
	v_mul_f32_e32 v78, 0xbfb8aa3b, v69
	v_exp_f32_e32 v78, v78
	v_cmp_gt_f32_e32 vcc, s22, v69
	v_add_f32_e32 v72, 1.0, v72
	v_log_f32_e32 v72, v72
	v_add_f32_e32 v78, 1.0, v78
	v_log_f32_e32 v78, v78
	v_sub_f32_e32 v68, -0.5, v68
	v_mul_f32_e32 v72, 0x3f317218, v72
	v_mul_f32_e32 v68, 0x3fb8aa3b, v68
	v_mul_f32_e32 v78, 0x3f317218, v78
	v_cndmask_b32_e64 v69, v78, -v69, vcc
	v_mul_f32_e32 v78, 0xbfb8aa3b, v70
	v_exp_f32_e32 v78, v78
	v_cmp_gt_f32_e32 vcc, s22, v70
	v_sub_f32_e32 v69, -0.5, v69
	v_mul_f32_e32 v69, 0x3fb8aa3b, v69
	v_add_f32_e32 v78, 1.0, v78
	v_log_f32_e32 v78, v78
	v_exp_f32_e32 v68, v68
	v_exp_f32_e32 v69, v69
	v_mul_f32_e32 v78, 0x3f317218, v78
	v_cndmask_b32_e64 v70, v78, -v70, vcc
	v_mul_f32_e32 v78, 0xbfb8aa3b, v71
	v_exp_f32_e32 v78, v78
	v_cmp_gt_f32_e32 vcc, s22, v71
	v_sub_f32_e32 v70, -0.5, v70
	v_mul_f32_e32 v70, 0x3fb8aa3b, v70
	v_add_f32_e32 v78, 1.0, v78
	v_log_f32_e32 v78, v78
	v_exp_f32_e32 v70, v70
	v_mul_f32_e32 v78, 0x3f317218, v78
	v_cndmask_b32_e64 v71, v78, -v71, vcc
	v_cmp_gt_f32_e32 vcc, s22, v64
	v_sub_f32_e32 v71, -0.5, v71
	v_mul_f32_e32 v71, 0x3fb8aa3b, v71
	v_cndmask_b32_e64 v64, v72, -v64, vcc
	v_sub_f32_e32 v64, -0.5, v64
	v_mul_f32_e32 v64, 0x3fb8aa3b, v64
	v_exp_f32_e32 v72, v64
	v_add_f32_e32 v64, v65, v73
	v_mul_f32_e32 v65, 0xbfb8aa3b, v64
	v_exp_f32_e32 v65, v65
	v_cmp_gt_f32_e32 vcc, s22, v64
	v_exp_f32_e32 v71, v71
	v_add_f32_e32 v65, 1.0, v65
	v_log_f32_e32 v65, v65
	s_nop 0
	v_mul_f32_e32 v65, 0x3f317218, v65
	v_cndmask_b32_e64 v64, v65, -v64, vcc
	v_sub_f32_e32 v64, -0.5, v64
	v_mul_f32_e32 v64, 0x3fb8aa3b, v64
	v_exp_f32_e32 v73, v64
	v_add_f32_e32 v64, v66, v74
	v_mul_f32_e32 v65, 0xbfb8aa3b, v64
	v_exp_f32_e32 v65, v65
	v_cmp_gt_f32_e32 vcc, s22, v64
	v_cvt_pk_f16_f32 v66, v72, v73
	v_add_f32_e32 v65, 1.0, v65
	v_log_f32_e32 v65, v65
	s_nop 0
	v_mul_f32_e32 v65, 0x3f317218, v65
	v_cndmask_b32_e64 v64, v65, -v64, vcc
	v_sub_f32_e32 v64, -0.5, v64
	v_mul_f32_e32 v64, 0x3fb8aa3b, v64
	v_exp_f32_e32 v74, v64
	v_add_f32_e32 v64, v67, v75
	v_mul_f32_e32 v65, 0xbfb8aa3b, v64
	v_exp_f32_e32 v65, v65
	v_cmp_gt_f32_e32 vcc, s22, v64
	v_add_f32_e32 v65, 1.0, v65
	v_log_f32_e32 v65, v65
	s_nop 0
	v_mul_f32_e32 v65, 0x3f317218, v65
	v_cndmask_b32_e64 v64, v65, -v64, vcc
	v_sub_f32_e32 v64, -0.5, v64
	v_mul_f32_e32 v64, 0x3fb8aa3b, v64
	v_exp_f32_e32 v67, v64
	v_cvt_pk_f16_f32 v64, v68, v69
	v_cvt_pk_f16_f32 v65, v70, v71
	v_cvt_pk_f16_f32 v67, v74, v67
	global_store_dwordx4 v[76:77], v[64:67], off offset:256
	s_nop 0
	s_nop 0
	v_mad_i64_i32 v[64:65], s[20:21], v143, s50, 0
	s_nop 0
	s_nop 1
	v_mov_b32_e32 v68, v160
	v_mov_b32_e32 v69, v161
	v_mov_b32_e32 v70, v162
	v_mov_b32_e32 v71, v163
	s_nop 1
	v_mov_b32_e32 v72, v164
	v_mov_b32_e32 v73, v165
	v_mov_b32_e32 v74, v166
	v_mov_b32_e32 v75, v167
	v_add_f32_e32 v56, v56, v68
	s_nop 0
	v_add_f32_e32 v60, v60, v72
	v_mul_f32_e32 v66, 0xbfb8aa3b, v60
	v_exp_f32_e32 v66, v66
	v_cmp_gt_f32_e32 vcc, s22, v60
	v_add_f32_e32 v57, v57, v69
	v_add_f32_e32 v58, v58, v70
	v_add_f32_e32 v66, 1.0, v66
	v_log_f32_e32 v66, v66
	v_add_f32_e32 v59, v59, v71
	v_mul_f32_e32 v66, 0x3f317218, v66
	v_cndmask_b32_e64 v60, v66, -v60, vcc
	v_sub_f32_e32 v60, -0.5, v60
	v_mul_f32_e32 v60, 0x3fb8aa3b, v60
	v_exp_f32_e32 v66, v60
	v_add_f32_e32 v60, v61, v73
	v_mul_f32_e32 v61, 0xbfb8aa3b, v60
	v_exp_f32_e32 v61, v61
	v_cmp_gt_f32_e32 vcc, s22, v60
	v_add_f32_e32 v61, 1.0, v61
	v_log_f32_e32 v61, v61
	s_nop 0
	v_mul_f32_e32 v61, 0x3f317218, v61
	v_cndmask_b32_e64 v60, v61, -v60, vcc
	v_sub_f32_e32 v60, -0.5, v60
	v_mul_f32_e32 v60, 0x3fb8aa3b, v60
; __device__ __forceinline__ unsigned cvt_pk_bf16(float lo, float hi) { f32x2 v = {lo, hi}; bf16v2_t r = __builtin_convertvector(v, bf16v2_t); return __builtin_bit_cast(unsigned, r); }
; __device__ __forceinline__ float fexp(float x) { return __builtin_amdgcn_exp2f(x * 1.44269504089f); }
; __device__ __forceinline__ float fsigmoid(float x) { return __builtin_amdgcn_rcpf(1.0f + fexp(-x)); }
;     template <int KIND>
;     __device__ __forceinline__ void run(const f32x4 (&acc)[2][2][4][2], const UnitG& u, int wr, int wc, int fr, int fq) const {
;     ...
;                     } else if (KIND == 4) {
;                         const int c = u.x1 * 256 + bj * 128 + col0;
; #pragma unroll
;                         for (int e = 0; e < 8; ++e) { const float xx = -(v[e] + b0[c + e]); const float sp = (xx > 15.f) ? xx : __builtin_amdgcn_logf(1.0f + fexp(xx)) * 0.69314718056f; v[e] = fexp(-sp - 0.5f); }
;                     } else if (KIND == 5) {
;                         const int c = u.x1 * 256 + bj * 128 + col0 - 1024;
; #pragma unroll
;                         for (int e = 0; e < 8; ++e) v[e] = fsigmoid(v[e] + b1[c + e]);
;                     }
;                     if (KIND == 4 || KIND == 5) { w.x = pkh2(v[0], v[1]); w.y = pkh2(v[2], v[3]); w.z = pkh2(v[4], v[5]); w.w = pkh2(v[6], v[7]); }
;                     else { w.x = cvt_pk_bf16(v[0], v[1]); w.y = cvt_pk_bf16(v[2], v[3]); w.z = cvt_pk_bf16(v[4], v[5]); w.w = cvt_pk_bf16(v[6], v[7]); }
;                     *(v4u*)dst = w; }
	v_exp_f32_e32 v67, v60
	v_add_f32_e32 v60, v62, v74
	v_mul_f32_e32 v61, 0xbfb8aa3b, v60
	v_exp_f32_e32 v61, v61
	v_cmp_gt_f32_e32 vcc, s22, v60
	v_add_f32_e32 v61, 1.0, v61
	v_log_f32_e32 v61, v61
	s_nop 0
	v_mul_f32_e32 v61, 0x3f317218, v61
	v_cndmask_b32_e64 v60, v61, -v60, vcc
	v_sub_f32_e32 v60, -0.5, v60
	v_mul_f32_e32 v60, 0x3fb8aa3b, v60
	v_exp_f32_e32 v62, v60
	v_add_f32_e32 v60, v63, v75
	v_mul_f32_e32 v61, 0xbfb8aa3b, v60
	v_exp_f32_e32 v61, v61
	v_cmp_gt_f32_e32 vcc, s22, v60
	v_add_f32_e32 v61, 1.0, v61
	v_log_f32_e32 v61, v61
	s_nop 0
	v_mul_f32_e32 v61, 0x3f317218, v61
	v_cndmask_b32_e64 v60, v61, -v60, vcc
	v_sub_f32_e32 v60, -0.5, v60
	v_mul_f32_e32 v60, 0x3fb8aa3b, v60
	v_exp_f32_e32 v63, v60
	v_mul_f32_e32 v60, 0xbfb8aa3b, v56
	v_exp_f32_e32 v60, v60
	v_cmp_gt_f32_e32 vcc, s22, v56
	v_add_f32_e32 v60, 1.0, v60
	v_log_f32_e32 v60, v60
	s_nop 0
	v_mul_f32_e32 v60, 0x3f317218, v60
	v_cndmask_b32_e64 v56, v60, -v56, vcc
	v_mul_f32_e32 v60, 0xbfb8aa3b, v57
	v_exp_f32_e32 v60, v60
	v_cmp_gt_f32_e32 vcc, s22, v57
	v_sub_f32_e32 v56, -0.5, v56
	v_mul_f32_e32 v56, 0x3fb8aa3b, v56
	v_add_f32_e32 v60, 1.0, v60
	v_log_f32_e32 v60, v60
	v_exp_f32_e32 v56, v56
	v_mul_f32_e32 v60, 0x3f317218, v60
	v_cndmask_b32_e64 v57, v60, -v57, vcc
	v_mul_f32_e32 v60, 0xbfb8aa3b, v58
	v_exp_f32_e32 v60, v60
	v_cmp_gt_f32_e32 vcc, s22, v58
	v_sub_f32_e32 v57, -0.5, v57
	v_mul_f32_e32 v57, 0x3fb8aa3b, v57
	v_add_f32_e32 v60, 1.0, v60
	v_log_f32_e32 v60, v60
	v_exp_f32_e32 v57, v57
	v_mul_f32_e32 v60, 0x3f317218, v60
	v_cndmask_b32_e64 v58, v60, -v58, vcc
	v_mul_f32_e32 v60, 0xbfb8aa3b, v59
	v_exp_f32_e32 v60, v60
	v_cmp_gt_f32_e32 vcc, s22, v59
	v_sub_f32_e32 v58, -0.5, v58
	v_mul_f32_e32 v58, 0x3fb8aa3b, v58
	v_add_f32_e32 v60, 1.0, v60
	v_log_f32_e32 v60, v60
	v_exp_f32_e32 v58, v58
	v_mul_f32_e32 v60, 0x3f317218, v60
	v_cndmask_b32_e64 v59, v60, -v59, vcc
	v_sub_f32_e32 v59, -0.5, v59
	v_mul_f32_e32 v59, 0x3fb8aa3b, v59
	v_exp_f32_e32 v59, v59
	v_lshl_add_u64 v[60:61], v[64:65], 1, v[136:137]
	v_cvt_pk_f16_f32 v64, v66, v67
	v_cvt_pk_f16_f32 v65, v62, v63
	v_cvt_pk_f16_f32 v66, v56, v57
	v_cvt_pk_f16_f32 v67, v58, v59
	global_store_dwordx4 v[60:61], v[64:67], off
	s_nop 0
	s_nop 0
	s_nop 0
	s_nop 0
	s_nop 1
	v_mov_b32_e32 v56, v168
	v_mov_b32_e32 v57, v169
	v_mov_b32_e32 v58, v170
	v_mov_b32_e32 v59, v171
	s_nop 1
	v_mov_b32_e32 v62, v172
	v_mov_b32_e32 v63, v173
	v_mov_b32_e32 v64, v174
	v_mov_b32_e32 v65, v175
	v_add_f32_e32 v48, v48, v56
	s_nop 0
	v_add_f32_e32 v52, v52, v62
	v_mul_f32_e32 v62, 0xbfb8aa3b, v52
	v_exp_f32_e32 v62, v62
	v_cmp_gt_f32_e32 vcc, s22, v52
	v_add_f32_e32 v53, v53, v63
	v_add_f32_e32 v54, v54, v64
	v_add_f32_e32 v62, 1.0, v62
	v_log_f32_e32 v62, v62
	v_add_f32_e32 v55, v55, v65
	v_mul_f32_e32 v56, 0xbfb8aa3b, v48
	v_exp_f32_e32 v56, v56
	v_mul_f32_e32 v62, 0x3f317218, v62
	v_cndmask_b32_e64 v52, v62, -v52, vcc
	v_mul_f32_e32 v62, 0xbfb8aa3b, v53
	v_exp_f32_e32 v62, v62
	v_cmp_gt_f32_e32 vcc, s22, v53
	v_add_f32_e32 v56, 1.0, v56
	v_log_f32_e32 v56, v56
	v_add_f32_e32 v62, 1.0, v62
	v_log_f32_e32 v62, v62
	v_sub_f32_e32 v52, -0.5, v52
	v_mul_f32_e32 v56, 0x3f317218, v56
	v_mul_f32_e32 v52, 0x3fb8aa3b, v52
	v_mul_f32_e32 v62, 0x3f317218, v62
	v_cndmask_b32_e64 v53, v62, -v53, vcc
	v_mul_f32_e32 v62, 0xbfb8aa3b, v54
	v_exp_f32_e32 v62, v62
	v_cmp_gt_f32_e32 vcc, s22, v54
	v_sub_f32_e32 v53, -0.5, v53
	v_mul_f32_e32 v53, 0x3fb8aa3b, v53
	v_add_f32_e32 v62, 1.0, v62
	v_log_f32_e32 v62, v62
	v_exp_f32_e32 v52, v52
	v_exp_f32_e32 v53, v53
	v_mul_f32_e32 v62, 0x3f317218, v62
	v_cndmask_b32_e64 v54, v62, -v54, vcc
	v_mul_f32_e32 v62, 0xbfb8aa3b, v55
	v_exp_f32_e32 v62, v62
	v_cmp_gt_f32_e32 vcc, s22, v55
	v_sub_f32_e32 v54, -0.5, v54
	v_mul_f32_e32 v54, 0x3fb8aa3b, v54
	v_add_f32_e32 v62, 1.0, v62
	v_log_f32_e32 v62, v62
	v_exp_f32_e32 v54, v54
	v_mul_f32_e32 v62, 0x3f317218, v62
	v_cndmask_b32_e64 v55, v62, -v55, vcc
	v_cmp_gt_f32_e32 vcc, s22, v48
	v_sub_f32_e32 v55, -0.5, v55
	v_mul_f32_e32 v55, 0x3fb8aa3b, v55
	v_cndmask_b32_e64 v48, v56, -v48, vcc
	v_sub_f32_e32 v48, -0.5, v48
	v_mul_f32_e32 v48, 0x3fb8aa3b, v48
	v_exp_f32_e32 v56, v48
	v_add_f32_e32 v48, v49, v57
	v_mul_f32_e32 v49, 0xbfb8aa3b, v48
	v_exp_f32_e32 v49, v49
	v_cmp_gt_f32_e32 vcc, s22, v48
	v_exp_f32_e32 v55, v55
	v_add_f32_e32 v49, 1.0, v49
	v_log_f32_e32 v49, v49
	s_nop 0
	v_mul_f32_e32 v49, 0x3f317218, v49
	v_cndmask_b32_e64 v48, v49, -v48, vcc
	v_sub_f32_e32 v48, -0.5, v48
	v_mul_f32_e32 v48, 0x3fb8aa3b, v48
	v_exp_f32_e32 v57, v48
	v_add_f32_e32 v48, v50, v58
	v_mul_f32_e32 v49, 0xbfb8aa3b, v48
	v_exp_f32_e32 v49, v49
	v_cmp_gt_f32_e32 vcc, s22, v48
	v_cvt_pk_f16_f32 v50, v56, v57
	v_add_f32_e32 v49, 1.0, v49
	v_log_f32_e32 v49, v49
	s_nop 0
	v_mul_f32_e32 v49, 0x3f317218, v49
	v_cndmask_b32_e64 v48, v49, -v48, vcc
	v_sub_f32_e32 v48, -0.5, v48
	v_mul_f32_e32 v48, 0x3fb8aa3b, v48
	v_exp_f32_e32 v58, v48
	v_add_f32_e32 v48, v51, v59
	v_mul_f32_e32 v49, 0xbfb8aa3b, v48
	v_exp_f32_e32 v49, v49
	v_cmp_gt_f32_e32 vcc, s22, v48
	v_add_f32_e32 v49, 1.0, v49
	v_log_f32_e32 v49, v49
	s_nop 0
	v_mul_f32_e32 v49, 0x3f317218, v49
	v_cndmask_b32_e64 v48, v49, -v48, vcc
	v_sub_f32_e32 v48, -0.5, v48
	v_mul_f32_e32 v48, 0x3fb8aa3b, v48
	v_exp_f32_e32 v51, v48
	v_cvt_pk_f16_f32 v48, v52, v53
	v_cvt_pk_f16_f32 v49, v54, v55
	v_cvt_pk_f16_f32 v51, v58, v51
	global_store_dwordx4 v[60:61], v[48:51], off offset:256
	s_nop 0
	s_nop 0
	v_mad_i64_i32 v[48:49], s[20:21], v142, s50, 0
	s_nop 0
	s_nop 1
	v_mov_b32_e32 v52, v160
	v_mov_b32_e32 v53, v161
	v_mov_b32_e32 v54, v162
	v_mov_b32_e32 v55, v163
	s_nop 1
	v_mov_b32_e32 v56, v164
	v_mov_b32_e32 v57, v165
	v_mov_b32_e32 v58, v166
; __device__ __forceinline__ unsigned cvt_pk_bf16(float lo, float hi) { f32x2 v = {lo, hi}; bf16v2_t r = __builtin_convertvector(v, bf16v2_t); return __builtin_bit_cast(unsigned, r); }
; __device__ __forceinline__ float fexp(float x) { return __builtin_amdgcn_exp2f(x * 1.44269504089f); }
; __device__ __forceinline__ float fsigmoid(float x) { return __builtin_amdgcn_rcpf(1.0f + fexp(-x)); }
;     template <int KIND>
;     __device__ __forceinline__ void run(const f32x4 (&acc)[2][2][4][2], const UnitG& u, int wr, int wc, int fr, int fq) const {
;     ...
;                     } else if (KIND == 4) {
;                         const int c = u.x1 * 256 + bj * 128 + col0;
; #pragma unroll
;                         for (int e = 0; e < 8; ++e) { const float xx = -(v[e] + b0[c + e]); const float sp = (xx > 15.f) ? xx : __builtin_amdgcn_logf(1.0f + fexp(xx)) * 0.69314718056f; v[e] = fexp(-sp - 0.5f); }
;                     } else if (KIND == 5) {
;                         const int c = u.x1 * 256 + bj * 128 + col0 - 1024;
; #pragma unroll
;                         for (int e = 0; e < 8; ++e) v[e] = fsigmoid(v[e] + b1[c + e]);
;                     }
;                     if (KIND == 4 || KIND == 5) { w.x = pkh2(v[0], v[1]); w.y = pkh2(v[2], v[3]); w.z = pkh2(v[4], v[5]); w.w = pkh2(v[6], v[7]); }
;                     else { w.x = cvt_pk_bf16(v[0], v[1]); w.y = cvt_pk_bf16(v[2], v[3]); w.z = cvt_pk_bf16(v[4], v[5]); w.w = cvt_pk_bf16(v[6], v[7]); }
;                     *(v4u*)dst = w; }
	v_mov_b32_e32 v59, v167
	v_add_f32_e32 v40, v40, v52
	s_nop 0
	v_add_f32_e32 v44, v44, v56
	v_mul_f32_e32 v50, 0xbfb8aa3b, v44
	v_exp_f32_e32 v50, v50
	v_cmp_gt_f32_e32 vcc, s22, v44
	v_add_f32_e32 v41, v41, v53
	v_add_f32_e32 v42, v42, v54
	v_add_f32_e32 v50, 1.0, v50
	v_log_f32_e32 v50, v50
	v_add_f32_e32 v43, v43, v55
	v_mul_f32_e32 v50, 0x3f317218, v50
	v_cndmask_b32_e64 v44, v50, -v44, vcc
	v_sub_f32_e32 v44, -0.5, v44
	v_mul_f32_e32 v44, 0x3fb8aa3b, v44
	v_exp_f32_e32 v50, v44
	v_add_f32_e32 v44, v45, v57
	v_mul_f32_e32 v45, 0xbfb8aa3b, v44
	v_exp_f32_e32 v45, v45
	v_cmp_gt_f32_e32 vcc, s22, v44
	v_add_f32_e32 v45, 1.0, v45
	v_log_f32_e32 v45, v45
	s_nop 0
	v_mul_f32_e32 v45, 0x3f317218, v45
	v_cndmask_b32_e64 v44, v45, -v44, vcc
	v_sub_f32_e32 v44, -0.5, v44
	v_mul_f32_e32 v44, 0x3fb8aa3b, v44
	v_exp_f32_e32 v51, v44
	v_add_f32_e32 v44, v46, v58
	v_mul_f32_e32 v45, 0xbfb8aa3b, v44
	v_exp_f32_e32 v45, v45
	v_cmp_gt_f32_e32 vcc, s22, v44
	v_add_f32_e32 v45, 1.0, v45
	v_log_f32_e32 v45, v45
	s_nop 0
	v_mul_f32_e32 v45, 0x3f317218, v45
	v_cndmask_b32_e64 v44, v45, -v44, vcc
	v_sub_f32_e32 v44, -0.5, v44
	v_mul_f32_e32 v44, 0x3fb8aa3b, v44
	v_exp_f32_e32 v46, v44
	v_add_f32_e32 v44, v47, v59
	v_mul_f32_e32 v45, 0xbfb8aa3b, v44
	v_exp_f32_e32 v45, v45
	v_cmp_gt_f32_e32 vcc, s22, v44
	v_add_f32_e32 v45, 1.0, v45
	v_log_f32_e32 v45, v45
	s_nop 0
	v_mul_f32_e32 v45, 0x3f317218, v45
	v_cndmask_b32_e64 v44, v45, -v44, vcc
	v_sub_f32_e32 v44, -0.5, v44
	v_mul_f32_e32 v44, 0x3fb8aa3b, v44
	v_exp_f32_e32 v47, v44
	v_mul_f32_e32 v44, 0xbfb8aa3b, v40
	v_exp_f32_e32 v44, v44
	v_cmp_gt_f32_e32 vcc, s22, v40
	v_add_f32_e32 v44, 1.0, v44
	v_log_f32_e32 v44, v44
	s_nop 0
	v_mul_f32_e32 v44, 0x3f317218, v44
	v_cndmask_b32_e64 v40, v44, -v40, vcc
	v_mul_f32_e32 v44, 0xbfb8aa3b, v41
	v_exp_f32_e32 v44, v44
	v_cmp_gt_f32_e32 vcc, s22, v41
	v_sub_f32_e32 v40, -0.5, v40
	v_mul_f32_e32 v40, 0x3fb8aa3b, v40
	v_add_f32_e32 v44, 1.0, v44
	v_log_f32_e32 v44, v44
	v_exp_f32_e32 v40, v40
	v_mul_f32_e32 v44, 0x3f317218, v44
	v_cndmask_b32_e64 v41, v44, -v41, vcc
	v_mul_f32_e32 v44, 0xbfb8aa3b, v42
	v_exp_f32_e32 v44, v44
	v_cmp_gt_f32_e32 vcc, s22, v42
	v_sub_f32_e32 v41, -0.5, v41
	v_mul_f32_e32 v41, 0x3fb8aa3b, v41
	v_add_f32_e32 v44, 1.0, v44
	v_log_f32_e32 v44, v44
	v_exp_f32_e32 v41, v41
	v_mul_f32_e32 v44, 0x3f317218, v44
	v_cndmask_b32_e64 v42, v44, -v42, vcc
	v_mul_f32_e32 v44, 0xbfb8aa3b, v43
	v_exp_f32_e32 v44, v44
	v_cmp_gt_f32_e32 vcc, s22, v43
	v_sub_f32_e32 v42, -0.5, v42
	v_mul_f32_e32 v42, 0x3fb8aa3b, v42
	v_add_f32_e32 v44, 1.0, v44
	v_log_f32_e32 v44, v44
	v_exp_f32_e32 v42, v42
	v_mul_f32_e32 v44, 0x3f317218, v44
	v_cndmask_b32_e64 v43, v44, -v43, vcc
	v_sub_f32_e32 v43, -0.5, v43
	v_mul_f32_e32 v43, 0x3fb8aa3b, v43
	v_exp_f32_e32 v43, v43
	v_lshl_add_u64 v[44:45], v[48:49], 1, v[136:137]
	v_cvt_pk_f16_f32 v48, v50, v51
	v_cvt_pk_f16_f32 v49, v46, v47
	v_cvt_pk_f16_f32 v50, v40, v41
	v_cvt_pk_f16_f32 v51, v42, v43
	global_store_dwordx4 v[44:45], v[48:51], off
	s_nop 0
	s_nop 0
	s_nop 0
	s_nop 0
	s_nop 1
	v_mov_b32_e32 v40, v168
	v_mov_b32_e32 v41, v169
	v_mov_b32_e32 v42, v170
	v_mov_b32_e32 v43, v171
	s_nop 1
	v_mov_b32_e32 v46, v172
	v_mov_b32_e32 v47, v173
	v_mov_b32_e32 v48, v174
	v_mov_b32_e32 v49, v175
	v_add_f32_e32 v32, v32, v40
	s_nop 0
	v_add_f32_e32 v36, v36, v46
	v_mul_f32_e32 v46, 0xbfb8aa3b, v36
	v_exp_f32_e32 v46, v46
	v_cmp_gt_f32_e32 vcc, s22, v36
	v_add_f32_e32 v37, v37, v47
	v_add_f32_e32 v38, v38, v48
	v_add_f32_e32 v46, 1.0, v46
	v_log_f32_e32 v46, v46
	v_add_f32_e32 v39, v39, v49
	v_mul_f32_e32 v40, 0xbfb8aa3b, v32
	v_exp_f32_e32 v40, v40
	v_mul_f32_e32 v46, 0x3f317218, v46
	v_cndmask_b32_e64 v36, v46, -v36, vcc
	v_mul_f32_e32 v46, 0xbfb8aa3b, v37
	v_exp_f32_e32 v46, v46
	v_cmp_gt_f32_e32 vcc, s22, v37
	v_add_f32_e32 v40, 1.0, v40
	v_log_f32_e32 v40, v40
	v_add_f32_e32 v46, 1.0, v46
	v_log_f32_e32 v46, v46
	v_sub_f32_e32 v36, -0.5, v36
	v_mul_f32_e32 v40, 0x3f317218, v40
	v_mul_f32_e32 v36, 0x3fb8aa3b, v36
	v_mul_f32_e32 v46, 0x3f317218, v46
	v_cndmask_b32_e64 v37, v46, -v37, vcc
	v_mul_f32_e32 v46, 0xbfb8aa3b, v38
	v_exp_f32_e32 v46, v46
	v_cmp_gt_f32_e32 vcc, s22, v38
	v_sub_f32_e32 v37, -0.5, v37
	v_mul_f32_e32 v37, 0x3fb8aa3b, v37
	v_add_f32_e32 v46, 1.0, v46
	v_log_f32_e32 v46, v46
	v_exp_f32_e32 v36, v36
	v_exp_f32_e32 v37, v37
	v_mul_f32_e32 v46, 0x3f317218, v46
	v_cndmask_b32_e64 v38, v46, -v38, vcc
	v_mul_f32_e32 v46, 0xbfb8aa3b, v39
	v_exp_f32_e32 v46, v46
	v_cmp_gt_f32_e32 vcc, s22, v39
	v_sub_f32_e32 v38, -0.5, v38
	v_mul_f32_e32 v38, 0x3fb8aa3b, v38
	v_add_f32_e32 v46, 1.0, v46
	v_log_f32_e32 v46, v46
	v_exp_f32_e32 v38, v38
	v_mul_f32_e32 v46, 0x3f317218, v46
	v_cndmask_b32_e64 v39, v46, -v39, vcc
	v_cmp_gt_f32_e32 vcc, s22, v32
	v_sub_f32_e32 v39, -0.5, v39
	v_mul_f32_e32 v39, 0x3fb8aa3b, v39
	v_cndmask_b32_e64 v32, v40, -v32, vcc
	v_sub_f32_e32 v32, -0.5, v32
	v_mul_f32_e32 v32, 0x3fb8aa3b, v32
	v_exp_f32_e32 v40, v32
	v_add_f32_e32 v32, v33, v41
	v_mul_f32_e32 v33, 0xbfb8aa3b, v32
	v_exp_f32_e32 v33, v33
	v_cmp_gt_f32_e32 vcc, s22, v32
	v_exp_f32_e32 v39, v39
	v_add_f32_e32 v33, 1.0, v33
	v_log_f32_e32 v33, v33
	s_nop 0
	v_mul_f32_e32 v33, 0x3f317218, v33
	v_cndmask_b32_e64 v32, v33, -v32, vcc
	v_sub_f32_e32 v32, -0.5, v32
	v_mul_f32_e32 v32, 0x3fb8aa3b, v32
	v_exp_f32_e32 v41, v32
	v_add_f32_e32 v32, v34, v42
	v_mul_f32_e32 v33, 0xbfb8aa3b, v32
	v_exp_f32_e32 v33, v33
	v_cmp_gt_f32_e32 vcc, s22, v32
	v_cvt_pk_f16_f32 v34, v40, v41
	v_add_f32_e32 v33, 1.0, v33
	v_log_f32_e32 v33, v33
	s_nop 0
	v_mul_f32_e32 v33, 0x3f317218, v33
	v_cndmask_b32_e64 v32, v33, -v32, vcc
	v_sub_f32_e32 v32, -0.5, v32
; __device__ __forceinline__ unsigned cvt_pk_bf16(float lo, float hi) { f32x2 v = {lo, hi}; bf16v2_t r = __builtin_convertvector(v, bf16v2_t); return __builtin_bit_cast(unsigned, r); }
; __device__ __forceinline__ float fexp(float x) { return __builtin_amdgcn_exp2f(x * 1.44269504089f); }
; __device__ __forceinline__ float fsigmoid(float x) { return __builtin_amdgcn_rcpf(1.0f + fexp(-x)); }
;     template <int KIND>
;     __device__ __forceinline__ void run(const f32x4 (&acc)[2][2][4][2], const UnitG& u, int wr, int wc, int fr, int fq) const {
;     ...
;                     } else if (KIND == 4) {
;                         const int c = u.x1 * 256 + bj * 128 + col0;
; #pragma unroll
;                         for (int e = 0; e < 8; ++e) { const float xx = -(v[e] + b0[c + e]); const float sp = (xx > 15.f) ? xx : __builtin_amdgcn_logf(1.0f + fexp(xx)) * 0.69314718056f; v[e] = fexp(-sp - 0.5f); }
;                     } else if (KIND == 5) {
;                         const int c = u.x1 * 256 + bj * 128 + col0 - 1024;
; #pragma unroll
;                         for (int e = 0; e < 8; ++e) v[e] = fsigmoid(v[e] + b1[c + e]);
;                     }
;                     if (KIND == 4 || KIND == 5) { w.x = pkh2(v[0], v[1]); w.y = pkh2(v[2], v[3]); w.z = pkh2(v[4], v[5]); w.w = pkh2(v[6], v[7]); }
;                     else { w.x = cvt_pk_bf16(v[0], v[1]); w.y = cvt_pk_bf16(v[2], v[3]); w.z = cvt_pk_bf16(v[4], v[5]); w.w = cvt_pk_bf16(v[6], v[7]); }
;                     *(v4u*)dst = w; }
	v_mul_f32_e32 v32, 0x3fb8aa3b, v32
	v_exp_f32_e32 v42, v32
	v_add_f32_e32 v32, v35, v43
	v_mul_f32_e32 v33, 0xbfb8aa3b, v32
	v_exp_f32_e32 v33, v33
	v_cmp_gt_f32_e32 vcc, s22, v32
	v_add_f32_e32 v33, 1.0, v33
	v_log_f32_e32 v33, v33
	s_nop 0
	v_mul_f32_e32 v33, 0x3f317218, v33
	v_cndmask_b32_e64 v32, v33, -v32, vcc
	v_sub_f32_e32 v32, -0.5, v32
	v_mul_f32_e32 v32, 0x3fb8aa3b, v32
	v_exp_f32_e32 v35, v32
	v_cvt_pk_f16_f32 v32, v36, v37
	v_cvt_pk_f16_f32 v33, v38, v39
	v_cvt_pk_f16_f32 v35, v42, v35
	global_store_dwordx4 v[44:45], v[32:35], off offset:256
	s_nop 0
	s_nop 0
	v_mad_i64_i32 v[32:33], s[20:21], v139, s50, 0
	s_nop 0
	s_nop 1
	v_mov_b32_e32 v36, v160
	v_mov_b32_e32 v37, v161
	v_mov_b32_e32 v38, v162
	v_mov_b32_e32 v39, v163
	s_nop 1
	v_mov_b32_e32 v40, v164
	v_mov_b32_e32 v41, v165
	v_mov_b32_e32 v42, v166
	v_mov_b32_e32 v43, v167
	v_add_f32_e32 v24, v24, v36
	s_nop 0
	v_add_f32_e32 v28, v28, v40
	v_mul_f32_e32 v34, 0xbfb8aa3b, v28
	v_exp_f32_e32 v34, v34
	v_cmp_gt_f32_e32 vcc, s22, v28
	v_add_f32_e32 v25, v25, v37
	v_add_f32_e32 v26, v26, v38
	v_add_f32_e32 v34, 1.0, v34
	v_log_f32_e32 v34, v34
	v_add_f32_e32 v27, v27, v39
	v_mul_f32_e32 v34, 0x3f317218, v34
	v_cndmask_b32_e64 v28, v34, -v28, vcc
	v_sub_f32_e32 v28, -0.5, v28
	v_mul_f32_e32 v28, 0x3fb8aa3b, v28
	v_exp_f32_e32 v34, v28
	v_add_f32_e32 v28, v29, v41
	v_mul_f32_e32 v29, 0xbfb8aa3b, v28
	v_exp_f32_e32 v29, v29
	v_cmp_gt_f32_e32 vcc, s22, v28
	v_add_f32_e32 v29, 1.0, v29
	v_log_f32_e32 v29, v29
	s_nop 0
	v_mul_f32_e32 v29, 0x3f317218, v29
	v_cndmask_b32_e64 v28, v29, -v28, vcc
	v_sub_f32_e32 v28, -0.5, v28
	v_mul_f32_e32 v28, 0x3fb8aa3b, v28
	v_exp_f32_e32 v35, v28
	v_add_f32_e32 v28, v30, v42
	v_mul_f32_e32 v29, 0xbfb8aa3b, v28
	v_exp_f32_e32 v29, v29
	v_cmp_gt_f32_e32 vcc, s22, v28
	v_add_f32_e32 v29, 1.0, v29
	v_log_f32_e32 v29, v29
	s_nop 0
	v_mul_f32_e32 v29, 0x3f317218, v29
	v_cndmask_b32_e64 v28, v29, -v28, vcc
	v_sub_f32_e32 v28, -0.5, v28
	v_mul_f32_e32 v28, 0x3fb8aa3b, v28
	v_exp_f32_e32 v30, v28
	v_add_f32_e32 v28, v31, v43
	v_mul_f32_e32 v29, 0xbfb8aa3b, v28
	v_exp_f32_e32 v29, v29
	v_cmp_gt_f32_e32 vcc, s22, v28
	v_add_f32_e32 v29, 1.0, v29
	v_log_f32_e32 v29, v29
	s_nop 0
	v_mul_f32_e32 v29, 0x3f317218, v29
	v_cndmask_b32_e64 v28, v29, -v28, vcc
	v_sub_f32_e32 v28, -0.5, v28
	v_mul_f32_e32 v28, 0x3fb8aa3b, v28
	v_exp_f32_e32 v31, v28
	v_mul_f32_e32 v28, 0xbfb8aa3b, v24
	v_exp_f32_e32 v28, v28
	v_cmp_gt_f32_e32 vcc, s22, v24
	v_add_f32_e32 v28, 1.0, v28
	v_log_f32_e32 v28, v28
	s_nop 0
	v_mul_f32_e32 v28, 0x3f317218, v28
	v_cndmask_b32_e64 v24, v28, -v24, vcc
	v_mul_f32_e32 v28, 0xbfb8aa3b, v25
	v_exp_f32_e32 v28, v28
	v_cmp_gt_f32_e32 vcc, s22, v25
	v_sub_f32_e32 v24, -0.5, v24
	v_mul_f32_e32 v24, 0x3fb8aa3b, v24
	v_add_f32_e32 v28, 1.0, v28
	v_log_f32_e32 v28, v28
	v_exp_f32_e32 v24, v24
	v_mul_f32_e32 v28, 0x3f317218, v28
	v_cndmask_b32_e64 v25, v28, -v25, vcc
	v_mul_f32_e32 v28, 0xbfb8aa3b, v26
	v_exp_f32_e32 v28, v28
	v_cmp_gt_f32_e32 vcc, s22, v26
	v_sub_f32_e32 v25, -0.5, v25
	v_mul_f32_e32 v25, 0x3fb8aa3b, v25
	v_add_f32_e32 v28, 1.0, v28
	v_log_f32_e32 v28, v28
	v_exp_f32_e32 v25, v25
	v_mul_f32_e32 v28, 0x3f317218, v28
	v_cndmask_b32_e64 v26, v28, -v26, vcc
	v_mul_f32_e32 v28, 0xbfb8aa3b, v27
	v_exp_f32_e32 v28, v28
	v_cmp_gt_f32_e32 vcc, s22, v27
	v_sub_f32_e32 v26, -0.5, v26
	v_mul_f32_e32 v26, 0x3fb8aa3b, v26
	v_add_f32_e32 v28, 1.0, v28
	v_log_f32_e32 v28, v28
	v_exp_f32_e32 v26, v26
	v_mul_f32_e32 v28, 0x3f317218, v28
	v_cndmask_b32_e64 v27, v28, -v27, vcc
	v_sub_f32_e32 v27, -0.5, v27
	v_mul_f32_e32 v27, 0x3fb8aa3b, v27
	v_exp_f32_e32 v27, v27
	v_lshl_add_u64 v[28:29], v[32:33], 1, v[136:137]
	v_cvt_pk_f16_f32 v32, v34, v35
	v_cvt_pk_f16_f32 v33, v30, v31
	v_cvt_pk_f16_f32 v34, v24, v25
	v_cvt_pk_f16_f32 v35, v26, v27
	global_store_dwordx4 v[28:29], v[32:35], off
	s_nop 0
	s_nop 0
	s_nop 0
	s_nop 0
	s_nop 1
	v_mov_b32_e32 v24, v168
	v_mov_b32_e32 v25, v169
	v_mov_b32_e32 v26, v170
	v_mov_b32_e32 v27, v171
	s_nop 1
	v_mov_b32_e32 v30, v172
	v_mov_b32_e32 v31, v173
	v_mov_b32_e32 v32, v174
	v_mov_b32_e32 v33, v175
	v_add_f32_e32 v16, v16, v24
	s_nop 0
	v_add_f32_e32 v20, v20, v30
	v_mul_f32_e32 v30, 0xbfb8aa3b, v20
	v_exp_f32_e32 v30, v30
	v_cmp_gt_f32_e32 vcc, s22, v20
	v_add_f32_e32 v21, v21, v31
	v_add_f32_e32 v22, v22, v32
	v_add_f32_e32 v30, 1.0, v30
	v_log_f32_e32 v30, v30
	v_add_f32_e32 v23, v23, v33
	v_mul_f32_e32 v24, 0xbfb8aa3b, v16
	v_exp_f32_e32 v24, v24
	v_mul_f32_e32 v30, 0x3f317218, v30
	v_cndmask_b32_e64 v20, v30, -v20, vcc
	v_mul_f32_e32 v30, 0xbfb8aa3b, v21
	v_exp_f32_e32 v30, v30
	v_cmp_gt_f32_e32 vcc, s22, v21
	v_add_f32_e32 v24, 1.0, v24
	v_log_f32_e32 v24, v24
	v_add_f32_e32 v30, 1.0, v30
	v_log_f32_e32 v30, v30
	v_sub_f32_e32 v20, -0.5, v20
	v_mul_f32_e32 v24, 0x3f317218, v24
	v_mul_f32_e32 v20, 0x3fb8aa3b, v20
	v_mul_f32_e32 v30, 0x3f317218, v30
	v_cndmask_b32_e64 v21, v30, -v21, vcc
	v_mul_f32_e32 v30, 0xbfb8aa3b, v22
	v_exp_f32_e32 v30, v30
	v_cmp_gt_f32_e32 vcc, s22, v22
	v_sub_f32_e32 v21, -0.5, v21
	v_mul_f32_e32 v21, 0x3fb8aa3b, v21
	v_add_f32_e32 v30, 1.0, v30
	v_log_f32_e32 v30, v30
	v_exp_f32_e32 v20, v20
	v_exp_f32_e32 v21, v21
	v_mul_f32_e32 v30, 0x3f317218, v30
	v_cndmask_b32_e64 v22, v30, -v22, vcc
	v_mul_f32_e32 v30, 0xbfb8aa3b, v23
	v_exp_f32_e32 v30, v30
	v_cmp_gt_f32_e32 vcc, s22, v23
	v_sub_f32_e32 v22, -0.5, v22
	v_mul_f32_e32 v22, 0x3fb8aa3b, v22
	v_add_f32_e32 v30, 1.0, v30
	v_log_f32_e32 v30, v30
	v_exp_f32_e32 v22, v22
	v_mul_f32_e32 v30, 0x3f317218, v30
	v_cndmask_b32_e64 v23, v30, -v23, vcc
	v_cmp_gt_f32_e32 vcc, s22, v16
	v_sub_f32_e32 v23, -0.5, v23
	v_mul_f32_e32 v23, 0x3fb8aa3b, v23
; __device__ __forceinline__ unsigned cvt_pk_bf16(float lo, float hi) { f32x2 v = {lo, hi}; bf16v2_t r = __builtin_convertvector(v, bf16v2_t); return __builtin_bit_cast(unsigned, r); }
; __device__ __forceinline__ float fexp(float x) { return __builtin_amdgcn_exp2f(x * 1.44269504089f); }
; __device__ __forceinline__ float fsigmoid(float x) { return __builtin_amdgcn_rcpf(1.0f + fexp(-x)); }
;     template <int KIND>
;     __device__ __forceinline__ void run(const f32x4 (&acc)[2][2][4][2], const UnitG& u, int wr, int wc, int fr, int fq) const {
;     ...
;                     } else if (KIND == 4) {
;                         const int c = u.x1 * 256 + bj * 128 + col0;
; #pragma unroll
;                         for (int e = 0; e < 8; ++e) { const float xx = -(v[e] + b0[c + e]); const float sp = (xx > 15.f) ? xx : __builtin_amdgcn_logf(1.0f + fexp(xx)) * 0.69314718056f; v[e] = fexp(-sp - 0.5f); }
;                     } else if (KIND == 5) {
;                         const int c = u.x1 * 256 + bj * 128 + col0 - 1024;
; #pragma unroll
;                         for (int e = 0; e < 8; ++e) v[e] = fsigmoid(v[e] + b1[c + e]);
;                     }
;                     if (KIND == 4 || KIND == 5) { w.x = pkh2(v[0], v[1]); w.y = pkh2(v[2], v[3]); w.z = pkh2(v[4], v[5]); w.w = pkh2(v[6], v[7]); }
;                     else { w.x = cvt_pk_bf16(v[0], v[1]); w.y = cvt_pk_bf16(v[2], v[3]); w.z = cvt_pk_bf16(v[4], v[5]); w.w = cvt_pk_bf16(v[6], v[7]); }
;                     *(v4u*)dst = w; }
	v_cndmask_b32_e64 v16, v24, -v16, vcc
	v_sub_f32_e32 v16, -0.5, v16
	v_mul_f32_e32 v16, 0x3fb8aa3b, v16
	v_exp_f32_e32 v24, v16
	v_add_f32_e32 v16, v17, v25
	v_mul_f32_e32 v17, 0xbfb8aa3b, v16
	v_exp_f32_e32 v17, v17
	v_cmp_gt_f32_e32 vcc, s22, v16
	v_exp_f32_e32 v23, v23
	v_add_f32_e32 v17, 1.0, v17
	v_log_f32_e32 v17, v17
	s_nop 0
	v_mul_f32_e32 v17, 0x3f317218, v17
	v_cndmask_b32_e64 v16, v17, -v16, vcc
	v_sub_f32_e32 v16, -0.5, v16
	v_mul_f32_e32 v16, 0x3fb8aa3b, v16
	v_exp_f32_e32 v25, v16
	v_add_f32_e32 v16, v18, v26
	v_mul_f32_e32 v17, 0xbfb8aa3b, v16
	v_exp_f32_e32 v17, v17
	v_cmp_gt_f32_e32 vcc, s22, v16
	v_cvt_pk_f16_f32 v18, v24, v25
	v_add_f32_e32 v17, 1.0, v17
	v_log_f32_e32 v17, v17
	s_nop 0
	v_mul_f32_e32 v17, 0x3f317218, v17
	v_cndmask_b32_e64 v16, v17, -v16, vcc
	v_sub_f32_e32 v16, -0.5, v16
	v_mul_f32_e32 v16, 0x3fb8aa3b, v16
	v_exp_f32_e32 v26, v16
	v_add_f32_e32 v16, v19, v27
	v_mul_f32_e32 v17, 0xbfb8aa3b, v16
	v_exp_f32_e32 v17, v17
	v_cmp_gt_f32_e32 vcc, s22, v16
	v_add_f32_e32 v17, 1.0, v17
	v_log_f32_e32 v17, v17
	s_nop 0
	v_mul_f32_e32 v17, 0x3f317218, v17
	v_cndmask_b32_e64 v16, v17, -v16, vcc
	v_sub_f32_e32 v16, -0.5, v16
	v_mul_f32_e32 v16, 0x3fb8aa3b, v16
	v_exp_f32_e32 v19, v16
	v_cvt_pk_f16_f32 v16, v20, v21
	v_cvt_pk_f16_f32 v17, v22, v23
	v_cvt_pk_f16_f32 v19, v26, v19
	global_store_dwordx4 v[28:29], v[16:19], off offset:256
	s_nop 0
	s_nop 0
	v_mad_i64_i32 v[16:17], s[20:21], v135, s50, 0
	s_nop 0
	s_nop 1
	v_mov_b32_e32 v20, v160
	v_mov_b32_e32 v21, v161
	v_mov_b32_e32 v22, v162
	v_mov_b32_e32 v23, v163
	s_nop 1
	v_mov_b32_e32 v24, v164
	v_mov_b32_e32 v25, v165
	v_mov_b32_e32 v26, v166
	v_mov_b32_e32 v27, v167
	v_add_f32_e32 v8, v8, v20
	s_nop 0
	v_add_f32_e32 v12, v12, v24
	v_mul_f32_e32 v18, 0xbfb8aa3b, v12
	v_exp_f32_e32 v18, v18
	v_cmp_gt_f32_e32 vcc, s22, v12
	v_add_f32_e32 v9, v9, v21
	v_add_f32_e32 v10, v10, v22
	v_add_f32_e32 v18, 1.0, v18
	v_log_f32_e32 v18, v18
	v_add_f32_e32 v11, v11, v23
	v_mul_f32_e32 v18, 0x3f317218, v18
	v_cndmask_b32_e64 v12, v18, -v12, vcc
	v_sub_f32_e32 v12, -0.5, v12
	v_mul_f32_e32 v12, 0x3fb8aa3b, v12
	v_exp_f32_e32 v18, v12
	v_add_f32_e32 v12, v13, v25
	v_mul_f32_e32 v13, 0xbfb8aa3b, v12
	v_exp_f32_e32 v13, v13
	v_cmp_gt_f32_e32 vcc, s22, v12
	v_add_f32_e32 v13, 1.0, v13
	v_log_f32_e32 v13, v13
	s_nop 0
	v_mul_f32_e32 v13, 0x3f317218, v13
	v_cndmask_b32_e64 v12, v13, -v12, vcc
	v_sub_f32_e32 v12, -0.5, v12
	v_mul_f32_e32 v12, 0x3fb8aa3b, v12
	v_exp_f32_e32 v19, v12
	v_add_f32_e32 v12, v14, v26
	v_mul_f32_e32 v13, 0xbfb8aa3b, v12
	v_exp_f32_e32 v13, v13
	v_cmp_gt_f32_e32 vcc, s22, v12
	v_add_f32_e32 v13, 1.0, v13
	v_log_f32_e32 v13, v13
	s_nop 0
	v_mul_f32_e32 v13, 0x3f317218, v13
	v_cndmask_b32_e64 v12, v13, -v12, vcc
	v_sub_f32_e32 v12, -0.5, v12
	v_mul_f32_e32 v12, 0x3fb8aa3b, v12
	v_exp_f32_e32 v14, v12
	v_add_f32_e32 v12, v15, v27
	v_mul_f32_e32 v13, 0xbfb8aa3b, v12
	v_exp_f32_e32 v13, v13
	v_cmp_gt_f32_e32 vcc, s22, v12
	v_add_f32_e32 v13, 1.0, v13
	v_log_f32_e32 v13, v13
	s_nop 0
	v_mul_f32_e32 v13, 0x3f317218, v13
	v_cndmask_b32_e64 v12, v13, -v12, vcc
	v_sub_f32_e32 v12, -0.5, v12
	v_mul_f32_e32 v12, 0x3fb8aa3b, v12
	v_exp_f32_e32 v15, v12
	v_mul_f32_e32 v12, 0xbfb8aa3b, v8
	v_exp_f32_e32 v12, v12
	v_cmp_gt_f32_e32 vcc, s22, v8
	v_add_f32_e32 v12, 1.0, v12
	v_log_f32_e32 v12, v12
	s_nop 0
	v_mul_f32_e32 v12, 0x3f317218, v12
	v_cndmask_b32_e64 v8, v12, -v8, vcc
	v_mul_f32_e32 v12, 0xbfb8aa3b, v9
	v_exp_f32_e32 v12, v12
	v_cmp_gt_f32_e32 vcc, s22, v9
	v_sub_f32_e32 v8, -0.5, v8
	v_mul_f32_e32 v8, 0x3fb8aa3b, v8
	v_add_f32_e32 v12, 1.0, v12
	v_log_f32_e32 v12, v12
	v_exp_f32_e32 v8, v8
	v_mul_f32_e32 v12, 0x3f317218, v12
	v_cndmask_b32_e64 v9, v12, -v9, vcc
	v_mul_f32_e32 v12, 0xbfb8aa3b, v10
	v_exp_f32_e32 v12, v12
	v_cmp_gt_f32_e32 vcc, s22, v10
	v_sub_f32_e32 v9, -0.5, v9
	v_mul_f32_e32 v9, 0x3fb8aa3b, v9
; __device__ __forceinline__ unsigned cvt_pk_bf16(float lo, float hi) { f32x2 v = {lo, hi}; bf16v2_t r = __builtin_convertvector(v, bf16v2_t); return __builtin_bit_cast(unsigned, r); }
; __device__ __forceinline__ float fexp(float x) { return __builtin_amdgcn_exp2f(x * 1.44269504089f); }
; __device__ __forceinline__ float fsigmoid(float x) { return __builtin_amdgcn_rcpf(1.0f + fexp(-x)); }
;     template <int KIND>
;     __device__ __forceinline__ void run(const f32x4 (&acc)[2][2][4][2], const UnitG& u, int wr, int wc, int fr, int fq) const {
;     ...
;                     } else if (KIND == 4) {
;                         const int c = u.x1 * 256 + bj * 128 + col0;
; #pragma unroll
;                         for (int e = 0; e < 8; ++e) { const float xx = -(v[e] + b0[c + e]); const float sp = (xx > 15.f) ? xx : __builtin_amdgcn_logf(1.0f + fexp(xx)) * 0.69314718056f; v[e] = fexp(-sp - 0.5f); }
;                     } else if (KIND == 5) {
;                         const int c = u.x1 * 256 + bj * 128 + col0 - 1024;
; #pragma unroll
;                         for (int e = 0; e < 8; ++e) v[e] = fsigmoid(v[e] + b1[c + e]);
;                     }
;                     if (KIND == 4 || KIND == 5) { w.x = pkh2(v[0], v[1]); w.y = pkh2(v[2], v[3]); w.z = pkh2(v[4], v[5]); w.w = pkh2(v[6], v[7]); }
;                     else { w.x = cvt_pk_bf16(v[0], v[1]); w.y = cvt_pk_bf16(v[2], v[3]); w.z = cvt_pk_bf16(v[4], v[5]); w.w = cvt_pk_bf16(v[6], v[7]); }
;                     *(v4u*)dst = w; }
	v_add_f32_e32 v12, 1.0, v12
	v_log_f32_e32 v12, v12
	v_exp_f32_e32 v9, v9
	v_mul_f32_e32 v12, 0x3f317218, v12
	v_cndmask_b32_e64 v10, v12, -v10, vcc
	v_mul_f32_e32 v12, 0xbfb8aa3b, v11
	v_exp_f32_e32 v12, v12
	v_cmp_gt_f32_e32 vcc, s22, v11
	v_sub_f32_e32 v10, -0.5, v10
	v_mul_f32_e32 v10, 0x3fb8aa3b, v10
	v_add_f32_e32 v12, 1.0, v12
	v_log_f32_e32 v12, v12
	v_exp_f32_e32 v10, v10
	v_mul_f32_e32 v12, 0x3f317218, v12
	v_cndmask_b32_e64 v11, v12, -v11, vcc
	v_sub_f32_e32 v11, -0.5, v11
	v_mul_f32_e32 v11, 0x3fb8aa3b, v11
	v_exp_f32_e32 v11, v11
	v_lshl_add_u64 v[12:13], v[16:17], 1, v[136:137]
	v_cvt_pk_f16_f32 v16, v18, v19
	v_cvt_pk_f16_f32 v17, v14, v15
	v_cvt_pk_f16_f32 v18, v8, v9
	v_cvt_pk_f16_f32 v19, v10, v11
	global_store_dwordx4 v[12:13], v[16:19], off
	s_nop 0
	s_nop 0
	s_nop 0
	s_nop 0
	s_nop 1
	v_mov_b32_e32 v8, v168
	v_mov_b32_e32 v9, v169
	v_mov_b32_e32 v10, v170
	v_mov_b32_e32 v11, v171
	s_nop 1
	v_mov_b32_e32 v14, v172
	v_mov_b32_e32 v15, v173
	v_mov_b32_e32 v16, v174
	v_mov_b32_e32 v17, v175
	v_add_f32_e32 v0, v0, v8
	s_nop 0
	v_add_f32_e32 v4, v4, v14
	v_mul_f32_e32 v14, 0xbfb8aa3b, v4
	v_exp_f32_e32 v14, v14
	v_cmp_gt_f32_e32 vcc, s22, v4
	v_add_f32_e32 v5, v5, v15
	v_add_f32_e32 v6, v6, v16
	v_add_f32_e32 v14, 1.0, v14
	v_log_f32_e32 v14, v14
	v_add_f32_e32 v7, v7, v17
	v_mul_f32_e32 v8, 0xbfb8aa3b, v0
	v_exp_f32_e32 v8, v8
	v_mul_f32_e32 v14, 0x3f317218, v14
	v_cndmask_b32_e64 v4, v14, -v4, vcc
	v_mul_f32_e32 v14, 0xbfb8aa3b, v5
	v_exp_f32_e32 v14, v14
	v_cmp_gt_f32_e32 vcc, s22, v5
	v_add_f32_e32 v8, 1.0, v8
	v_log_f32_e32 v8, v8
	v_add_f32_e32 v14, 1.0, v14
	v_log_f32_e32 v14, v14
	v_sub_f32_e32 v4, -0.5, v4
	v_mul_f32_e32 v8, 0x3f317218, v8
	v_mul_f32_e32 v4, 0x3fb8aa3b, v4
	v_mul_f32_e32 v14, 0x3f317218, v14
	v_cndmask_b32_e64 v5, v14, -v5, vcc
	v_mul_f32_e32 v14, 0xbfb8aa3b, v6
	v_exp_f32_e32 v14, v14
	v_cmp_gt_f32_e32 vcc, s22, v6
	v_sub_f32_e32 v5, -0.5, v5
	v_mul_f32_e32 v5, 0x3fb8aa3b, v5
	v_add_f32_e32 v14, 1.0, v14
	v_log_f32_e32 v14, v14
	v_exp_f32_e32 v4, v4
	v_exp_f32_e32 v5, v5
	v_mul_f32_e32 v14, 0x3f317218, v14
	v_cndmask_b32_e64 v6, v14, -v6, vcc
	v_mul_f32_e32 v14, 0xbfb8aa3b, v7
	v_exp_f32_e32 v14, v14
	v_cmp_gt_f32_e32 vcc, s22, v7
	v_sub_f32_e32 v6, -0.5, v6
	v_mul_f32_e32 v6, 0x3fb8aa3b, v6
	v_add_f32_e32 v14, 1.0, v14
	v_log_f32_e32 v14, v14
	v_exp_f32_e32 v6, v6
	v_mul_f32_e32 v14, 0x3f317218, v14
	v_cndmask_b32_e64 v7, v14, -v7, vcc
	v_cmp_gt_f32_e32 vcc, s22, v0
	v_sub_f32_e32 v7, -0.5, v7
	v_mul_f32_e32 v7, 0x3fb8aa3b, v7
	v_cndmask_b32_e64 v0, v8, -v0, vcc
	v_sub_f32_e32 v0, -0.5, v0
	v_mul_f32_e32 v0, 0x3fb8aa3b, v0
	v_exp_f32_e32 v8, v0
	v_add_f32_e32 v0, v1, v9
	v_mul_f32_e32 v1, 0xbfb8aa3b, v0
	v_exp_f32_e32 v1, v1
	v_cmp_gt_f32_e32 vcc, s22, v0
	v_exp_f32_e32 v7, v7
	v_add_f32_e32 v1, 1.0, v1
	v_log_f32_e32 v1, v1
	s_nop 0
	v_mul_f32_e32 v1, 0x3f317218, v1
	v_cndmask_b32_e64 v0, v1, -v0, vcc
	v_sub_f32_e32 v0, -0.5, v0
	v_mul_f32_e32 v0, 0x3fb8aa3b, v0
	v_exp_f32_e32 v9, v0
	v_add_f32_e32 v0, v2, v10
	v_mul_f32_e32 v1, 0xbfb8aa3b, v0
	v_exp_f32_e32 v1, v1
	v_cmp_gt_f32_e32 vcc, s22, v0
	v_cvt_pk_f16_f32 v2, v8, v9
	v_add_f32_e32 v1, 1.0, v1
	v_log_f32_e32 v1, v1
	s_nop 0
	v_mul_f32_e32 v1, 0x3f317218, v1
	v_cndmask_b32_e64 v0, v1, -v0, vcc
	v_sub_f32_e32 v0, -0.5, v0
	v_mul_f32_e32 v0, 0x3fb8aa3b, v0
	v_exp_f32_e32 v10, v0
	v_add_f32_e32 v0, v3, v11
	v_mul_f32_e32 v1, 0xbfb8aa3b, v0
	v_exp_f32_e32 v1, v1
	v_cmp_gt_f32_e32 vcc, s22, v0
	v_add_f32_e32 v1, 1.0, v1
	v_log_f32_e32 v1, v1
	s_nop 0
	v_mul_f32_e32 v1, 0x3f317218, v1
	v_cndmask_b32_e64 v0, v1, -v0, vcc
	v_sub_f32_e32 v0, -0.5, v0
	v_mul_f32_e32 v0, 0x3fb8aa3b, v0
	v_exp_f32_e32 v3, v0
	v_cvt_pk_f16_f32 v0, v4, v5
	v_cvt_pk_f16_f32 v1, v6, v7
	v_cvt_pk_f16_f32 v3, v10, v3
	global_store_dwordx4 v[12:13], v[0:3], off offset:256
	s_andn2_b64 vcc, exec, s[18:19]
	s_cbranch_vccz .LBB0_552

; __device__ __forceinline__ float h_lo(unsigned w) { h2 v = __builtin_bit_cast(h2, w); return (float)v.x; }
; __device__ __forceinline__ float h_hi(unsigned w) { h2 v = __builtin_bit_cast(h2, w); return (float)v.y; }
; __device__ __forceinline__ void phase_rwkv_post(const Frame& F, const Args& a, int l) {
;     ...
;     for (int t = F.gw; t < T; t += F.NGW) {
;         float y[8];
;     ...
;         { const v4u p = *(const v4u*)(YSB + (size_t)t * 512 + c0), q = *(const v4u*)(YSB + ((size_t)T + t) * 512 + c0);
; #pragma unroll
;           for (int i = 0; i < 4; ++i) { y[2 * i] = bf_lo(p[i]) + bf_lo(q[i]); y[2 * i + 1] = bf_hi(p[i]) + bf_hi(q[i]); } }
;     ...
;         { const f32x4 p0 = *(const f32x4*)(YS + (size_t)t * 512 + c0), p1 = *(const f32x4*)(YS + (size_t)t * 512 + c0 + 4);
;           const f32x4 q0 = *(const f32x4*)(YS + ((size_t)T + t) * 512 + c0), q1 = *(const f32x4*)(YS + ((size_t)T + t) * 512 + c0 + 4);
;           y[0] = p0.x + q0.x; y[1] = p0.y + q0.y; y[2] = p0.z + q0.z; y[3] = p0.w + q0.w; y[4] = p1.x + q1.x; y[5] = p1.y + q1.y; y[6] = p1.z + q1.z; y[7] = p1.w + q1.w; }
;     ...
;         const v4u rr = *(const v4u*)(RK + (size_t)t * 2048 + c0), kk = *(const v4u*)(RK + (size_t)t * 2048 + 512 + c0), vv = *(const v4u*)(RK + (size_t)t * 2048 + 1024 + c0);
;         const v4u a0 = *(const v4u*)(EA + (size_t)t * 2048 + 1024 + c0), a1 = *(const v4u*)(EA + (size_t)t * 2048 + 1536 + c0);
;         const v4u gg = *(const v4u*)(GT + (size_t)t * 512 + c0);
;         float r[8], k[8], v[8], aa0[8], aa1[8], g[8];
; #pragma unroll
;         for (int q = 0; q < 4; ++q) { r[2 * q] = h_lo(rr[q]); r[2 * q + 1] = h_hi(rr[q]); k[2 * q] = h_lo(kk[q]); k[2 * q + 1] = h_hi(kk[q]); v[2 * q] = h_lo(vv[q]); v[2 * q + 1] = h_hi(vv[q]);
;             aa0[2 * q] = h_lo(a0[q]); aa0[2 * q + 1] = h_hi(a0[q]); aa1[2 * q] = h_lo(a1[q]); aa1[2 * q + 1] = h_hi(a1[q]); g[2 * q] = bf_lo(gg[q]); g[2 * q + 1] = bf_hi(gg[q]); }
;         float s = 0.f, bon = 0.f;
; #pragma unroll
;         for (int e = 0; e < 8; ++e) { s += y[e]; const float kaa = k_a[c0 + e]; bon += r[e] * k[e] * r_k[c0 + e] * ((1.0f + (aa0[e] - 1.0f) * kaa) + (1.0f + (aa1[e] - 1.0f) * kaa)); }
.LBB0_832:
	v_lshl_add_u64 v[20:21], s[16:17], 0, v[184:185]
	v_add_co_u32_e32 v0, vcc, 0x19e00000, v20
	v_lshl_add_u64 v[30:31], s[12:13], 0, v[184:185]
	s_nop 0
	v_addc_co_u32_e32 v1, vcc, 0, v21, vcc
	v_add_co_u32_e32 v4, vcc, 0x1c600000, v20
	global_load_dwordx4 v[0:3], v[0:1], off
	s_nop 0
	v_addc_co_u32_e32 v5, vcc, 0, v21, vcc
	v_add_co_u32_e32 v8, vcc, s68, v30
	global_load_dwordx4 v[4:7], v[4:5], off
	s_nop 0
	v_addc_co_u32_e32 v9, vcc, 0, v31, vcc
	global_load_dwordx4 v[22:25], v[8:9], off
	global_load_dwordx4 v[26:29], v[8:9], off offset:1024
	s_nop 0
	global_load_dwordx4 v[8:11], v[8:9], off offset:2048
	s_mov_b32 s4, 0x37600000
	v_add_co_u32_e32 v34, vcc, s4, v30
	s_mov_b32 s4, 0x41600000
	s_nop 0
	v_addc_co_u32_e32 v35, vcc, 0, v31, vcc
	global_load_dwordx4 v[30:33], v[34:35], off offset:2048
	s_nop 0
	global_load_dwordx4 v[34:37], v[34:35], off offset:3072
	v_add_co_u32_e32 v38, vcc, s4, v20
	s_add_i32 s8, s8, s10
	s_nop 0
	v_addc_co_u32_e32 v39, vcc, 0, v21, vcc
	global_load_dwordx4 v[38:41], v[38:39], off
	s_nop 0
	s_nop 0
	s_nop 0
	s_add_u32 s12, s12, s14
	s_addc_u32 s13, s13, s15
	s_add_u32 s16, s16, s18
	s_addc_u32 s17, s17, s19
	s_cmp_lt_i32 s8, 0xa000
	s_waitcnt vmcnt(5)
	s_nop 1
	v_mov_b32_e32 v42, v96
	v_mov_b32_e32 v43, v97
	v_mov_b32_e32 v44, v98
	v_mov_b32_e32 v45, v99
	s_nop 1
	v_mov_b32_e32 v46, v100
	v_mov_b32_e32 v47, v101
	v_mov_b32_e32 v48, v102
	v_mov_b32_e32 v49, v103
	v_cvt_f32_f16_e32 v50, v22
	v_cvt_f32_f16_sdwa v51, v22 dst_sel:DWORD dst_unused:UNUSED_PAD src0_sel:WORD_1
	s_waitcnt vmcnt(4)
	v_cvt_f32_f16_e32 v52, v26
	v_cvt_f32_f16_sdwa v53, v26 dst_sel:DWORD dst_unused:UNUSED_PAD src0_sel:WORD_1
	v_cvt_f32_f16_e32 v26, v27
	v_cvt_f32_f16_sdwa v27, v27 dst_sel:DWORD dst_unused:UNUSED_PAD src0_sel:WORD_1
	v_pk_mul_f32 v[62:63], v[50:51], v[52:53]
	s_nop 0
	s_nop 0
	s_waitcnt vmcnt(2)
	s_nop 1
	v_mov_b32_e32 v50, v104
	v_mov_b32_e32 v51, v105
	v_mov_b32_e32 v52, v106
	v_mov_b32_e32 v53, v107
	s_nop 1
	v_mov_b32_e32 v54, v108
	v_mov_b32_e32 v55, v109
	v_mov_b32_e32 v56, v110
	v_mov_b32_e32 v57, v111
	v_cvt_f32_f16_e32 v58, v30
	v_cvt_f32_f16_sdwa v59, v30 dst_sel:DWORD dst_unused:UNUSED_PAD src0_sel:WORD_1
	s_waitcnt vmcnt(1)
	v_cvt_f32_f16_e32 v60, v34
	v_cvt_f32_f16_sdwa v61, v34 dst_sel:DWORD dst_unused:UNUSED_PAD src0_sel:WORD_1
	v_cvt_f32_f16_e32 v30, v31
	v_pk_add_f32 v[58:59], v[58:59], -1.0 op_sel_hi:[1,0]
	v_cvt_f32_f16_sdwa v31, v31 dst_sel:DWORD dst_unused:UNUSED_PAD src0_sel:WORD_1
	v_pk_add_f32 v[60:61], v[60:61], -1.0 op_sel_hi:[1,0]
	s_waitcnt vmcnt(0)
	v_pk_fma_f32 v[58:59], v[46:47], v[58:59], 1.0 op_sel_hi:[1,1,0]
	v_pk_fma_f32 v[46:47], v[46:47], v[60:61], 1.0 op_sel_hi:[1,1,0]
	v_cvt_f32_f16_e32 v34, v35
	v_pk_add_f32 v[46:47], v[58:59], v[46:47]
	v_cvt_f32_f16_sdwa v35, v35 dst_sel:DWORD dst_unused:UNUSED_PAD src0_sel:WORD_1
	s_waitcnt vmcnt(0)
	v_pk_mul_f32 v[54:55], v[62:63], v[54:55]
	s_nop 0
	v_pk_mul_f32 v[46:47], v[54:55], v[46:47]
	v_lshlrev_b32_e32 v54, 16, v0
	v_add_f32_e32 v22, 0, v46
	v_add_f32_e32 v46, v22, v47
	v_cvt_f32_f16_e32 v22, v23
	v_cvt_f32_f16_sdwa v23, v23 dst_sel:DWORD dst_unused:UNUSED_PAD src0_sel:WORD_1
	v_cvt_f32_f16_sdwa v47, v11 dst_sel:DWORD dst_unused:UNUSED_PAD src0_sel:WORD_1
	v_and_b32_e32 v55, 0xffff0000, v0
	v_lshlrev_b32_e32 v0, 16, v4
	v_pk_mul_f32 v[22:23], v[22:23], v[26:27]
	v_pk_add_f32 v[26:27], v[30:31], -1.0 op_sel_hi:[1,0]
	v_pk_add_f32 v[30:31], v[34:35], -1.0 op_sel_hi:[1,0]
	v_pk_fma_f32 v[26:27], v[26:27], v[48:49], 1.0 op_sel_hi:[1,1,0]
	v_pk_fma_f32 v[30:31], v[30:31], v[48:49], 1.0 op_sel_hi:[1,1,0]
	v_pk_mul_f32 v[22:23], v[22:23], v[56:57]
	v_pk_add_f32 v[26:27], v[26:27], v[30:31]
	v_cvt_f32_f16_e32 v30, v32
	v_pk_mul_f32 v[22:23], v[22:23], v[26:27]
	v_cvt_f32_f16_e32 v26, v28
	v_add_f32_e32 v22, v46, v22
	v_add_f32_e32 v46, v22, v23
	v_cvt_f32_f16_e32 v22, v24
	v_cvt_f32_f16_sdwa v23, v24 dst_sel:DWORD dst_unused:UNUSED_PAD src0_sel:WORD_1
	v_cvt_f32_f16_sdwa v27, v28 dst_sel:DWORD dst_unused:UNUSED_PAD src0_sel:WORD_1
	v_cvt_f32_f16_sdwa v31, v32 dst_sel:DWORD dst_unused:UNUSED_PAD src0_sel:WORD_1
	v_cvt_f32_f16_e32 v34, v36
	v_cvt_f32_f16_sdwa v35, v36 dst_sel:DWORD dst_unused:UNUSED_PAD src0_sel:WORD_1
	v_pk_mul_f32 v[22:23], v[22:23], v[26:27]
	v_pk_add_f32 v[26:27], v[30:31], -1.0 op_sel_hi:[1,0]
	v_pk_mul_f32 v[22:23], v[22:23], v[50:51]
	v_pk_add_f32 v[30:31], v[34:35], -1.0 op_sel_hi:[1,0]
	v_pk_fma_f32 v[26:27], v[26:27], v[42:43], 1.0 op_sel_hi:[1,1,0]
	v_pk_fma_f32 v[30:31], v[30:31], v[42:43], 1.0 op_sel_hi:[1,1,0]
	v_cvt_f32_f16_e32 v24, v29
	v_pk_add_f32 v[26:27], v[26:27], v[30:31]
	v_cvt_f32_f16_e32 v28, v37
	v_pk_mul_f32 v[22:23], v[22:23], v[26:27]
	v_cvt_f32_f16_e32 v26, v33
	v_add_f32_e32 v22, v46, v22
	v_add_f32_e32 v30, v22, v23
	v_cvt_f32_f16_e32 v22, v25
	v_cvt_f32_f16_sdwa v23, v25 dst_sel:DWORD dst_unused:UNUSED_PAD src0_sel:WORD_1
	v_cvt_f32_f16_sdwa v25, v29 dst_sel:DWORD dst_unused:UNUSED_PAD src0_sel:WORD_1
	v_cvt_f32_f16_sdwa v27, v33 dst_sel:DWORD dst_unused:UNUSED_PAD src0_sel:WORD_1
	v_cvt_f32_f16_sdwa v29, v37 dst_sel:DWORD dst_unused:UNUSED_PAD src0_sel:WORD_1
	v_cvt_f32_f16_e32 v46, v11
	v_pk_mul_f32 v[22:23], v[22:23], v[24:25]
	v_pk_add_f32 v[24:25], v[26:27], -1.0 op_sel_hi:[1,0]
	v_pk_add_f32 v[26:27], v[28:29], -1.0 op_sel_hi:[1,0]
	v_pk_fma_f32 v[24:25], v[24:25], v[44:45], 1.0 op_sel_hi:[1,1,0]
	v_pk_fma_f32 v[26:27], v[26:27], v[44:45], 1.0 op_sel_hi:[1,1,0]
	v_pk_mul_f32 v[22:23], v[22:23], v[52:53]
	v_pk_add_f32 v[24:25], v[24:25], v[26:27]
	v_lshlrev_b32_e32 v48, 16, v41
	v_pk_mul_f32 v[22:23], v[22:23], v[24:25]
	v_lshlrev_b32_e32 v24, 16, v7
	v_add_f32_e32 v22, v30, v22
	v_add_f32_e32 v22, v22, v23
	v_mbcnt_lo_u32_b32 v23, -1, 0
	v_mbcnt_hi_u32_b32 v23, -1, v23
	v_and_b32_e32 v25, 0xffff0000, v7
	v_lshlrev_b32_e32 v23, 2, v23
	v_xor_b32_e32 v43, 4, v23
	v_mbcnt_lo_u32_b32 v23, -1, 0
	v_mbcnt_hi_u32_b32 v23, -1, v23
	v_and_b32_e32 v49, 0xffff0000, v41
	v_lshlrev_b32_e32 v23, 2, v23
	v_xor_b32_e32 v56, 8, v23
	v_mbcnt_lo_u32_b32 v23, -1, 0
	v_mbcnt_hi_u32_b32 v23, -1, v23
	v_cvt_f32_f16_sdwa v7, v10 dst_sel:DWORD dst_unused:UNUSED_PAD src0_sel:WORD_1
	v_lshlrev_b32_e32 v23, 2, v23
	v_xor_b32_e32 v57, 16, v23
	v_mbcnt_lo_u32_b32 v23, -1, 0
	v_mbcnt_hi_u32_b32 v23, -1, v23
	v_and_b32_e32 v11, 0xffff0000, v40
	v_lshlrev_b32_e32 v23, 2, v23
	v_xor_b32_e32 v23, 4, v23
	ds_bpermute_b32 v23, v23, v22
	v_and_b32_e32 v41, 0xffff0000, v1
	v_lshlrev_b32_e32 v50, 16, v5
	v_and_b32_e32 v51, 0xffff0000, v5
	v_cvt_f32_f16_sdwa v5, v8 dst_sel:DWORD dst_unused:UNUSED_PAD src0_sel:WORD_1
	s_waitcnt lgkmcnt(0)
; __device__ __forceinline__ unsigned pk2(float lo, float hi) { return cvt_pk_bf16(lo, hi); }
; __device__ __forceinline__ float shfl_xor_(float v, int m) { return __builtin_bit_cast(float, __builtin_amdgcn_ds_bpermute((lane_id() ^ m) << 2, __builtin_bit_cast(int, v))); }
; __device__ __forceinline__ void phase_rwkv_post(const Frame& F, const Args& a, int l) {
;     ...
;         s += shfl_xor_(s, 1); s += shfl_xor_(s, 2); s += shfl_xor_(s, 4);
;         bon += shfl_xor_(bon, 1); bon += shfl_xor_(bon, 2); bon += shfl_xor_(bon, 4);
;         const float mu = s * (1.0f / 64.0f); float q2 = 0.f;
; #pragma unroll
;         for (int e = 0; e < 8; ++e) { const float d_ = y[e] - mu; q2 += d_ * d_; }
;         q2 += shfl_xor_(q2, 1); q2 += shfl_xor_(q2, 2); q2 += shfl_xor_(q2, 4);
;         const float rstd = 1.0f / sqrtf(q2 * (1.0f / 64.0f) + 64e-5f);
;         float o[8];
; #pragma unroll
;         for (int e = 0; e < 8; ++e) o[e] = (((y[e] - mu) * rstd) * ln_w[c0 + e] + ln_b[c0 + e] + bon * v[e]) * g[e];
;         v4u w; w.x = pk2(o[0], o[1]); w.y = pk2(o[2], o[3]); w.z = pk2(o[4], o[5]); w.w = pk2(o[6], o[7]);
;         *(v4u*)(YC + (size_t)t * 512 + c0) = w;
	v_add_f32_e32 v22, v22, v23
	v_mbcnt_lo_u32_b32 v23, -1, 0
	v_mbcnt_hi_u32_b32 v23, -1, v23
	v_lshlrev_b32_e32 v52, 16, v39
	v_lshlrev_b32_e32 v23, 2, v23
	v_xor_b32_e32 v23, 8, v23
	ds_bpermute_b32 v23, v23, v22
	v_and_b32_e32 v53, 0xffff0000, v39
	s_waitcnt lgkmcnt(0)
	v_add_f32_e32 v22, v22, v23
	v_mbcnt_lo_u32_b32 v23, -1, 0
	v_mbcnt_hi_u32_b32 v23, -1, v23
	s_nop 0
	v_lshlrev_b32_e32 v23, 2, v23
	v_xor_b32_e32 v23, 16, v23
	ds_bpermute_b32 v23, v23, v22
	s_waitcnt lgkmcnt(0)
	v_add_f32_e32 v42, v22, v23
	v_mbcnt_lo_u32_b32 v22, -1, 0
	v_mbcnt_hi_u32_b32 v22, -1, v22
	v_and_b32_e32 v23, 0xffff0000, v3
	v_lshlrev_b32_e32 v22, 2, v22
	v_xor_b32_e32 v60, 4, v22
	v_mbcnt_lo_u32_b32 v22, -1, 0
	v_mbcnt_hi_u32_b32 v22, -1, v22
	s_nop 0
	v_lshlrev_b32_e32 v22, 2, v22
	v_xor_b32_e32 v61, 8, v22
	v_mbcnt_lo_u32_b32 v22, -1, 0
	v_mbcnt_hi_u32_b32 v22, -1, v22
	s_nop 0
	v_lshlrev_b32_e32 v22, 2, v22
	v_xor_b32_e32 v62, 16, v22
	v_lshlrev_b32_e32 v22, 16, v3
	v_pk_add_f32 v[44:45], v[22:23], v[24:25]
	v_lshlrev_b32_e32 v22, 16, v2
	v_and_b32_e32 v23, 0xffff0000, v2
	v_lshlrev_b32_e32 v2, 16, v6
	v_and_b32_e32 v3, 0xffff0000, v6
	v_cvt_f32_f16_e32 v6, v10
	v_lshlrev_b32_e32 v10, 16, v40
	v_lshlrev_b32_e32 v40, 16, v1
	v_and_b32_e32 v1, 0xffff0000, v4
	v_pk_add_f32 v[0:1], v[54:55], v[0:1]
	v_pk_add_f32 v[40:41], v[40:41], v[50:51]
	v_cvt_f32_f16_e32 v50, v9
	v_cvt_f32_f16_sdwa v51, v9 dst_sel:DWORD dst_unused:UNUSED_PAD src0_sel:WORD_1
	v_cvt_f32_f16_e32 v4, v8
	v_lshlrev_b32_e32 v8, 16, v38
	v_and_b32_e32 v9, 0xffff0000, v38
	v_add_f32_e32 v38, 0, v0
	v_add_f32_e32 v38, v1, v38
	v_add_f32_e32 v38, v40, v38
	v_pk_add_f32 v[2:3], v[22:23], v[2:3]
	v_add_f32_e32 v38, v41, v38
	s_nop 0
	s_nop 1
	v_mov_b32_e32 v22, v112
	v_mov_b32_e32 v23, v113
	v_mov_b32_e32 v24, v114
	v_mov_b32_e32 v25, v115
	s_nop 0
	s_nop 1
	v_mov_b32_e32 v26, v116
	v_mov_b32_e32 v27, v117
	v_mov_b32_e32 v28, v118
	v_mov_b32_e32 v29, v119
	s_nop 0
	s_nop 1
	v_mov_b32_e32 v30, v120
	v_mov_b32_e32 v31, v121
	v_mov_b32_e32 v32, v122
	v_mov_b32_e32 v33, v123
	s_nop 0
	s_nop 1
	v_mov_b32_e32 v34, v124
	v_mov_b32_e32 v35, v125
	v_mov_b32_e32 v36, v126
	v_mov_b32_e32 v37, v127
	v_add_f32_e32 v38, v2, v38
	v_add_f32_e32 v38, v3, v38
	v_add_f32_e32 v38, v44, v38
	v_add_f32_e32 v38, v45, v38
	ds_bpermute_b32 v39, v43, v38
	s_waitcnt lgkmcnt(0)
	v_add_f32_e32 v38, v38, v39
	ds_bpermute_b32 v39, v56, v38
	s_waitcnt lgkmcnt(0)
	v_add_f32_e32 v38, v38, v39
	ds_bpermute_b32 v39, v57, v38
	s_waitcnt lgkmcnt(0)
	v_add_f32_e32 v38, v38, v39
	v_mul_f32_e32 v38, 0x3c800000, v38
	v_pk_add_f32 v[0:1], v[0:1], v[38:39] op_sel_hi:[1,0] neg_lo:[0,1] neg_hi:[0,1]
	v_pk_add_f32 v[40:41], v[40:41], v[38:39] op_sel_hi:[1,0] neg_lo:[0,1] neg_hi:[0,1]
	v_pk_mul_f32 v[54:55], v[0:1], v[0:1]
	v_pk_mul_f32 v[56:57], v[40:41], v[40:41]
	v_add_f32_e32 v43, v54, v55
	v_pk_add_f32 v[2:3], v[2:3], v[38:39] op_sel_hi:[1,0] neg_lo:[0,1] neg_hi:[0,1]
	v_add_f32_e32 v43, v56, v43
	v_pk_mul_f32 v[58:59], v[2:3], v[2:3]
	v_add_f32_e32 v43, v57, v43
	v_pk_add_f32 v[38:39], v[44:45], v[38:39] op_sel_hi:[1,0] neg_lo:[0,1] neg_hi:[0,1]
	v_add_f32_e32 v43, v58, v43
	v_pk_mul_f32 v[44:45], v[38:39], v[38:39]
	v_add_f32_e32 v43, v59, v43
	v_add_f32_e32 v43, v44, v43
	v_add_f32_e32 v43, v45, v43
	ds_bpermute_b32 v44, v60, v43
	s_waitcnt lgkmcnt(0)
	v_add_f32_e32 v43, v43, v44
	ds_bpermute_b32 v44, v61, v43
	s_waitcnt lgkmcnt(0)
	v_add_f32_e32 v43, v43, v44
	ds_bpermute_b32 v44, v62, v43
	s_waitcnt lgkmcnt(0)
	v_add_f32_e32 v43, v43, v44
	v_fmamk_f32 v43, v43, 0x3c800000, v252
	v_cmp_gt_f32_e32 vcc, s86, v43
	v_mul_f32_e32 v44, 0x4f800000, v43
	s_nop 0
	v_cndmask_b32_e32 v43, v43, v44, vcc
	v_sqrt_f32_e32 v44, v43
	s_nop 0
	v_add_u32_e32 v45, -1, v44
	v_fma_f32 v54, -v45, v44, v43
	v_cmp_ge_f32_e64 s[4:5], 0, v54
	v_add_u32_e32 v54, 1, v44
	s_nop 0
	v_cndmask_b32_e64 v45, v44, v45, s[4:5]
	v_fma_f32 v44, -v54, v44, v43
	v_cmp_lt_f32_e64 s[4:5], 0, v44
	s_nop 1
	v_cndmask_b32_e64 v44, v45, v54, s[4:5]
	v_mul_f32_e32 v45, 0x37800000, v44
	v_cndmask_b32_e32 v44, v44, v45, vcc
	v_cmp_class_f32_e32 vcc, v43, v204
	s_nop 1
	v_cndmask_b32_e32 v43, v44, v43, vcc
	v_div_scale_f32 v44, s[4:5], v43, v43, 1.0
	v_rcp_f32_e32 v45, v44
	s_mov_b32 s4, 0x17600000
	v_fma_f32 v54, -v44, v45, 1.0
	v_fmac_f32_e32 v45, v54, v45
	v_div_scale_f32 v54, vcc, 1.0, v43, 1.0
	v_mul_f32_e32 v55, v54, v45
	v_fma_f32 v56, -v44, v55, v54
	v_fmac_f32_e32 v55, v56, v45
	v_fma_f32 v44, -v44, v55, v54
	v_div_fmas_f32 v44, v44, v45, v55
	v_div_fixup_f32 v44, v44, v43, 1.0
	v_pk_mul_f32 v[0:1], v[0:1], v[44:45] op_sel_hi:[1,0]
	v_pk_mul_f32 v[2:3], v[2:3], v[44:45] op_sel_hi:[1,0]
	s_nop 0
	v_pk_fma_f32 v[0:1], v[26:27], v[0:1], v[34:35]
	v_pk_fma_f32 v[2:3], v[2:3], v[22:23], v[30:31]
	v_pk_fma_f32 v[0:1], v[42:43], v[4:5], v[0:1] op_sel_hi:[0,1,1]
	v_pk_mul_f32 v[4:5], v[40:41], v[44:45] op_sel_hi:[1,0]
	v_pk_fma_f32 v[2:3], v[42:43], v[6:7], v[2:3] op_sel_hi:[0,1,1]
	v_pk_fma_f32 v[4:5], v[28:29], v[4:5], v[36:37]
	v_pk_mul_f32 v[6:7], v[38:39], v[44:45] op_sel_hi:[1,0]
	v_pk_fma_f32 v[4:5], v[42:43], v[50:51], v[4:5] op_sel_hi:[0,1,1]
	v_pk_fma_f32 v[6:7], v[6:7], v[24:25], v[32:33]
	v_pk_mul_f32 v[0:1], v[0:1], v[8:9]
	v_pk_mul_f32 v[4:5], v[4:5], v[52:53]
	v_pk_fma_f32 v[6:7], v[42:43], v[46:47], v[6:7] op_sel_hi:[0,1,1]
	v_pk_mul_f32 v[2:3], v[2:3], v[10:11]
	v_pk_mul_f32 v[6:7], v[6:7], v[48:49]
	v_cvt_pk_bf16_f32 v0, v0, v1
	v_cvt_pk_bf16_f32 v1, v4, v5
	v_add_co_u32_e32 v4, vcc, s4, v20
	v_cvt_pk_bf16_f32 v2, v2, v3
	v_cvt_pk_bf16_f32 v3, v6, v7
	v_addc_co_u32_e32 v5, vcc, 0, v21, vcc
	global_store_dwordx4 v[4:5], v[0:3], off
	s_cbranch_scc1 .LBB0_832

; __device__ __forceinline__ void phase_final_norm(const Frame& F, const bf16* x, const float* gain, float* out) {
;     for (int m = F.gw; m < T; m += F.NGW) {
;         const v4u* xr = (const v4u*)(x + (size_t)m * D) + F.lane;
;         v4u v[4]; float s = 0.f;
; #pragma unroll
;         for (int j = 0; j < 4; ++j) v[j] = xr[64 * j];
; #pragma unroll
;         for (int j = 0; j < 4; ++j)
; #pragma unroll
;             for (int q = 0; q < 4; ++q) { const float a = bf_lo(v[j][q]), b = bf_hi(v[j][q]); s += a * a + b * b; }
;         const float rstd = 1.0f / sqrtf(wave_sum(s) * (1.0f / D) + 1e-6f);
.LBB0_1506:
	global_load_dwordx4 v[20:23], v[14:15], off offset:3072
	global_load_dwordx4 v[24:27], v[14:15], off
	global_load_dwordx4 v[28:31], v[14:15], off offset:1024
	global_load_dwordx4 v[32:35], v[14:15], off offset:2048
	v_mbcnt_lo_u32_b32 v38, -1, 0
	v_mbcnt_hi_u32_b32 v38, -1, v38
	v_mbcnt_lo_u32_b32 v39, -1, 0
	v_mbcnt_hi_u32_b32 v39, -1, v39
	v_mbcnt_lo_u32_b32 v40, -1, 0
	v_mbcnt_hi_u32_b32 v40, -1, v40
	v_mbcnt_lo_u32_b32 v41, -1, 0
	v_mbcnt_hi_u32_b32 v41, -1, v41
	v_mbcnt_lo_u32_b32 v42, -1, 0
	v_mbcnt_hi_u32_b32 v42, -1, v42
	v_mbcnt_lo_u32_b32 v43, -1, 0
	v_mbcnt_hi_u32_b32 v43, -1, v43
	s_nop 0
	s_nop 0
	v_lshlrev_b32_e32 v40, 2, v40
	v_lshlrev_b32_e32 v41, 2, v41
	v_lshlrev_b32_e32 v42, 2, v42
	v_lshlrev_b32_e32 v43, 2, v43
	v_xor_b32_e32 v86, 16, v40
	v_xor_b32_e32 v87, 32, v41
	v_xor_b32_e32 v88, 64, v42
	v_xor_b32_e32 v89, 0x80, v43
	v_lshlrev_b32_e32 v38, 2, v38
	v_lshlrev_b32_e32 v39, 2, v39
	v_xor_b32_e32 v84, 4, v38
	v_xor_b32_e32 v85, 8, v39
	v_add_co_u32_e32 v36, vcc, s5, v16
	s_add_i32 s2, s2, s4
	s_nop 0
	v_addc_co_u32_e32 v37, vcc, -1, v17, vcc
	v_lshl_add_u64 v[14:15], v[14:15], 0, s[6:7]
	s_cmp_lt_i32 s2, 0xa000
	s_waitcnt vmcnt(3)
	v_lshlrev_b32_e32 v52, 16, v20
	s_waitcnt vmcnt(2)
	v_lshlrev_b32_e32 v40, 16, v26
	v_and_b32_e32 v41, 0xffff0000, v26
	v_lshlrev_b32_e32 v26, 16, v27
	v_and_b32_e32 v27, 0xffff0000, v27
	v_lshlrev_b32_e32 v42, 16, v24
	v_and_b32_e32 v43, 0xffff0000, v24
	v_lshlrev_b32_e32 v24, 16, v25
	v_and_b32_e32 v25, 0xffff0000, v25
	v_pk_mul_f32 v[58:59], v[26:27], v[26:27]
	v_pk_mul_f32 v[60:61], v[42:43], v[42:43]
	v_pk_mul_f32 v[62:63], v[24:25], v[24:25]
	v_pk_mul_f32 v[56:57], v[40:41], v[40:41]
	v_add_f32_e32 v58, v58, v59
	v_add_f32_e32 v59, v62, v63
	v_add_f32_e32 v60, v60, v61
	s_waitcnt vmcnt(1)
	v_lshlrev_b32_e32 v46, 16, v28
	v_and_b32_e32 v47, 0xffff0000, v28
	v_add_f32_e32 v56, v56, v57
	v_add_f32_e32 v59, v60, v59
	v_lshlrev_b32_e32 v28, 16, v29
	v_and_b32_e32 v29, 0xffff0000, v29
	v_pk_mul_f32 v[68:69], v[46:47], v[46:47]
	v_add_f32_e32 v56, v56, v59
	v_lshlrev_b32_e32 v44, 16, v30
	v_and_b32_e32 v45, 0xffff0000, v30
	v_pk_mul_f32 v[70:71], v[28:29], v[28:29]
	v_add_f32_e32 v57, v68, v69
	v_add_f32_e32 v56, v58, v56
	v_lshlrev_b32_e32 v30, 16, v31
	v_and_b32_e32 v31, 0xffff0000, v31
	v_pk_mul_f32 v[64:65], v[44:45], v[44:45]
	v_add_f32_e32 v61, v70, v71
	v_add_f32_e32 v56, v57, v56
	s_waitcnt vmcnt(0)
	v_lshlrev_b32_e32 v50, 16, v32
	v_and_b32_e32 v51, 0xffff0000, v32
	v_pk_mul_f32 v[66:67], v[30:31], v[30:31]
	v_add_f32_e32 v62, v64, v65
	v_add_f32_e32 v56, v61, v56
	v_lshlrev_b32_e32 v32, 16, v33
	v_and_b32_e32 v33, 0xffff0000, v33
	v_pk_mul_f32 v[76:77], v[50:51], v[50:51]
	v_add_f32_e32 v63, v66, v67
	v_add_f32_e32 v56, v62, v56
	v_lshlrev_b32_e32 v48, 16, v34
	v_and_b32_e32 v49, 0xffff0000, v34
	v_pk_mul_f32 v[78:79], v[32:33], v[32:33]
	v_add_f32_e32 v64, v76, v77
	v_add_f32_e32 v56, v63, v56
	v_lshlrev_b32_e32 v34, 16, v35
	v_and_b32_e32 v35, 0xffff0000, v35
	v_pk_mul_f32 v[72:73], v[48:49], v[48:49]
	v_add_f32_e32 v65, v78, v79
	v_add_f32_e32 v56, v64, v56
	v_and_b32_e32 v53, 0xffff0000, v20
	v_pk_mul_f32 v[74:75], v[34:35], v[34:35]
	v_add_f32_e32 v66, v72, v73
	v_add_f32_e32 v56, v65, v56
	v_lshlrev_b32_e32 v20, 16, v21
	v_and_b32_e32 v21, 0xffff0000, v21
	v_pk_mul_f32 v[80:81], v[52:53], v[52:53]
	v_add_f32_e32 v67, v74, v75
	v_add_f32_e32 v56, v66, v56
	v_lshlrev_b32_e32 v39, 16, v23
	v_lshlrev_b32_e32 v38, 16, v22
	v_and_b32_e32 v23, 0xffff0000, v23
	v_and_b32_e32 v22, 0xffff0000, v22
	v_pk_mul_f32 v[82:83], v[20:21], v[20:21]
	v_add_f32_e32 v68, v80, v81
	v_add_f32_e32 v56, v67, v56
	v_pk_mul_f32 v[54:55], v[22:23], v[22:23]
	v_add_f32_e32 v69, v82, v83
	v_add_f32_e32 v56, v68, v56
	v_pk_fma_f32 v[54:55], v[38:39], v[38:39], v[54:55]
	v_add_f32_e32 v56, v69, v56
	v_add_f32_e32 v54, v54, v56
	v_add_f32_e32 v54, v55, v54
	ds_bpermute_b32 v55, v84, v54
	s_waitcnt lgkmcnt(0)
	v_add_f32_e32 v54, v54, v55
	ds_bpermute_b32 v55, v85, v54
	s_waitcnt lgkmcnt(0)
	v_add_f32_e32 v54, v54, v55
	ds_bpermute_b32 v55, v86, v54
	s_waitcnt lgkmcnt(0)
	v_add_f32_e32 v54, v54, v55
	ds_bpermute_b32 v55, v87, v54
	s_waitcnt lgkmcnt(0)
	v_add_f32_e32 v54, v54, v55
	ds_bpermute_b32 v55, v88, v54
	s_waitcnt lgkmcnt(0)
; __device__ __forceinline__ void phase_final_norm(const Frame& F, const bf16* x, const float* gain, float* out) {
;     ...
;         const float rstd = 1.0f / sqrtf(wave_sum(s) * (1.0f / D) + 1e-6f);
;         const f32x4* gr = (const f32x4*)gain + 2 * F.lane; f32x4* o = (f32x4*)(out + (size_t)m * D) + 2 * F.lane;
; #pragma unroll
;         for (int j = 0; j < 4; ++j) { const f32x4 g0 = gr[128 * j], g1 = gr[128 * j + 1]; const v4u w = v[j];
;             f32x4 o0, o1; o0.x = bf_lo(w.x) * rstd * g0.x; o0.y = bf_hi(w.x) * rstd * g0.y; o0.z = bf_lo(w.y) * rstd * g0.z; o0.w = bf_hi(w.y) * rstd * g0.w;
;             o1.x = bf_lo(w.z) * rstd * g1.x; o1.y = bf_hi(w.z) * rstd * g1.y; o1.z = bf_lo(w.w) * rstd * g1.z; o1.w = bf_hi(w.w) * rstd * g1.w;
;             o[128 * j] = o0; o[128 * j + 1] = o1; }
	v_add_f32_e32 v54, v54, v55
	ds_bpermute_b32 v55, v89, v54
	s_waitcnt lgkmcnt(0)
	v_add_f32_e32 v54, v54, v55
	v_fmamk_f32 v54, v54, 0x3a000000, v18
	v_mul_f32_e32 v55, 0x4f800000, v54
	v_cmp_gt_f32_e32 vcc, s3, v54
	s_nop 1
	v_cndmask_b32_e32 v54, v54, v55, vcc
	v_sqrt_f32_e32 v55, v54
	s_nop 0
	v_add_u32_e32 v56, -1, v55
	v_add_u32_e32 v57, 1, v55
	v_fma_f32 v58, -v56, v55, v54
	v_fma_f32 v59, -v57, v55, v54
	v_cmp_ge_f32_e64 s[0:1], 0, v58
	s_nop 1
	v_cndmask_b32_e64 v55, v55, v56, s[0:1]
	v_cmp_lt_f32_e64 s[0:1], 0, v59
	s_nop 1
	v_cndmask_b32_e64 v55, v55, v57, s[0:1]
	v_mul_f32_e32 v56, 0x37800000, v55
	v_cndmask_b32_e32 v55, v55, v56, vcc
	v_cmp_class_f32_e32 vcc, v54, v19
	s_nop 1
	v_cndmask_b32_e32 v54, v55, v54, vcc
	v_div_scale_f32 v55, s[0:1], v54, v54, 1.0
	v_rcp_f32_e32 v57, v55
	v_div_scale_f32 v56, vcc, 1.0, v54, 1.0
	v_fma_f32 v58, -v55, v57, 1.0
	v_fmac_f32_e32 v57, v58, v57
	v_mul_f32_e32 v58, v56, v57
	v_fma_f32 v59, -v55, v58, v56
	v_fmac_f32_e32 v58, v59, v57
	v_fma_f32 v55, -v55, v58, v56
	v_div_fmas_f32 v55, v55, v57, v58
	v_div_fixup_f32 v54, v55, v54, 1.0
	v_pk_mul_f32 v[42:43], v[54:55], v[42:43] op_sel_hi:[0,1]
	v_pk_mul_f32 v[24:25], v[54:55], v[24:25] op_sel_hi:[0,1]
	v_pk_mul_f32 v[40:41], v[54:55], v[40:41] op_sel_hi:[0,1]
	v_pk_mul_f32 v[26:27], v[54:55], v[26:27] op_sel_hi:[0,1]
	s_waitcnt vmcnt(0)
	s_nop 1
	v_mov_b32_e32 v0, v96
	v_mov_b32_e32 v1, v97
	v_mov_b32_e32 v2, v98
	v_mov_b32_e32 v3, v99
	s_nop 1
	v_mov_b32_e32 v4, v100
	v_mov_b32_e32 v5, v101
	v_mov_b32_e32 v6, v102
	v_mov_b32_e32 v7, v103
	v_pk_mul_f32 v[6:7], v[6:7], v[24:25]
	v_pk_mul_f32 v[4:5], v[4:5], v[42:43]
	v_pk_mul_f32 v[2:3], v[2:3], v[26:27]
	v_pk_mul_f32 v[0:1], v[0:1], v[40:41]
	global_store_dwordx4 v[36:37], v[4:7], off offset:-2064
	global_store_dwordx4 v[36:37], v[0:3], off offset:-2048
	s_nop 0
	s_nop 1
	v_mov_b32_e32 v0, v104
	v_mov_b32_e32 v1, v105
	v_mov_b32_e32 v2, v106
	v_mov_b32_e32 v3, v107
	s_nop 0
	s_nop 0
	s_nop 1
	v_mov_b32_e32 v4, v108
	v_mov_b32_e32 v5, v109
	v_mov_b32_e32 v6, v110
	v_mov_b32_e32 v7, v111
	v_pk_mul_f32 v[24:25], v[54:55], v[28:29] op_sel_hi:[0,1]
	v_pk_mul_f32 v[26:27], v[54:55], v[46:47] op_sel_hi:[0,1]
	v_pk_mul_f32 v[28:29], v[54:55], v[30:31] op_sel_hi:[0,1]
	v_pk_mul_f32 v[30:31], v[54:55], v[44:45] op_sel_hi:[0,1]
	v_pk_mul_f32 v[20:21], v[54:55], v[20:21] op_sel_hi:[0,1]
	s_nop 0
	v_pk_mul_f32 v[0:1], v[0:1], v[26:27]
	v_pk_mul_f32 v[2:3], v[2:3], v[24:25]
	s_nop 0
	v_pk_mul_f32 v[4:5], v[4:5], v[30:31]
	v_pk_mul_f32 v[6:7], v[6:7], v[28:29]
	global_store_dwordx4 v[36:37], v[0:3], off offset:-16
	global_store_dwordx4 v[16:17], v[4:7], off offset:-4096
	s_nop 0
	s_nop 1
	v_mov_b32_e32 v0, v112
	v_mov_b32_e32 v1, v113
	v_mov_b32_e32 v2, v114
	v_mov_b32_e32 v3, v115
	s_nop 0
	s_nop 0
	s_nop 1
	v_mov_b32_e32 v4, v116
	v_mov_b32_e32 v5, v117
	v_mov_b32_e32 v6, v118
	v_mov_b32_e32 v7, v119
	v_pk_mul_f32 v[24:25], v[54:55], v[32:33] op_sel_hi:[0,1]
	v_pk_mul_f32 v[26:27], v[54:55], v[50:51] op_sel_hi:[0,1]
	v_pk_mul_f32 v[28:29], v[54:55], v[34:35] op_sel_hi:[0,1]
	v_pk_mul_f32 v[30:31], v[54:55], v[48:49] op_sel_hi:[0,1]
	s_nop 0
	v_pk_mul_f32 v[0:1], v[0:1], v[26:27]
	v_pk_mul_f32 v[2:3], v[2:3], v[24:25]
	s_nop 0
	v_pk_mul_f32 v[4:5], v[4:5], v[30:31]
	v_pk_mul_f32 v[6:7], v[6:7], v[28:29]
	global_store_dwordx4 v[16:17], v[0:3], off offset:-2064
	global_store_dwordx4 v[16:17], v[4:7], off offset:-2048
	s_nop 0
	s_nop 1
	v_mov_b32_e32 v0, v120
	v_mov_b32_e32 v1, v121
	v_mov_b32_e32 v2, v122
	v_mov_b32_e32 v3, v123
	s_nop 0
	s_nop 0
	s_nop 1
	v_mov_b32_e32 v4, v124
	v_mov_b32_e32 v5, v125
	v_mov_b32_e32 v6, v126
	v_mov_b32_e32 v7, v127
	v_mov_b32_e32 v24, v38
	v_mov_b32_e32 v25, v22
	v_mov_b32_e32 v22, v39
	v_pk_mul_f32 v[26:27], v[54:55], v[52:53] op_sel_hi:[0,1]
	v_pk_mul_f32 v[24:25], v[54:55], v[24:25] op_sel_hi:[0,1]
	v_pk_mul_f32 v[22:23], v[54:55], v[22:23] op_sel_hi:[0,1]
	s_nop 0
	v_pk_mul_f32 v[0:1], v[0:1], v[26:27]
	v_pk_mul_f32 v[2:3], v[2:3], v[20:21]
	s_nop 0
	v_pk_mul_f32 v[4:5], v[4:5], v[24:25]
	v_pk_mul_f32 v[6:7], v[6:7], v[22:23]
	global_store_dwordx4 v[16:17], v[0:3], off offset:-16
	global_store_dwordx4 v[16:17], v[4:7], off
	v_lshl_add_u64 v[16:17], v[16:17], 0, s[8:9]
	s_cbranch_scc1 .LBB0_1506
